# GEMM K-loops: one static s_setprio 1 for waves 4-7 at loop entry, per-phase priority flips removed
# speedup vs baseline: 1.0143x; 1.0121x over previous
.LBB0_669:
	s_xor_b64 s[12:13], s[42:43], -1
	s_and_b64 s[42:43], s[42:43], exec
	s_cselect_b32 s11, s9, s39
	s_cselect_b32 s17, s8, s38
	s_cselect_b32 s23, s7, s41
	s_cselect_b32 s44, s6, s40
	s_add_u32 s38, s38, 0x40080
	s_addc_u32 s39, s39, 0
	s_add_u32 s45, s40, 0x100
	v_mov_b32_e32 v0, 0
	s_addc_u32 s52, s41, 0
	s_mov_b32 s53, -2
	v_readlane_b32 vcc_lo, v252, 38
	v_readlane_b32 vcc_hi, v252, 39
	v_lshl_add_u32 v154, s34, 8, v141
	v_ashrrev_i32_e32 v155, 31, v154
	s_nop 0
	v_lshl_add_u64 v[158:159], v[154:155], 2, vcc
	global_load_dword v144, v[158:159], off
	global_load_dword v148, v[158:159], off offset:64
	global_load_dword v152, v[158:159], off offset:128
	global_load_dword v183, v[158:159], off offset:192
	global_load_dword v230, v[158:159], off offset:512
	global_load_dword v231, v[158:159], off offset:576
	global_load_dword v233, v[158:159], off offset:640
	global_load_dword v250, v[158:159], off offset:704
	v_mov_b32_e32 v1, v0
	v_mov_b32_e32 v2, v0
	v_mov_b32_e32 v3, v0
	v_mov_b32_e32 v4, v0
	v_mov_b32_e32 v5, v0
	v_mov_b32_e32 v6, v0
	v_mov_b32_e32 v7, v0
	v_mov_b32_e32 v8, v0
	v_mov_b32_e32 v9, v0
	v_mov_b32_e32 v10, v0
	v_mov_b32_e32 v11, v0
	v_mov_b32_e32 v18, v0
	v_mov_b32_e32 v19, v0
	v_mov_b32_e32 v20, v0
	v_mov_b32_e32 v21, v0
	v_mov_b32_e32 v26, v0
	v_mov_b32_e32 v27, v0
	v_mov_b32_e32 v28, v0
	v_mov_b32_e32 v29, v0
	v_mov_b32_e32 v34, v0
	v_mov_b32_e32 v35, v0
	v_mov_b32_e32 v36, v0
	v_mov_b32_e32 v37, v0
	v_mov_b32_e32 v42, v0
	v_mov_b32_e32 v43, v0
	v_mov_b32_e32 v44, v0
	v_mov_b32_e32 v45, v0
	v_mov_b32_e32 v50, v0
	v_mov_b32_e32 v51, v0
	v_mov_b32_e32 v52, v0
	v_mov_b32_e32 v53, v0
	v_mov_b32_e32 v12, v0
	v_mov_b32_e32 v13, v0
	v_mov_b32_e32 v14, v0
	v_mov_b32_e32 v15, v0
	v_mov_b32_e32 v22, v0
	v_mov_b32_e32 v23, v0
	v_mov_b32_e32 v24, v0
	v_mov_b32_e32 v25, v0
	v_mov_b32_e32 v30, v0
	v_mov_b32_e32 v31, v0
	v_mov_b32_e32 v32, v0
	v_mov_b32_e32 v33, v0
	v_mov_b32_e32 v38, v0
	v_mov_b32_e32 v39, v0
	v_mov_b32_e32 v40, v0
	v_mov_b32_e32 v41, v0
	v_mov_b32_e32 v46, v0
	v_mov_b32_e32 v47, v0
	v_mov_b32_e32 v48, v0
	v_mov_b32_e32 v49, v0
	v_mov_b32_e32 v54, v0
	v_mov_b32_e32 v55, v0
	v_mov_b32_e32 v56, v0
	v_mov_b32_e32 v57, v0
	v_mov_b32_e32 v58, v0
	v_mov_b32_e32 v59, v0
	v_mov_b32_e32 v60, v0
	v_mov_b32_e32 v61, v0
	v_mov_b32_e32 v62, v0
	v_mov_b32_e32 v63, v0
	v_mov_b32_e32 v64, v0
	v_mov_b32_e32 v65, v0
	v_mov_b32_e32 v66, v0
	v_mov_b32_e32 v67, v0
	v_mov_b32_e32 v68, v0
	v_mov_b32_e32 v69, v0
	v_mov_b32_e32 v70, v0
	v_mov_b32_e32 v71, v0
	v_mov_b32_e32 v72, v0
	v_mov_b32_e32 v73, v0
	v_mov_b32_e32 v74, v0
	v_mov_b32_e32 v75, v0
	v_mov_b32_e32 v76, v0
	v_mov_b32_e32 v77, v0
	v_mov_b32_e32 v82, v0
	v_mov_b32_e32 v83, v0
	v_mov_b32_e32 v84, v0
	v_mov_b32_e32 v85, v0
	v_mov_b32_e32 v90, v0
	v_mov_b32_e32 v91, v0
	v_mov_b32_e32 v92, v0
	v_mov_b32_e32 v93, v0
	v_mov_b32_e32 v98, v0
	v_mov_b32_e32 v99, v0
	v_mov_b32_e32 v100, v0
	v_mov_b32_e32 v101, v0
	v_mov_b32_e32 v106, v0
	v_mov_b32_e32 v107, v0
	v_mov_b32_e32 v108, v0
	v_mov_b32_e32 v109, v0
	v_mov_b32_e32 v114, v0
	v_mov_b32_e32 v115, v0
	v_mov_b32_e32 v116, v0
	v_mov_b32_e32 v117, v0
	v_mov_b32_e32 v78, v0
	v_mov_b32_e32 v79, v0
	v_mov_b32_e32 v80, v0
	v_mov_b32_e32 v81, v0
	v_mov_b32_e32 v86, v0
	v_mov_b32_e32 v87, v0
	v_mov_b32_e32 v88, v0
	v_mov_b32_e32 v89, v0
	v_mov_b32_e32 v94, v0
	v_mov_b32_e32 v95, v0
	v_mov_b32_e32 v96, v0
	v_mov_b32_e32 v97, v0
	v_mov_b32_e32 v102, v0
	v_mov_b32_e32 v103, v0
	v_mov_b32_e32 v104, v0
	v_mov_b32_e32 v105, v0
	v_mov_b32_e32 v110, v0
	v_mov_b32_e32 v111, v0
	v_mov_b32_e32 v112, v0
	v_mov_b32_e32 v113, v0
	v_mov_b32_e32 v118, v0
	v_mov_b32_e32 v119, v0
	v_mov_b32_e32 v120, v0
	v_mov_b32_e32 v121, v0
	v_mov_b32_e32 v122, v0
	v_mov_b32_e32 v123, v0
	v_mov_b32_e32 v124, v0
	v_mov_b32_e32 v125, v0
	v_mov_b32_e32 v126, v0
	v_mov_b32_e32 v127, v0
	v_mov_b32_e32 v128, v0
	v_mov_b32_e32 v129, v0
	v_readfirstlane_b32 s98, v232
	s_cmp_ge_u32 s98, 0x100
	s_cbranch_scc0 .Lsp_sk0
	s_setprio 1
.Lsp_sk0:
.LBB0_670:
	s_add_u32 s40, s38, 0xfffc0080
	s_addc_u32 s41, s39, -1
	s_add_i32 s54, 0, 0x10000
	v_add_u32_e32 v140, s54, v145
	ds_read_b128 v[154:157], v140
	ds_read_b128 v[158:161], v140 offset:1024
	ds_read_b128 v[162:165], v140 offset:2048
	ds_read_b128 v[166:169], v140 offset:3072
	s_cmp_eq_u32 s53, 12
	s_cselect_b32 s43, s11, s41
	s_cselect_b32 s42, s17, s40
	s_cselect_b32 s41, s23, s52
	s_cselect_b32 s40, s44, s45
	v_lshl_add_u64 v[142:143], s[38:39], 0, v[136:137]
	s_add_i32 m0, s21, 0xc000
	ds_read_b128 v[170:173], v153
	ds_read_b128 v[174:177], v153 offset:1024
	ds_read_b128 v[188:191], v153 offset:2048
	ds_read_b128 v[192:195], v153 offset:3072
	ds_read_b128 v[196:199], v153 offset:4096
	ds_read_b128 v[200:203], v153 offset:5120
	ds_read_b128 v[204:207], v153 offset:6144
	ds_read_b128 v[208:211], v153 offset:7168
	global_load_lds_dwordx4 v[142:143], off
	v_lshl_add_u64 v[142:143], s[38:39], 0, v[138:139]
	s_add_i32 m0, s21, 0xe000
	s_nop 0
	global_load_lds_dwordx4 v[142:143], off
	s_waitcnt lgkmcnt(8)
	s_barrier
	s_waitcnt lgkmcnt(0)
	s_waitcnt lgkmcnt(0)
	v_mfma_f32_16x16x32_bf16 v[126:129], v[154:157], v[170:173], v[126:129]
	v_mfma_f32_16x16x32_bf16 v[122:125], v[162:165], v[170:173], v[122:125]
	v_mfma_f32_16x16x32_bf16 v[118:121], v[154:157], v[188:191], v[118:121]
	v_mfma_f32_16x16x32_bf16 v[110:113], v[162:165], v[188:191], v[110:113]
	v_mfma_f32_16x16x32_bf16 v[102:105], v[154:157], v[196:199], v[102:105]
	v_mfma_f32_16x16x32_bf16 v[94:97], v[162:165], v[196:199], v[94:97]
	v_mfma_f32_16x16x32_bf16 v[86:89], v[154:157], v[204:207], v[86:89]
	v_mfma_f32_16x16x32_bf16 v[78:81], v[162:165], v[204:207], v[78:81]
	v_mfma_f32_16x16x32_bf16 v[126:129], v[158:161], v[174:177], v[126:129]
	v_mfma_f32_16x16x32_bf16 v[122:125], v[166:169], v[174:177], v[122:125]
	v_mfma_f32_16x16x32_bf16 v[118:121], v[158:161], v[192:195], v[118:121]
	v_mfma_f32_16x16x32_bf16 v[110:113], v[166:169], v[192:195], v[110:113]
	v_mfma_f32_16x16x32_bf16 v[102:105], v[158:161], v[200:203], v[102:105]
	v_mfma_f32_16x16x32_bf16 v[94:97], v[166:169], v[200:203], v[94:97]
	v_mfma_f32_16x16x32_bf16 v[86:89], v[158:161], v[208:211], v[86:89]
	v_mfma_f32_16x16x32_bf16 v[78:81], v[166:169], v[208:211], v[78:81]
	s_barrier
	s_add_i32 s56, 0, 0x14000
	s_add_i32 s54, s54, s20
	v_add_u32_e32 v140, s56, v145
	v_lshl_add_u64 v[142:143], s[40:41], 0, v[16:17]
	s_mov_b32 m0, s54
	ds_read_b128 v[212:215], v140
	ds_read_b128 v[216:219], v140 offset:1024
	ds_read_b128 v[220:223], v140 offset:2048
	ds_read_b128 v[224:227], v140 offset:3072
	global_load_lds_dwordx4 v[142:143], off
	v_lshl_add_u64 v[146:147], s[40:41], 0, v[134:135]
	s_add_i32 m0, s54, 0x2000
	s_nop 0
	global_load_lds_dwordx4 v[146:147], off
	s_barrier
	s_waitcnt lgkmcnt(0)
	s_waitcnt lgkmcnt(0)
	v_mfma_f32_16x16x32_bf16 v[114:117], v[212:215], v[170:173], v[114:117]
	v_mfma_f32_16x16x32_bf16 v[106:109], v[220:223], v[170:173], v[106:109]
	v_mfma_f32_16x16x32_bf16 v[98:101], v[212:215], v[188:191], v[98:101]
	v_mfma_f32_16x16x32_bf16 v[90:93], v[220:223], v[188:191], v[90:93]
	v_mfma_f32_16x16x32_bf16 v[82:85], v[212:215], v[196:199], v[82:85]
	v_mfma_f32_16x16x32_bf16 v[74:77], v[220:223], v[196:199], v[74:77]
	v_mfma_f32_16x16x32_bf16 v[70:73], v[212:215], v[204:207], v[70:73]
	v_mfma_f32_16x16x32_bf16 v[66:69], v[220:223], v[204:207], v[66:69]
	v_mfma_f32_16x16x32_bf16 v[114:117], v[216:219], v[174:177], v[114:117]
	v_mfma_f32_16x16x32_bf16 v[106:109], v[224:227], v[174:177], v[106:109]
	v_mfma_f32_16x16x32_bf16 v[98:101], v[216:219], v[192:195], v[98:101]
	v_mfma_f32_16x16x32_bf16 v[90:93], v[224:227], v[192:195], v[90:93]
	v_mfma_f32_16x16x32_bf16 v[82:85], v[216:219], v[200:203], v[82:85]
	v_mfma_f32_16x16x32_bf16 v[74:77], v[224:227], v[200:203], v[74:77]
	v_mfma_f32_16x16x32_bf16 v[70:73], v[216:219], v[208:211], v[70:73]
	v_mfma_f32_16x16x32_bf16 v[66:69], v[224:227], v[208:211], v[66:69]
	s_mov_b32 m0, s21
	v_lshl_add_u64 v[150:151], s[42:43], 0, v[130:131]
	s_barrier
	ds_read_b128 v[170:173], v153 offset:16384
	ds_read_b128 v[174:177], v153 offset:17408
	ds_read_b128 v[188:191], v153 offset:18432
	ds_read_b128 v[192:195], v153 offset:19456
	ds_read_b128 v[196:199], v153 offset:20480
	ds_read_b128 v[200:203], v153 offset:21504
	ds_read_b128 v[204:207], v153 offset:22528
	ds_read_b128 v[208:211], v153 offset:23552
	global_load_lds_dwordx4 v[150:151], off
	v_lshl_add_u64 v[178:179], s[42:43], 0, v[132:133]
	s_mov_b32 m0, s25
	s_nop 0
	global_load_lds_dwordx4 v[178:179], off
	s_barrier
	s_waitcnt lgkmcnt(0)
	s_waitcnt lgkmcnt(0)
	v_mfma_f32_16x16x32_bf16 v[62:65], v[154:157], v[170:173], v[62:65]
	v_mfma_f32_16x16x32_bf16 v[58:61], v[162:165], v[170:173], v[58:61]
	v_mfma_f32_16x16x32_bf16 v[54:57], v[154:157], v[188:191], v[54:57]
	v_mfma_f32_16x16x32_bf16 v[46:49], v[162:165], v[188:191], v[46:49]
	v_mfma_f32_16x16x32_bf16 v[38:41], v[154:157], v[196:199], v[38:41]
	v_mfma_f32_16x16x32_bf16 v[30:33], v[162:165], v[196:199], v[30:33]
	v_mfma_f32_16x16x32_bf16 v[22:25], v[154:157], v[204:207], v[22:25]
	v_mfma_f32_16x16x32_bf16 v[12:15], v[162:165], v[204:207], v[12:15]
	v_mfma_f32_16x16x32_bf16 v[62:65], v[158:161], v[174:177], v[62:65]
	v_mfma_f32_16x16x32_bf16 v[58:61], v[166:169], v[174:177], v[58:61]
	v_mfma_f32_16x16x32_bf16 v[54:57], v[158:161], v[192:195], v[54:57]
	v_mfma_f32_16x16x32_bf16 v[46:49], v[166:169], v[192:195], v[46:49]
	v_mfma_f32_16x16x32_bf16 v[38:41], v[158:161], v[200:203], v[38:41]
	v_mfma_f32_16x16x32_bf16 v[30:33], v[166:169], v[200:203], v[30:33]
	v_mfma_f32_16x16x32_bf16 v[22:25], v[158:161], v[208:211], v[22:25]
	v_mfma_f32_16x16x32_bf16 v[12:15], v[166:169], v[208:211], v[12:15]
	s_barrier
	s_add_u32 s54, s40, 0x40000
	s_addc_u32 s55, s41, 0
	s_add_i32 s56, s56, s20
	v_lshl_add_u64 v[154:155], s[54:55], 0, v[16:17]
	s_mov_b32 m0, s56
	s_nop 0
	global_load_lds_dwordx4 v[154:155], off
	v_lshl_add_u64 v[154:155], s[54:55], 0, v[134:135]
	s_add_i32 m0, s56, 0x2000
	s_nop 0
	global_load_lds_dwordx4 v[154:155], off
	s_waitcnt vmcnt(6)
	s_barrier
	v_mfma_f32_16x16x32_bf16 v[50:53], v[212:215], v[170:173], v[50:53]
	v_mfma_f32_16x16x32_bf16 v[42:45], v[220:223], v[170:173], v[42:45]
	v_mfma_f32_16x16x32_bf16 v[34:37], v[212:215], v[188:191], v[34:37]
	v_mfma_f32_16x16x32_bf16 v[26:29], v[220:223], v[188:191], v[26:29]
	v_mfma_f32_16x16x32_bf16 v[18:21], v[212:215], v[196:199], v[18:21]
	v_mfma_f32_16x16x32_bf16 v[8:11], v[220:223], v[196:199], v[8:11]
	v_mfma_f32_16x16x32_bf16 v[4:7], v[212:215], v[204:207], v[4:7]
	v_mfma_f32_16x16x32_bf16 v[0:3], v[220:223], v[204:207], v[0:3]
	v_mfma_f32_16x16x32_bf16 v[50:53], v[216:219], v[174:177], v[50:53]
	v_mfma_f32_16x16x32_bf16 v[42:45], v[224:227], v[174:177], v[42:45]
	v_mfma_f32_16x16x32_bf16 v[34:37], v[216:219], v[192:195], v[34:37]
	v_mfma_f32_16x16x32_bf16 v[26:29], v[224:227], v[192:195], v[26:29]
	v_mfma_f32_16x16x32_bf16 v[18:21], v[216:219], v[200:203], v[18:21]
	v_mfma_f32_16x16x32_bf16 v[8:11], v[224:227], v[200:203], v[8:11]
	v_mfma_f32_16x16x32_bf16 v[4:7], v[216:219], v[208:211], v[4:7]
	v_mfma_f32_16x16x32_bf16 v[0:3], v[224:227], v[208:211], v[0:3]
	s_add_i32 s54, 0, 0x18000
	v_add_u32_e32 v140, s54, v145
	s_barrier
	ds_read_b128 v[154:157], v140
	ds_read_b128 v[158:161], v140 offset:1024
	ds_read_b128 v[162:165], v140 offset:2048
	ds_read_b128 v[166:169], v140 offset:3072
	s_add_u32 s42, s42, 0x40000
	s_addc_u32 s43, s43, 0
	s_mov_b32 m0, s33
	v_lshl_add_u64 v[180:181], s[42:43], 0, v[130:131]
	ds_read_b128 v[170:173], v153 offset:32768
	ds_read_b128 v[174:177], v153 offset:33792
	ds_read_b128 v[188:191], v153 offset:34816
	ds_read_b128 v[192:195], v153 offset:35840
	ds_read_b128 v[196:199], v153 offset:36864
	ds_read_b128 v[200:203], v153 offset:37888
	ds_read_b128 v[204:207], v153 offset:38912
	ds_read_b128 v[208:211], v153 offset:39936
	global_load_lds_dwordx4 v[180:181], off
	v_lshl_add_u64 v[180:181], s[42:43], 0, v[132:133]
	s_mov_b32 m0, s35
	s_nop 0
	global_load_lds_dwordx4 v[180:181], off
	s_waitcnt lgkmcnt(8)
	s_barrier
	s_waitcnt lgkmcnt(0)
	s_waitcnt lgkmcnt(0)
	v_mfma_f32_16x16x32_bf16 v[126:129], v[154:157], v[170:173], v[126:129]
	v_mfma_f32_16x16x32_bf16 v[122:125], v[162:165], v[170:173], v[122:125]
	v_mfma_f32_16x16x32_bf16 v[118:121], v[154:157], v[188:191], v[118:121]
	v_mfma_f32_16x16x32_bf16 v[110:113], v[162:165], v[188:191], v[110:113]
	v_mfma_f32_16x16x32_bf16 v[102:105], v[154:157], v[196:199], v[102:105]
	v_mfma_f32_16x16x32_bf16 v[94:97], v[162:165], v[196:199], v[94:97]
	v_mfma_f32_16x16x32_bf16 v[86:89], v[154:157], v[204:207], v[86:89]
	v_mfma_f32_16x16x32_bf16 v[78:81], v[162:165], v[204:207], v[78:81]
	v_mfma_f32_16x16x32_bf16 v[126:129], v[158:161], v[174:177], v[126:129]
	v_mfma_f32_16x16x32_bf16 v[122:125], v[166:169], v[174:177], v[122:125]
	v_mfma_f32_16x16x32_bf16 v[118:121], v[158:161], v[192:195], v[118:121]
	v_mfma_f32_16x16x32_bf16 v[110:113], v[166:169], v[192:195], v[110:113]
	v_mfma_f32_16x16x32_bf16 v[102:105], v[158:161], v[200:203], v[102:105]
	v_mfma_f32_16x16x32_bf16 v[94:97], v[166:169], v[200:203], v[94:97]
	v_mfma_f32_16x16x32_bf16 v[86:89], v[158:161], v[208:211], v[86:89]
	v_mfma_f32_16x16x32_bf16 v[78:81], v[166:169], v[208:211], v[78:81]
	s_barrier
	s_add_i32 s42, 0, 0x1c000
	s_add_i32 s43, s54, s20
	v_add_u32_e32 v140, s42, v145
	v_lshl_add_u64 v[142:143], v[142:143], 0, s[14:15]
	s_mov_b32 m0, s43
	ds_read_b128 v[212:215], v140
	ds_read_b128 v[216:219], v140 offset:1024
	ds_read_b128 v[220:223], v140 offset:2048
	ds_read_b128 v[224:227], v140 offset:3072
	global_load_lds_dwordx4 v[142:143], off
	v_lshl_add_u64 v[142:143], v[146:147], 0, s[14:15]
	s_add_i32 m0, s43, 0x2000
	s_nop 0
	global_load_lds_dwordx4 v[142:143], off
	s_barrier
	s_waitcnt lgkmcnt(0)
	s_waitcnt lgkmcnt(0)
	v_mfma_f32_16x16x32_bf16 v[114:117], v[212:215], v[170:173], v[114:117]
	v_mfma_f32_16x16x32_bf16 v[106:109], v[220:223], v[170:173], v[106:109]
	v_mfma_f32_16x16x32_bf16 v[98:101], v[212:215], v[188:191], v[98:101]
	v_mfma_f32_16x16x32_bf16 v[90:93], v[220:223], v[188:191], v[90:93]
	v_mfma_f32_16x16x32_bf16 v[82:85], v[212:215], v[196:199], v[82:85]
	v_mfma_f32_16x16x32_bf16 v[74:77], v[220:223], v[196:199], v[74:77]
	v_mfma_f32_16x16x32_bf16 v[70:73], v[212:215], v[204:207], v[70:73]
	v_mfma_f32_16x16x32_bf16 v[66:69], v[220:223], v[204:207], v[66:69]
	v_mfma_f32_16x16x32_bf16 v[114:117], v[216:219], v[174:177], v[114:117]
	v_mfma_f32_16x16x32_bf16 v[106:109], v[224:227], v[174:177], v[106:109]
	v_mfma_f32_16x16x32_bf16 v[98:101], v[216:219], v[192:195], v[98:101]
	v_mfma_f32_16x16x32_bf16 v[90:93], v[224:227], v[192:195], v[90:93]
	v_mfma_f32_16x16x32_bf16 v[82:85], v[216:219], v[200:203], v[82:85]
	v_mfma_f32_16x16x32_bf16 v[74:77], v[224:227], v[200:203], v[74:77]
	v_mfma_f32_16x16x32_bf16 v[70:73], v[216:219], v[208:211], v[70:73]
	v_mfma_f32_16x16x32_bf16 v[66:69], v[224:227], v[208:211], v[66:69]
	s_mov_b32 m0, s46
	v_lshl_add_u64 v[142:143], v[150:151], 0, s[14:15]
	s_barrier
	ds_read_b128 v[170:173], v153 offset:49152
	ds_read_b128 v[174:177], v153 offset:50176
	ds_read_b128 v[188:191], v153 offset:51200
	ds_read_b128 v[192:195], v153 offset:52224
	ds_read_b128 v[196:199], v153 offset:53248
	ds_read_b128 v[200:203], v153 offset:54272
	ds_read_b128 v[204:207], v153 offset:55296
	ds_read_b128 v[208:211], v153 offset:56320
	global_load_lds_dwordx4 v[142:143], off
	v_lshl_add_u64 v[142:143], v[178:179], 0, s[14:15]
	s_mov_b32 m0, s47
	s_nop 0
	global_load_lds_dwordx4 v[142:143], off
	s_barrier
	s_waitcnt lgkmcnt(0)
	s_waitcnt lgkmcnt(0)
	v_mfma_f32_16x16x32_bf16 v[62:65], v[154:157], v[170:173], v[62:65]
	v_mfma_f32_16x16x32_bf16 v[58:61], v[162:165], v[170:173], v[58:61]
	v_mfma_f32_16x16x32_bf16 v[54:57], v[154:157], v[188:191], v[54:57]
	v_mfma_f32_16x16x32_bf16 v[46:49], v[162:165], v[188:191], v[46:49]
	v_mfma_f32_16x16x32_bf16 v[38:41], v[154:157], v[196:199], v[38:41]
	v_mfma_f32_16x16x32_bf16 v[30:33], v[162:165], v[196:199], v[30:33]
	v_mfma_f32_16x16x32_bf16 v[22:25], v[154:157], v[204:207], v[22:25]
	v_mfma_f32_16x16x32_bf16 v[12:15], v[162:165], v[204:207], v[12:15]
	v_mfma_f32_16x16x32_bf16 v[62:65], v[158:161], v[174:177], v[62:65]
	v_mfma_f32_16x16x32_bf16 v[58:61], v[166:169], v[174:177], v[58:61]
	v_mfma_f32_16x16x32_bf16 v[54:57], v[158:161], v[192:195], v[54:57]
	v_mfma_f32_16x16x32_bf16 v[46:49], v[166:169], v[192:195], v[46:49]
	v_mfma_f32_16x16x32_bf16 v[38:41], v[158:161], v[200:203], v[38:41]
	v_mfma_f32_16x16x32_bf16 v[30:33], v[166:169], v[200:203], v[30:33]
	v_mfma_f32_16x16x32_bf16 v[22:25], v[158:161], v[208:211], v[22:25]
	v_mfma_f32_16x16x32_bf16 v[12:15], v[166:169], v[208:211], v[12:15]
	s_barrier
	s_add_u32 s40, s40, 0x40080
	s_addc_u32 s41, s41, 0
	s_add_i32 s42, s42, s20
	v_lshl_add_u64 v[142:143], s[40:41], 0, v[16:17]
	s_mov_b32 m0, s42
	s_nop 0
	global_load_lds_dwordx4 v[142:143], off
	v_lshl_add_u64 v[142:143], s[40:41], 0, v[134:135]
	s_add_i32 m0, s42, 0x2000
	s_nop 0
	global_load_lds_dwordx4 v[142:143], off
	s_waitcnt vmcnt(6)
	s_barrier
	v_mfma_f32_16x16x32_bf16 v[50:53], v[212:215], v[170:173], v[50:53]
	v_mfma_f32_16x16x32_bf16 v[42:45], v[220:223], v[170:173], v[42:45]
	v_mfma_f32_16x16x32_bf16 v[34:37], v[212:215], v[188:191], v[34:37]
	v_mfma_f32_16x16x32_bf16 v[26:29], v[220:223], v[188:191], v[26:29]
	v_mfma_f32_16x16x32_bf16 v[18:21], v[212:215], v[196:199], v[18:21]
	v_mfma_f32_16x16x32_bf16 v[8:11], v[220:223], v[196:199], v[8:11]
	v_mfma_f32_16x16x32_bf16 v[4:7], v[212:215], v[204:207], v[4:7]
	v_mfma_f32_16x16x32_bf16 v[0:3], v[220:223], v[204:207], v[0:3]
	v_mfma_f32_16x16x32_bf16 v[50:53], v[216:219], v[174:177], v[50:53]
	v_mfma_f32_16x16x32_bf16 v[42:45], v[224:227], v[174:177], v[42:45]
	v_mfma_f32_16x16x32_bf16 v[34:37], v[216:219], v[192:195], v[34:37]
	v_mfma_f32_16x16x32_bf16 v[26:29], v[224:227], v[192:195], v[26:29]
	v_mfma_f32_16x16x32_bf16 v[18:21], v[216:219], v[200:203], v[18:21]
	v_mfma_f32_16x16x32_bf16 v[8:11], v[224:227], v[200:203], v[8:11]
	v_mfma_f32_16x16x32_bf16 v[4:7], v[216:219], v[208:211], v[4:7]
	v_mfma_f32_16x16x32_bf16 v[0:3], v[224:227], v[208:211], v[0:3]
	s_add_i32 s53, s53, 2
	s_add_u32 s38, s38, 0x100
	s_addc_u32 s39, s39, 0
	s_add_u32 s45, s45, 0x100
	s_addc_u32 s52, s52, 0
	s_cmp_gt_u32 s53, 13
	s_barrier
	s_cbranch_scc0 .LBB0_670
	s_setprio 0
	v_lshl_add_u32 v168, s34, 8, v141
	v_readlane_b32 s38, v252, 38
	v_ashrrev_i32_e32 v169, 31, v168
	v_or_b32_e32 v164, 16, v168
	v_or_b32_e32 v160, 32, v168
	v_or_b32_e32 v154, 48, v168
	v_readlane_b32 s39, v252, 39
	v_ashrrev_i32_e32 v165, 31, v164
	v_ashrrev_i32_e32 v161, 31, v160
	v_ashrrev_i32_e32 v155, 31, v154
	v_lshl_add_u64 v[142:143], v[168:169], 2, s[38:39]
	v_lshl_add_u64 v[146:147], v[164:165], 2, s[38:39]
	v_lshl_add_u64 v[150:151], v[160:161], 2, s[38:39]
	v_lshl_add_u64 v[156:157], v[154:155], 2, s[38:39]
	s_waitcnt vmcnt(6)
	v_mov_b32_e32 v170, v144
	v_mov_b32_e32 v166, v148
	v_mov_b32_e32 v162, v152
	v_mov_b32_e32 v158, v183
	v_mov_b32_e32 v152, v230
	v_mov_b32_e32 v148, v231
	v_mov_b32_e32 v144, v233
	v_mov_b32_e32 v140, v250
	v_add_u32_e32 v156, 0x80, v168
	v_add_u32_e32 v150, 0x90, v168
	v_add_u32_e32 v146, 0xa0, v168
	v_add_u32_e32 v142, 0xb0, v168
	v_lshl_or_b32 v172, s22, 8, v149
	s_cmp_eq_u32 s51, 0
	v_ashrrev_i32_e32 v157, 31, v156
	v_ashrrev_i32_e32 v151, 31, v150
	v_ashrrev_i32_e32 v147, 31, v146
	v_ashrrev_i32_e32 v143, 31, v142
	v_ashrrev_i32_e32 v173, 31, v172
	s_cbranch_scc1 .LBB0_673
	v_mul_f32_e32 v170, 0xbfb8aa3b, v170
	v_mul_f32_e32 v166, 0xbfb8aa3b, v166
	v_mul_f32_e32 v162, 0xbfb8aa3b, v162
	v_mul_f32_e32 v158, 0xbfb8aa3b, v158
	v_mul_f32_e32 v152, 0xbfb8aa3b, v152
	v_mul_f32_e32 v148, 0xbfb8aa3b, v148
	v_mul_f32_e32 v144, 0xbfb8aa3b, v144
	v_mul_f32_e32 v140, 0xbfb8aa3b, v140
	v_mul_f32_e32 v176, v124, v170
	v_exp_f32_e32 v176, v176
	v_mul_f32_e32 v159, v126, v170
	v_mul_f32_e32 v167, v127, v170
	v_lshlrev_b64 v[174:175], 12, v[168:169]
	v_mul_f32_e32 v163, v122, v170
	v_mul_f32_e32 v169, v123, v170
	v_mul_f32_e32 v171, v128, v170
	v_add_f32_e32 v176, 1.0, v176
	v_mul_f32_e32 v177, v129, v170
	v_exp_f32_e32 v159, v159
	v_exp_f32_e32 v167, v167
	v_rcp_f32_e32 v176, v176
	v_mul_f32_e32 v178, v125, v170
	v_exp_f32_e32 v163, v163
	v_exp_f32_e32 v169, v169
	v_exp_f32_e32 v171, v171
	v_exp_f32_e32 v177, v177
	v_exp_f32_e32 v178, v178
	v_add_f32_e32 v159, 1.0, v159
	v_add_f32_e32 v167, 1.0, v167
	v_fma_f32 v176, v176, s31, 0.5
	v_rcp_f32_e32 v159, v159
	v_add_f32_e32 v163, 1.0, v163
	v_rcp_f32_e32 v167, v167
	v_add_f32_e32 v169, 1.0, v169
	v_add_f32_e32 v171, 1.0, v171
	v_max_f32_e32 v176, 1.0, v176
	v_add_f32_e32 v177, 1.0, v177
	v_rcp_f32_e32 v163, v163
	v_rcp_f32_e32 v169, v169
	v_rcp_f32_e32 v171, v171
	v_rcp_f32_e32 v177, v177
	v_cvt_u32_f32_sdwa v179, v176 dst_sel:WORD_1 dst_unused:UNUSED_PAD src0_sel:DWORD
	v_add_f32_e32 v176, 1.0, v178
	v_rcp_f32_e32 v176, v176
	v_fma_f32 v159, v159, s31, 0.5
	v_fma_f32 v167, v167, s31, 0.5
	v_max_f32_e32 v159, 1.0, v159
	v_fma_f32 v163, v163, s31, 0.5
	v_max_f32_e32 v167, 1.0, v167
	v_fma_f32 v169, v169, s31, 0.5
	v_fma_f32 v171, v171, s31, 0.5
	v_fma_f32 v177, v177, s31, 0.5
	v_cvt_u32_f32_e32 v159, v159
	v_max_f32_e32 v163, 1.0, v163
	v_cvt_u32_f32_e32 v167, v167
	v_max_f32_e32 v169, 1.0, v169
	v_max_f32_e32 v171, 1.0, v171
	v_max_f32_e32 v177, 1.0, v177
	v_fma_f32 v176, v176, s31, 0.5
	v_cvt_u32_f32_e32 v163, v163
	v_cvt_u32_f32_e32 v169, v169
	v_cvt_u32_f32_sdwa v171, v171 dst_sel:WORD_1 dst_unused:UNUSED_PAD src0_sel:DWORD
	v_cvt_u32_f32_sdwa v177, v177 dst_sel:BYTE_3 dst_unused:UNUSED_PAD src0_sel:DWORD
	v_max_f32_e32 v176, 1.0, v176
	v_cvt_u32_f32_sdwa v178, v176 dst_sel:BYTE_3 dst_unused:UNUSED_PAD src0_sel:DWORD
	v_readlane_b32 s22, v252, 34
	v_readlane_b32 s23, v252, 35
	v_lshl_or_b32 v159, v167, 8, v159
	v_or3_b32 v176, v159, v171, v177
	v_lshl_add_u64 v[174:175], s[22:23], 0, v[174:175]
	v_lshl_or_b32 v159, v169, 8, v163
	v_lshl_add_u64 v[174:175], v[174:175], 0, v[172:173]
	v_or3_b32 v177, v159, v179, v178
	global_store_dwordx2 v[174:175], v[176:177], off
	v_mul_f32_e32 v176, v108, v170
	v_exp_f32_e32 v176, v176
	v_mul_f32_e32 v159, v114, v170
	v_mul_f32_e32 v167, v115, v170
	v_mul_f32_e32 v163, v106, v170
	v_mul_f32_e32 v169, v107, v170
	v_mul_f32_e32 v171, v116, v170
	v_add_f32_e32 v176, 1.0, v176
	v_mul_f32_e32 v177, v117, v170
	v_exp_f32_e32 v159, v159
	v_exp_f32_e32 v167, v167
	v_rcp_f32_e32 v176, v176
	v_mul_f32_e32 v178, v109, v170
	v_exp_f32_e32 v163, v163
	v_exp_f32_e32 v169, v169
	v_exp_f32_e32 v171, v171
	v_exp_f32_e32 v177, v177
	v_exp_f32_e32 v178, v178
	v_add_f32_e32 v159, 1.0, v159
	v_add_f32_e32 v167, 1.0, v167
	v_fma_f32 v176, v176, s31, 0.5
	v_rcp_f32_e32 v159, v159
	v_add_f32_e32 v163, 1.0, v163
	v_rcp_f32_e32 v167, v167
	v_add_f32_e32 v169, 1.0, v169
	v_add_f32_e32 v171, 1.0, v171
	v_max_f32_e32 v176, 1.0, v176
	v_add_f32_e32 v177, 1.0, v177
	v_rcp_f32_e32 v163, v163
	v_rcp_f32_e32 v169, v169
	v_rcp_f32_e32 v171, v171
	v_rcp_f32_e32 v177, v177
	v_cvt_u32_f32_sdwa v179, v176 dst_sel:WORD_1 dst_unused:UNUSED_PAD src0_sel:DWORD
	v_add_f32_e32 v176, 1.0, v178
	v_rcp_f32_e32 v176, v176
	v_fma_f32 v159, v159, s31, 0.5
	v_fma_f32 v167, v167, s31, 0.5
	v_max_f32_e32 v159, 1.0, v159
	v_fma_f32 v163, v163, s31, 0.5
	v_max_f32_e32 v167, 1.0, v167
	v_fma_f32 v169, v169, s31, 0.5
	v_fma_f32 v171, v171, s31, 0.5
	v_fma_f32 v177, v177, s31, 0.5
	v_cvt_u32_f32_e32 v159, v159
	v_max_f32_e32 v163, 1.0, v163
	v_cvt_u32_f32_e32 v167, v167
	v_max_f32_e32 v169, 1.0, v169
	v_max_f32_e32 v171, 1.0, v171
	v_max_f32_e32 v177, 1.0, v177
	v_fma_f32 v176, v176, s31, 0.5
	v_cvt_u32_f32_e32 v163, v163
	v_cvt_u32_f32_e32 v169, v169
	v_cvt_u32_f32_sdwa v171, v171 dst_sel:WORD_1 dst_unused:UNUSED_PAD src0_sel:DWORD
	v_cvt_u32_f32_sdwa v177, v177 dst_sel:BYTE_3 dst_unused:UNUSED_PAD src0_sel:DWORD
	v_max_f32_e32 v176, 1.0, v176
	v_cvt_u32_f32_sdwa v178, v176 dst_sel:BYTE_3 dst_unused:UNUSED_PAD src0_sel:DWORD
	v_lshl_or_b32 v159, v167, 8, v159
	v_or3_b32 v176, v159, v171, v177
	v_lshl_or_b32 v159, v169, 8, v163
	v_or3_b32 v177, v159, v179, v178
	global_store_dwordx2 v[174:175], v[176:177], off offset:128
	v_lshlrev_b64 v[174:175], 12, v[164:165]
	v_mul_f32_e32 v159, v118, v166
	v_mul_f32_e32 v165, v119, v166
	v_mul_f32_e32 v163, v110, v166
	v_mul_f32_e32 v167, v111, v166
	v_mul_f32_e32 v169, v120, v166
	v_mul_f32_e32 v176, v121, v166
	v_exp_f32_e32 v159, v159
	v_exp_f32_e32 v165, v165
	v_mul_f32_e32 v171, v112, v166
	v_mul_f32_e32 v177, v113, v166
	v_exp_f32_e32 v163, v163
	v_exp_f32_e32 v167, v167
	v_exp_f32_e32 v169, v169
	v_exp_f32_e32 v176, v176
	v_exp_f32_e32 v171, v171
	v_exp_f32_e32 v177, v177
	v_add_f32_e32 v159, 1.0, v159
	v_add_f32_e32 v165, 1.0, v165
	v_rcp_f32_e32 v159, v159
	v_add_f32_e32 v163, 1.0, v163
	v_rcp_f32_e32 v165, v165
	v_add_f32_e32 v167, 1.0, v167
	v_add_f32_e32 v169, 1.0, v169
	v_add_f32_e32 v176, 1.0, v176
	v_rcp_f32_e32 v163, v163
	v_rcp_f32_e32 v167, v167
	v_rcp_f32_e32 v169, v169
	v_add_f32_e32 v171, 1.0, v171
	v_rcp_f32_e32 v176, v176
	v_add_f32_e32 v177, 1.0, v177
	v_rcp_f32_e32 v171, v171
	v_rcp_f32_e32 v177, v177
	v_fma_f32 v159, v159, s31, 0.5
	v_fma_f32 v165, v165, s31, 0.5
	v_max_f32_e32 v159, 1.0, v159
	v_fma_f32 v163, v163, s31, 0.5
	v_max_f32_e32 v165, 1.0, v165
	v_fma_f32 v167, v167, s31, 0.5
	v_fma_f32 v169, v169, s31, 0.5
	v_fma_f32 v176, v176, s31, 0.5
	v_cvt_u32_f32_e32 v159, v159
	v_max_f32_e32 v163, 1.0, v163
	v_cvt_u32_f32_e32 v165, v165
	v_max_f32_e32 v167, 1.0, v167
	v_max_f32_e32 v169, 1.0, v169
	v_fma_f32 v171, v171, s31, 0.5
	v_max_f32_e32 v176, 1.0, v176
	v_fma_f32 v177, v177, s31, 0.5
	v_cvt_u32_f32_e32 v163, v163
	v_cvt_u32_f32_e32 v167, v167
	v_cvt_u32_f32_sdwa v169, v169 dst_sel:WORD_1 dst_unused:UNUSED_PAD src0_sel:DWORD
	v_max_f32_e32 v171, 1.0, v171
	v_cvt_u32_f32_sdwa v176, v176 dst_sel:BYTE_3 dst_unused:UNUSED_PAD src0_sel:DWORD
	v_max_f32_e32 v177, 1.0, v177
	v_cvt_u32_f32_sdwa v171, v171 dst_sel:WORD_1 dst_unused:UNUSED_PAD src0_sel:DWORD
	v_cvt_u32_f32_sdwa v177, v177 dst_sel:BYTE_3 dst_unused:UNUSED_PAD src0_sel:DWORD
	v_lshl_or_b32 v159, v165, 8, v159
	v_lshl_add_u64 v[174:175], s[22:23], 0, v[174:175]
	v_or3_b32 v176, v159, v169, v176
	v_lshl_or_b32 v159, v167, 8, v163
	v_lshl_add_u64 v[174:175], v[174:175], 0, v[172:173]
	v_or3_b32 v177, v159, v171, v177
	v_mul_f32_e32 v159, v98, v166
	v_mul_f32_e32 v165, v99, v166
	v_mul_f32_e32 v163, v90, v166
	global_store_dwordx2 v[174:175], v[176:177], off
	v_mul_f32_e32 v167, v91, v166
	v_mul_f32_e32 v169, v100, v166
	v_mul_f32_e32 v176, v101, v166
	v_exp_f32_e32 v159, v159
	v_exp_f32_e32 v165, v165
	v_mul_f32_e32 v171, v92, v166
	v_mul_f32_e32 v177, v93, v166
	v_exp_f32_e32 v163, v163
	v_exp_f32_e32 v167, v167
	v_exp_f32_e32 v169, v169
	v_exp_f32_e32 v176, v176
	v_exp_f32_e32 v171, v171
	v_exp_f32_e32 v177, v177
	v_add_f32_e32 v159, 1.0, v159
	v_add_f32_e32 v165, 1.0, v165
	v_rcp_f32_e32 v159, v159
	v_add_f32_e32 v163, 1.0, v163
	v_rcp_f32_e32 v165, v165
	v_add_f32_e32 v167, 1.0, v167
	v_add_f32_e32 v169, 1.0, v169
	v_add_f32_e32 v176, 1.0, v176
	v_rcp_f32_e32 v163, v163
	v_rcp_f32_e32 v167, v167
	v_rcp_f32_e32 v169, v169
	v_add_f32_e32 v171, 1.0, v171
	v_rcp_f32_e32 v176, v176
	v_add_f32_e32 v177, 1.0, v177
	v_rcp_f32_e32 v171, v171
	v_rcp_f32_e32 v177, v177
	v_fma_f32 v159, v159, s31, 0.5
	v_fma_f32 v165, v165, s31, 0.5
	v_max_f32_e32 v159, 1.0, v159
	v_fma_f32 v163, v163, s31, 0.5
	v_max_f32_e32 v165, 1.0, v165
	v_fma_f32 v167, v167, s31, 0.5
	v_fma_f32 v169, v169, s31, 0.5
	v_fma_f32 v176, v176, s31, 0.5
	v_cvt_u32_f32_e32 v159, v159
	v_max_f32_e32 v163, 1.0, v163
	v_cvt_u32_f32_e32 v165, v165
	v_max_f32_e32 v167, 1.0, v167
	v_max_f32_e32 v169, 1.0, v169
	v_fma_f32 v171, v171, s31, 0.5
	v_max_f32_e32 v176, 1.0, v176
	v_fma_f32 v177, v177, s31, 0.5
	v_cvt_u32_f32_e32 v163, v163
	v_cvt_u32_f32_e32 v167, v167
	v_cvt_u32_f32_sdwa v169, v169 dst_sel:WORD_1 dst_unused:UNUSED_PAD src0_sel:DWORD
	v_max_f32_e32 v171, 1.0, v171
	v_cvt_u32_f32_sdwa v176, v176 dst_sel:BYTE_3 dst_unused:UNUSED_PAD src0_sel:DWORD
	v_max_f32_e32 v177, 1.0, v177
	v_cvt_u32_f32_sdwa v171, v171 dst_sel:WORD_1 dst_unused:UNUSED_PAD src0_sel:DWORD
	v_cvt_u32_f32_sdwa v177, v177 dst_sel:BYTE_3 dst_unused:UNUSED_PAD src0_sel:DWORD
	v_lshl_or_b32 v159, v165, 8, v159
	v_or3_b32 v176, v159, v169, v176
	v_lshl_or_b32 v159, v167, 8, v163
	v_or3_b32 v177, v159, v171, v177
	v_mul_f32_e32 v159, v102, v162
	v_mul_f32_e32 v163, v103, v162
	global_store_dwordx2 v[174:175], v[176:177], off offset:128
	v_lshlrev_b64 v[174:175], 12, v[160:161]
	v_mul_f32_e32 v161, v94, v162
	v_mul_f32_e32 v165, v95, v162
	v_mul_f32_e32 v167, v104, v162
	v_mul_f32_e32 v171, v105, v162
	v_exp_f32_e32 v159, v159
	v_exp_f32_e32 v163, v163
	v_mul_f32_e32 v169, v96, v162
	v_mul_f32_e32 v176, v97, v162
	v_exp_f32_e32 v161, v161
	v_exp_f32_e32 v165, v165
	v_exp_f32_e32 v167, v167
	v_exp_f32_e32 v171, v171
	v_exp_f32_e32 v169, v169
	v_exp_f32_e32 v176, v176
	v_add_f32_e32 v159, 1.0, v159
	v_add_f32_e32 v163, 1.0, v163
	v_rcp_f32_e32 v159, v159
	v_add_f32_e32 v161, 1.0, v161
	v_rcp_f32_e32 v163, v163
	v_add_f32_e32 v165, 1.0, v165
	v_add_f32_e32 v167, 1.0, v167
	v_add_f32_e32 v171, 1.0, v171
	v_rcp_f32_e32 v161, v161
	v_rcp_f32_e32 v165, v165
	v_rcp_f32_e32 v167, v167
	v_add_f32_e32 v169, 1.0, v169
	v_rcp_f32_e32 v171, v171
	v_add_f32_e32 v176, 1.0, v176
	v_rcp_f32_e32 v169, v169
	v_rcp_f32_e32 v176, v176
	v_fma_f32 v159, v159, s31, 0.5
	v_fma_f32 v163, v163, s31, 0.5
	v_max_f32_e32 v159, 1.0, v159
	v_fma_f32 v161, v161, s31, 0.5
	v_max_f32_e32 v163, 1.0, v163
	v_fma_f32 v165, v165, s31, 0.5
	v_fma_f32 v167, v167, s31, 0.5
	v_fma_f32 v171, v171, s31, 0.5
	v_cvt_u32_f32_e32 v159, v159
	v_max_f32_e32 v161, 1.0, v161
	v_cvt_u32_f32_e32 v163, v163
	v_max_f32_e32 v165, 1.0, v165
	v_max_f32_e32 v167, 1.0, v167
	v_fma_f32 v169, v169, s31, 0.5
	v_max_f32_e32 v171, 1.0, v171
	v_fma_f32 v176, v176, s31, 0.5
	v_cvt_u32_f32_e32 v161, v161
	v_cvt_u32_f32_e32 v165, v165
	v_cvt_u32_f32_sdwa v167, v167 dst_sel:WORD_1 dst_unused:UNUSED_PAD src0_sel:DWORD
	v_max_f32_e32 v169, 1.0, v169
	v_cvt_u32_f32_sdwa v171, v171 dst_sel:BYTE_3 dst_unused:UNUSED_PAD src0_sel:DWORD
	v_max_f32_e32 v176, 1.0, v176
	v_cvt_u32_f32_sdwa v169, v169 dst_sel:WORD_1 dst_unused:UNUSED_PAD src0_sel:DWORD
	v_cvt_u32_f32_sdwa v177, v176 dst_sel:BYTE_3 dst_unused:UNUSED_PAD src0_sel:DWORD
	v_lshl_or_b32 v159, v163, 8, v159
	v_or3_b32 v176, v159, v167, v171
	v_lshl_or_b32 v159, v165, 8, v161
	v_lshl_add_u64 v[174:175], s[22:23], 0, v[174:175]
	v_or3_b32 v177, v159, v169, v177
	v_mul_f32_e32 v159, v82, v162
	v_mul_f32_e32 v163, v83, v162
	v_lshl_add_u64 v[174:175], v[174:175], 0, v[172:173]
	v_mul_f32_e32 v161, v74, v162
	v_mul_f32_e32 v165, v75, v162
	v_mul_f32_e32 v167, v84, v162
	v_mul_f32_e32 v171, v85, v162
	v_exp_f32_e32 v159, v159
	global_store_dwordx2 v[174:175], v[176:177], off
	v_exp_f32_e32 v163, v163
	v_mul_f32_e32 v169, v76, v162
	v_mul_f32_e32 v176, v77, v162
	v_exp_f32_e32 v161, v161
	v_exp_f32_e32 v165, v165
	v_exp_f32_e32 v167, v167
	v_exp_f32_e32 v171, v171
	v_exp_f32_e32 v169, v169
	v_exp_f32_e32 v176, v176
	v_add_f32_e32 v159, 1.0, v159
	v_add_f32_e32 v163, 1.0, v163
	v_rcp_f32_e32 v159, v159
	v_add_f32_e32 v161, 1.0, v161
	v_rcp_f32_e32 v163, v163
	v_add_f32_e32 v165, 1.0, v165
	v_add_f32_e32 v167, 1.0, v167
	v_add_f32_e32 v171, 1.0, v171
	v_rcp_f32_e32 v161, v161
	v_rcp_f32_e32 v165, v165
	v_rcp_f32_e32 v167, v167
	v_add_f32_e32 v169, 1.0, v169
	v_rcp_f32_e32 v171, v171
	v_add_f32_e32 v176, 1.0, v176
	v_rcp_f32_e32 v169, v169
	v_rcp_f32_e32 v176, v176
	v_fma_f32 v159, v159, s31, 0.5
	v_fma_f32 v163, v163, s31, 0.5
	v_max_f32_e32 v159, 1.0, v159
	v_fma_f32 v161, v161, s31, 0.5
	v_max_f32_e32 v163, 1.0, v163
	v_fma_f32 v165, v165, s31, 0.5
	v_fma_f32 v167, v167, s31, 0.5
	v_fma_f32 v171, v171, s31, 0.5
	v_cvt_u32_f32_e32 v159, v159
	v_max_f32_e32 v161, 1.0, v161
	v_cvt_u32_f32_e32 v163, v163
	v_max_f32_e32 v165, 1.0, v165
	v_max_f32_e32 v167, 1.0, v167
	v_fma_f32 v169, v169, s31, 0.5
	v_max_f32_e32 v171, 1.0, v171
	v_fma_f32 v176, v176, s31, 0.5
	v_cvt_u32_f32_e32 v161, v161
	v_cvt_u32_f32_e32 v165, v165
	v_cvt_u32_f32_sdwa v167, v167 dst_sel:WORD_1 dst_unused:UNUSED_PAD src0_sel:DWORD
	v_max_f32_e32 v169, 1.0, v169
	v_cvt_u32_f32_sdwa v171, v171 dst_sel:BYTE_3 dst_unused:UNUSED_PAD src0_sel:DWORD
	v_max_f32_e32 v176, 1.0, v176
	v_cvt_u32_f32_sdwa v169, v169 dst_sel:WORD_1 dst_unused:UNUSED_PAD src0_sel:DWORD
	v_cvt_u32_f32_sdwa v177, v176 dst_sel:BYTE_3 dst_unused:UNUSED_PAD src0_sel:DWORD
	v_lshl_or_b32 v159, v163, 8, v159
	v_or3_b32 v176, v159, v167, v171
	v_lshl_or_b32 v159, v165, 8, v161
	v_or3_b32 v177, v159, v169, v177
	global_store_dwordx2 v[174:175], v[176:177], off offset:128
	v_lshlrev_b64 v[174:175], 12, v[154:155]
	v_mul_f32_e32 v155, v86, v158
	v_mul_f32_e32 v161, v87, v158
	v_mul_f32_e32 v159, v78, v158
	v_mul_f32_e32 v163, v79, v158
	v_mul_f32_e32 v165, v88, v158
	v_mul_f32_e32 v169, v89, v158
	v_exp_f32_e32 v155, v155
	v_exp_f32_e32 v161, v161
	v_mul_f32_e32 v167, v80, v158
	v_mul_f32_e32 v171, v81, v158
	v_exp_f32_e32 v159, v159
	v_exp_f32_e32 v163, v163
	v_exp_f32_e32 v165, v165
	v_exp_f32_e32 v169, v169
	v_exp_f32_e32 v167, v167
	v_exp_f32_e32 v171, v171
	v_add_f32_e32 v155, 1.0, v155
	v_add_f32_e32 v161, 1.0, v161
	v_rcp_f32_e32 v155, v155
	v_add_f32_e32 v159, 1.0, v159
	v_rcp_f32_e32 v161, v161
	v_add_f32_e32 v163, 1.0, v163
	v_add_f32_e32 v165, 1.0, v165
	v_add_f32_e32 v169, 1.0, v169
	v_rcp_f32_e32 v159, v159
	v_rcp_f32_e32 v163, v163
	v_rcp_f32_e32 v165, v165
	v_add_f32_e32 v167, 1.0, v167
	v_rcp_f32_e32 v169, v169
	v_add_f32_e32 v171, 1.0, v171
	v_rcp_f32_e32 v167, v167
	v_rcp_f32_e32 v171, v171
	v_fma_f32 v155, v155, s31, 0.5
	v_fma_f32 v161, v161, s31, 0.5
	v_max_f32_e32 v155, 1.0, v155
	v_fma_f32 v159, v159, s31, 0.5
	v_max_f32_e32 v161, 1.0, v161
	v_fma_f32 v163, v163, s31, 0.5
	v_fma_f32 v165, v165, s31, 0.5
	v_fma_f32 v169, v169, s31, 0.5
	v_cvt_u32_f32_e32 v155, v155
	v_max_f32_e32 v159, 1.0, v159
	v_cvt_u32_f32_e32 v161, v161
	v_max_f32_e32 v163, 1.0, v163
	v_max_f32_e32 v165, 1.0, v165
	v_fma_f32 v167, v167, s31, 0.5
	v_max_f32_e32 v169, 1.0, v169
	v_fma_f32 v171, v171, s31, 0.5
	v_cvt_u32_f32_e32 v159, v159
	v_cvt_u32_f32_e32 v163, v163
	v_cvt_u32_f32_sdwa v165, v165 dst_sel:WORD_1 dst_unused:UNUSED_PAD src0_sel:DWORD
	v_max_f32_e32 v167, 1.0, v167
	v_cvt_u32_f32_sdwa v169, v169 dst_sel:BYTE_3 dst_unused:UNUSED_PAD src0_sel:DWORD
	v_max_f32_e32 v171, 1.0, v171
	v_cvt_u32_f32_sdwa v167, v167 dst_sel:WORD_1 dst_unused:UNUSED_PAD src0_sel:DWORD
	v_cvt_u32_f32_sdwa v171, v171 dst_sel:BYTE_3 dst_unused:UNUSED_PAD src0_sel:DWORD
	v_lshl_or_b32 v155, v161, 8, v155
	v_or3_b32 v176, v155, v165, v169
	v_lshl_or_b32 v155, v163, 8, v159
	v_or3_b32 v177, v155, v167, v171
	v_mul_f32_e32 v155, v70, v158
	v_mul_f32_e32 v161, v71, v158
	v_mul_f32_e32 v159, v66, v158
	v_mul_f32_e32 v163, v67, v158
	v_mul_f32_e32 v165, v72, v158
	v_mul_f32_e32 v169, v73, v158
	v_exp_f32_e32 v155, v155
	v_exp_f32_e32 v161, v161
	v_mul_f32_e32 v167, v68, v158
	v_mul_f32_e32 v171, v69, v158
	v_exp_f32_e32 v159, v159
	v_exp_f32_e32 v163, v163
	v_exp_f32_e32 v165, v165
	v_exp_f32_e32 v169, v169
	v_exp_f32_e32 v167, v167
	v_exp_f32_e32 v171, v171
	v_add_f32_e32 v155, 1.0, v155
	v_add_f32_e32 v161, 1.0, v161
	v_rcp_f32_e32 v155, v155
	v_add_f32_e32 v159, 1.0, v159
	v_rcp_f32_e32 v161, v161
	v_add_f32_e32 v163, 1.0, v163
	v_add_f32_e32 v165, 1.0, v165
	v_add_f32_e32 v169, 1.0, v169
	v_rcp_f32_e32 v159, v159
	v_rcp_f32_e32 v163, v163
	v_rcp_f32_e32 v165, v165
	v_add_f32_e32 v167, 1.0, v167
	v_rcp_f32_e32 v169, v169
	v_add_f32_e32 v171, 1.0, v171
	v_rcp_f32_e32 v167, v167
	v_rcp_f32_e32 v171, v171
	v_fma_f32 v155, v155, s31, 0.5
	v_fma_f32 v161, v161, s31, 0.5
	v_max_f32_e32 v155, 1.0, v155
	v_fma_f32 v159, v159, s31, 0.5
	v_max_f32_e32 v161, 1.0, v161
	v_fma_f32 v163, v163, s31, 0.5
	v_fma_f32 v165, v165, s31, 0.5
	v_fma_f32 v169, v169, s31, 0.5
	v_cvt_u32_f32_e32 v155, v155
	v_max_f32_e32 v159, 1.0, v159
	v_cvt_u32_f32_e32 v161, v161
	v_max_f32_e32 v163, 1.0, v163
	v_max_f32_e32 v165, 1.0, v165
	v_fma_f32 v167, v167, s31, 0.5
	v_max_f32_e32 v169, 1.0, v169
	v_fma_f32 v171, v171, s31, 0.5
	v_cvt_u32_f32_e32 v159, v159
	v_cvt_u32_f32_e32 v163, v163
	v_cvt_u32_f32_sdwa v165, v165 dst_sel:WORD_1 dst_unused:UNUSED_PAD src0_sel:DWORD
	v_max_f32_e32 v167, 1.0, v167
	v_cvt_u32_f32_sdwa v169, v169 dst_sel:BYTE_3 dst_unused:UNUSED_PAD src0_sel:DWORD
	v_max_f32_e32 v171, 1.0, v171
	v_cvt_u32_f32_sdwa v167, v167 dst_sel:WORD_1 dst_unused:UNUSED_PAD src0_sel:DWORD
	v_cvt_u32_f32_sdwa v171, v171 dst_sel:BYTE_3 dst_unused:UNUSED_PAD src0_sel:DWORD
	v_lshl_add_u64 v[174:175], s[22:23], 0, v[174:175]
	v_lshl_add_u64 v[174:175], v[174:175], 0, v[172:173]
	v_lshl_or_b32 v155, v161, 8, v155
	global_store_dwordx2 v[174:175], v[176:177], off
	v_or3_b32 v176, v155, v165, v169
	v_lshl_or_b32 v155, v163, 8, v159
	v_or3_b32 v177, v155, v167, v171
	v_mul_f32_e32 v155, v62, v152
	v_mul_f32_e32 v159, v63, v152
	global_store_dwordx2 v[174:175], v[176:177], off offset:128
	v_lshlrev_b64 v[174:175], 12, v[156:157]
	v_mul_f32_e32 v157, v58, v152
	v_mul_f32_e32 v161, v59, v152
	v_mul_f32_e32 v163, v64, v152
	v_mul_f32_e32 v167, v65, v152
	v_exp_f32_e32 v155, v155
	v_exp_f32_e32 v159, v159
	v_mul_f32_e32 v165, v60, v152
	v_mul_f32_e32 v169, v61, v152
	v_exp_f32_e32 v157, v157
	v_exp_f32_e32 v161, v161
	v_exp_f32_e32 v163, v163
	v_exp_f32_e32 v167, v167
	v_exp_f32_e32 v165, v165
	v_exp_f32_e32 v169, v169
	v_add_f32_e32 v155, 1.0, v155
	v_add_f32_e32 v159, 1.0, v159
	v_rcp_f32_e32 v155, v155
	v_add_f32_e32 v157, 1.0, v157
	v_rcp_f32_e32 v159, v159
	v_add_f32_e32 v161, 1.0, v161
	v_add_f32_e32 v163, 1.0, v163
	v_add_f32_e32 v167, 1.0, v167
	v_rcp_f32_e32 v157, v157
	v_rcp_f32_e32 v161, v161
	v_rcp_f32_e32 v163, v163
	v_add_f32_e32 v165, 1.0, v165
	v_rcp_f32_e32 v167, v167
	v_add_f32_e32 v169, 1.0, v169
	v_rcp_f32_e32 v165, v165
	v_rcp_f32_e32 v169, v169
	v_fma_f32 v155, v155, s31, 0.5
	v_fma_f32 v159, v159, s31, 0.5
	v_max_f32_e32 v155, 1.0, v155
	v_fma_f32 v157, v157, s31, 0.5
	v_max_f32_e32 v159, 1.0, v159
	v_fma_f32 v161, v161, s31, 0.5
	v_fma_f32 v163, v163, s31, 0.5
	v_fma_f32 v167, v167, s31, 0.5
	v_cvt_u32_f32_e32 v155, v155
	v_max_f32_e32 v157, 1.0, v157
	v_cvt_u32_f32_e32 v159, v159
	v_max_f32_e32 v161, 1.0, v161
	v_max_f32_e32 v163, 1.0, v163
	v_fma_f32 v165, v165, s31, 0.5
	v_max_f32_e32 v167, 1.0, v167
	v_fma_f32 v169, v169, s31, 0.5
	v_cvt_u32_f32_e32 v157, v157
	v_cvt_u32_f32_e32 v161, v161
	v_cvt_u32_f32_sdwa v163, v163 dst_sel:WORD_1 dst_unused:UNUSED_PAD src0_sel:DWORD
	v_max_f32_e32 v165, 1.0, v165
	v_cvt_u32_f32_sdwa v167, v167 dst_sel:BYTE_3 dst_unused:UNUSED_PAD src0_sel:DWORD
	v_max_f32_e32 v169, 1.0, v169
	v_cvt_u32_f32_sdwa v165, v165 dst_sel:WORD_1 dst_unused:UNUSED_PAD src0_sel:DWORD
	v_cvt_u32_f32_sdwa v169, v169 dst_sel:BYTE_3 dst_unused:UNUSED_PAD src0_sel:DWORD
	v_lshl_or_b32 v155, v159, 8, v155
	v_or3_b32 v176, v155, v163, v167
	v_lshl_or_b32 v155, v161, 8, v157
	v_or3_b32 v177, v155, v165, v169
	v_mul_f32_e32 v155, v50, v152
	v_mul_f32_e32 v159, v51, v152
	v_mul_f32_e32 v157, v42, v152
	v_mul_f32_e32 v161, v43, v152
	v_mul_f32_e32 v163, v52, v152
	v_mul_f32_e32 v167, v53, v152
	v_exp_f32_e32 v155, v155
	v_exp_f32_e32 v159, v159
	v_mul_f32_e32 v165, v44, v152
	v_mul_f32_e32 v169, v45, v152
	v_exp_f32_e32 v157, v157
	v_exp_f32_e32 v161, v161
	v_exp_f32_e32 v163, v163
	v_exp_f32_e32 v167, v167
	v_exp_f32_e32 v165, v165
	v_exp_f32_e32 v169, v169
	v_add_f32_e32 v155, 1.0, v155
	v_add_f32_e32 v159, 1.0, v159
	v_rcp_f32_e32 v155, v155
	v_add_f32_e32 v157, 1.0, v157
	v_rcp_f32_e32 v159, v159
	v_add_f32_e32 v161, 1.0, v161
	v_add_f32_e32 v163, 1.0, v163
	v_add_f32_e32 v167, 1.0, v167
	v_rcp_f32_e32 v157, v157
	v_rcp_f32_e32 v161, v161
	v_rcp_f32_e32 v163, v163
	v_add_f32_e32 v165, 1.0, v165
	v_rcp_f32_e32 v167, v167
	v_add_f32_e32 v169, 1.0, v169
	v_rcp_f32_e32 v165, v165
	v_rcp_f32_e32 v169, v169
	v_fma_f32 v155, v155, s31, 0.5
	v_fma_f32 v159, v159, s31, 0.5
	v_max_f32_e32 v155, 1.0, v155
	v_fma_f32 v157, v157, s31, 0.5
	v_max_f32_e32 v159, 1.0, v159
	v_fma_f32 v161, v161, s31, 0.5
	v_fma_f32 v163, v163, s31, 0.5
	v_fma_f32 v167, v167, s31, 0.5
	v_cvt_u32_f32_e32 v155, v155
	v_max_f32_e32 v157, 1.0, v157
	v_cvt_u32_f32_e32 v159, v159
	v_max_f32_e32 v161, 1.0, v161
	v_max_f32_e32 v163, 1.0, v163
	v_fma_f32 v165, v165, s31, 0.5
	v_max_f32_e32 v167, 1.0, v167
	v_fma_f32 v169, v169, s31, 0.5
	v_cvt_u32_f32_e32 v157, v157
	v_cvt_u32_f32_e32 v161, v161
	v_cvt_u32_f32_sdwa v163, v163 dst_sel:WORD_1 dst_unused:UNUSED_PAD src0_sel:DWORD
	v_max_f32_e32 v165, 1.0, v165
	v_cvt_u32_f32_sdwa v167, v167 dst_sel:BYTE_3 dst_unused:UNUSED_PAD src0_sel:DWORD
	v_max_f32_e32 v169, 1.0, v169
	v_cvt_u32_f32_sdwa v165, v165 dst_sel:WORD_1 dst_unused:UNUSED_PAD src0_sel:DWORD
	v_cvt_u32_f32_sdwa v169, v169 dst_sel:BYTE_3 dst_unused:UNUSED_PAD src0_sel:DWORD
	v_lshl_add_u64 v[174:175], s[22:23], 0, v[174:175]
	v_lshl_add_u64 v[174:175], v[174:175], 0, v[172:173]
	v_lshl_or_b32 v155, v159, 8, v155
	global_store_dwordx2 v[174:175], v[176:177], off
	v_or3_b32 v176, v155, v163, v167
	v_lshl_or_b32 v155, v161, 8, v157
	v_or3_b32 v177, v155, v165, v169
	global_store_dwordx2 v[174:175], v[176:177], off offset:128
	v_lshlrev_b64 v[174:175], 12, v[150:151]
	v_mul_f32_e32 v151, v54, v148
	v_mul_f32_e32 v157, v55, v148
	v_mul_f32_e32 v155, v46, v148
	v_mul_f32_e32 v159, v47, v148
	v_mul_f32_e32 v161, v56, v148
	v_mul_f32_e32 v165, v57, v148
	v_exp_f32_e32 v151, v151
	v_exp_f32_e32 v157, v157
	v_mul_f32_e32 v163, v48, v148
	v_mul_f32_e32 v167, v49, v148
	v_exp_f32_e32 v155, v155
	v_exp_f32_e32 v159, v159
	v_exp_f32_e32 v161, v161
	v_exp_f32_e32 v165, v165
	v_exp_f32_e32 v163, v163
	v_exp_f32_e32 v167, v167
	v_add_f32_e32 v151, 1.0, v151
	v_add_f32_e32 v157, 1.0, v157
	v_rcp_f32_e32 v151, v151
	v_add_f32_e32 v155, 1.0, v155
	v_rcp_f32_e32 v157, v157
	v_add_f32_e32 v159, 1.0, v159
	v_add_f32_e32 v161, 1.0, v161
	v_add_f32_e32 v165, 1.0, v165
	v_rcp_f32_e32 v155, v155
	v_rcp_f32_e32 v159, v159
	v_rcp_f32_e32 v161, v161
	v_add_f32_e32 v163, 1.0, v163
	v_rcp_f32_e32 v165, v165
	v_add_f32_e32 v167, 1.0, v167
	v_rcp_f32_e32 v163, v163
	v_rcp_f32_e32 v167, v167
	v_fma_f32 v151, v151, s31, 0.5
	v_fma_f32 v157, v157, s31, 0.5
	v_max_f32_e32 v151, 1.0, v151
	v_fma_f32 v155, v155, s31, 0.5
	v_max_f32_e32 v157, 1.0, v157
	v_fma_f32 v159, v159, s31, 0.5
	v_fma_f32 v161, v161, s31, 0.5
	v_fma_f32 v165, v165, s31, 0.5
	v_cvt_u32_f32_e32 v151, v151
	v_max_f32_e32 v155, 1.0, v155
	v_cvt_u32_f32_e32 v157, v157
	v_max_f32_e32 v159, 1.0, v159
	v_max_f32_e32 v161, 1.0, v161
	v_fma_f32 v163, v163, s31, 0.5
	v_max_f32_e32 v165, 1.0, v165
	v_fma_f32 v167, v167, s31, 0.5
	v_cvt_u32_f32_e32 v155, v155
	v_cvt_u32_f32_e32 v159, v159
	v_cvt_u32_f32_sdwa v161, v161 dst_sel:WORD_1 dst_unused:UNUSED_PAD src0_sel:DWORD
	v_max_f32_e32 v163, 1.0, v163
	v_cvt_u32_f32_sdwa v165, v165 dst_sel:BYTE_3 dst_unused:UNUSED_PAD src0_sel:DWORD
	v_max_f32_e32 v167, 1.0, v167
	v_cvt_u32_f32_sdwa v163, v163 dst_sel:WORD_1 dst_unused:UNUSED_PAD src0_sel:DWORD
	v_cvt_u32_f32_sdwa v167, v167 dst_sel:BYTE_3 dst_unused:UNUSED_PAD src0_sel:DWORD
	v_lshl_or_b32 v151, v157, 8, v151
	v_or3_b32 v176, v151, v161, v165
	v_lshl_or_b32 v151, v159, 8, v155
	v_or3_b32 v177, v151, v163, v167
	v_mul_f32_e32 v151, v34, v148
	v_mul_f32_e32 v157, v35, v148
	v_mul_f32_e32 v155, v26, v148
	v_mul_f32_e32 v159, v27, v148
	v_mul_f32_e32 v161, v36, v148
	v_mul_f32_e32 v165, v37, v148
	v_exp_f32_e32 v151, v151
	v_exp_f32_e32 v157, v157
	v_mul_f32_e32 v163, v28, v148
	v_mul_f32_e32 v167, v29, v148
	v_exp_f32_e32 v155, v155
	v_exp_f32_e32 v159, v159
	v_exp_f32_e32 v161, v161
	v_exp_f32_e32 v165, v165
	v_exp_f32_e32 v163, v163
	v_exp_f32_e32 v167, v167
	v_add_f32_e32 v151, 1.0, v151
	v_add_f32_e32 v157, 1.0, v157
	v_rcp_f32_e32 v151, v151
	v_add_f32_e32 v155, 1.0, v155
	v_rcp_f32_e32 v157, v157
	v_add_f32_e32 v159, 1.0, v159
	v_add_f32_e32 v161, 1.0, v161
	v_add_f32_e32 v165, 1.0, v165
	v_rcp_f32_e32 v155, v155
	v_rcp_f32_e32 v159, v159
	v_rcp_f32_e32 v161, v161
	v_add_f32_e32 v163, 1.0, v163
	v_rcp_f32_e32 v165, v165
	v_add_f32_e32 v167, 1.0, v167
	v_rcp_f32_e32 v163, v163
	v_rcp_f32_e32 v167, v167
	v_fma_f32 v151, v151, s31, 0.5
	v_fma_f32 v157, v157, s31, 0.5
	v_max_f32_e32 v151, 1.0, v151
	v_fma_f32 v155, v155, s31, 0.5
	v_max_f32_e32 v157, 1.0, v157
	v_fma_f32 v159, v159, s31, 0.5
	v_fma_f32 v161, v161, s31, 0.5
	v_fma_f32 v165, v165, s31, 0.5
	v_cvt_u32_f32_e32 v151, v151
	v_max_f32_e32 v155, 1.0, v155
	v_cvt_u32_f32_e32 v157, v157
	v_max_f32_e32 v159, 1.0, v159
	v_max_f32_e32 v161, 1.0, v161
	v_fma_f32 v163, v163, s31, 0.5
	v_max_f32_e32 v165, 1.0, v165
	v_fma_f32 v167, v167, s31, 0.5
	v_cvt_u32_f32_e32 v155, v155
	v_cvt_u32_f32_e32 v159, v159
	v_cvt_u32_f32_sdwa v161, v161 dst_sel:WORD_1 dst_unused:UNUSED_PAD src0_sel:DWORD
	v_max_f32_e32 v163, 1.0, v163
	v_cvt_u32_f32_sdwa v165, v165 dst_sel:BYTE_3 dst_unused:UNUSED_PAD src0_sel:DWORD
	v_max_f32_e32 v167, 1.0, v167
	v_cvt_u32_f32_sdwa v163, v163 dst_sel:WORD_1 dst_unused:UNUSED_PAD src0_sel:DWORD
	v_cvt_u32_f32_sdwa v167, v167 dst_sel:BYTE_3 dst_unused:UNUSED_PAD src0_sel:DWORD
	v_lshl_add_u64 v[174:175], s[22:23], 0, v[174:175]
	v_lshl_add_u64 v[174:175], v[174:175], 0, v[172:173]
	v_lshl_or_b32 v151, v157, 8, v151
	global_store_dwordx2 v[174:175], v[176:177], off
	v_or3_b32 v176, v151, v161, v165
	v_lshl_or_b32 v151, v159, 8, v155
	v_or3_b32 v177, v151, v163, v167
	global_store_dwordx2 v[174:175], v[176:177], off offset:128
	v_lshlrev_b64 v[174:175], 12, v[146:147]
	v_mul_f32_e32 v147, v38, v144
	v_mul_f32_e32 v155, v39, v144
	v_mul_f32_e32 v151, v30, v144
	v_mul_f32_e32 v157, v31, v144
	v_mul_f32_e32 v159, v40, v144
	v_mul_f32_e32 v163, v41, v144
	v_exp_f32_e32 v147, v147
	v_exp_f32_e32 v155, v155
	v_mul_f32_e32 v161, v32, v144
	v_mul_f32_e32 v165, v33, v144
	v_exp_f32_e32 v151, v151
	v_exp_f32_e32 v157, v157
	v_exp_f32_e32 v159, v159
	v_exp_f32_e32 v163, v163
	v_exp_f32_e32 v161, v161
	v_exp_f32_e32 v165, v165
	v_add_f32_e32 v147, 1.0, v147
	v_add_f32_e32 v155, 1.0, v155
	v_rcp_f32_e32 v147, v147
	v_add_f32_e32 v151, 1.0, v151
	v_rcp_f32_e32 v155, v155
	v_add_f32_e32 v157, 1.0, v157
	v_add_f32_e32 v159, 1.0, v159
	v_add_f32_e32 v163, 1.0, v163
	v_rcp_f32_e32 v151, v151
	v_rcp_f32_e32 v157, v157
	v_rcp_f32_e32 v159, v159
	v_add_f32_e32 v161, 1.0, v161
	v_rcp_f32_e32 v163, v163
	v_add_f32_e32 v165, 1.0, v165
	v_rcp_f32_e32 v161, v161
	v_rcp_f32_e32 v165, v165
	v_fma_f32 v147, v147, s31, 0.5
	v_fma_f32 v155, v155, s31, 0.5
	v_max_f32_e32 v147, 1.0, v147
	v_fma_f32 v151, v151, s31, 0.5
	v_max_f32_e32 v155, 1.0, v155
	v_fma_f32 v157, v157, s31, 0.5
	v_fma_f32 v159, v159, s31, 0.5
	v_fma_f32 v163, v163, s31, 0.5
	v_cvt_u32_f32_e32 v147, v147
	v_max_f32_e32 v151, 1.0, v151
	v_cvt_u32_f32_e32 v155, v155
	v_max_f32_e32 v157, 1.0, v157
	v_max_f32_e32 v159, 1.0, v159
	v_fma_f32 v161, v161, s31, 0.5
	v_max_f32_e32 v163, 1.0, v163
	v_fma_f32 v165, v165, s31, 0.5
	v_cvt_u32_f32_e32 v151, v151
	v_cvt_u32_f32_e32 v157, v157
	v_cvt_u32_f32_sdwa v159, v159 dst_sel:WORD_1 dst_unused:UNUSED_PAD src0_sel:DWORD
	v_max_f32_e32 v161, 1.0, v161
	v_cvt_u32_f32_sdwa v163, v163 dst_sel:BYTE_3 dst_unused:UNUSED_PAD src0_sel:DWORD
	v_max_f32_e32 v165, 1.0, v165
	v_cvt_u32_f32_sdwa v161, v161 dst_sel:WORD_1 dst_unused:UNUSED_PAD src0_sel:DWORD
	v_cvt_u32_f32_sdwa v165, v165 dst_sel:BYTE_3 dst_unused:UNUSED_PAD src0_sel:DWORD
	v_lshl_or_b32 v147, v155, 8, v147
	v_or3_b32 v176, v147, v159, v163
	v_lshl_or_b32 v147, v157, 8, v151
	v_or3_b32 v177, v147, v161, v165
	v_mul_f32_e32 v147, v18, v144
	v_mul_f32_e32 v155, v19, v144
	v_mul_f32_e32 v151, v8, v144
	v_mul_f32_e32 v157, v9, v144
	v_mul_f32_e32 v159, v20, v144
	v_mul_f32_e32 v163, v21, v144
	v_exp_f32_e32 v147, v147
	v_exp_f32_e32 v155, v155
	v_mul_f32_e32 v161, v10, v144
	v_mul_f32_e32 v165, v11, v144
	v_exp_f32_e32 v151, v151
	v_exp_f32_e32 v157, v157
	v_exp_f32_e32 v159, v159
	v_exp_f32_e32 v163, v163
	v_exp_f32_e32 v161, v161
	v_exp_f32_e32 v165, v165
	v_add_f32_e32 v147, 1.0, v147
	v_add_f32_e32 v155, 1.0, v155
	v_rcp_f32_e32 v147, v147
	v_add_f32_e32 v151, 1.0, v151
	v_rcp_f32_e32 v155, v155
	v_add_f32_e32 v157, 1.0, v157
	v_add_f32_e32 v159, 1.0, v159
	v_add_f32_e32 v163, 1.0, v163
	v_rcp_f32_e32 v151, v151
	v_rcp_f32_e32 v157, v157
	v_rcp_f32_e32 v159, v159
	v_add_f32_e32 v161, 1.0, v161
	v_rcp_f32_e32 v163, v163
	v_add_f32_e32 v165, 1.0, v165
	v_rcp_f32_e32 v161, v161
	v_rcp_f32_e32 v165, v165
	v_fma_f32 v147, v147, s31, 0.5
	v_fma_f32 v155, v155, s31, 0.5
	v_max_f32_e32 v147, 1.0, v147
	v_fma_f32 v151, v151, s31, 0.5
	v_max_f32_e32 v155, 1.0, v155
	v_fma_f32 v157, v157, s31, 0.5
	v_fma_f32 v159, v159, s31, 0.5
	v_fma_f32 v163, v163, s31, 0.5
	v_cvt_u32_f32_e32 v147, v147
	v_max_f32_e32 v151, 1.0, v151
	v_cvt_u32_f32_e32 v155, v155
	v_max_f32_e32 v157, 1.0, v157
	v_max_f32_e32 v159, 1.0, v159
	v_fma_f32 v161, v161, s31, 0.5
	v_max_f32_e32 v163, 1.0, v163
	v_fma_f32 v165, v165, s31, 0.5
	v_cvt_u32_f32_e32 v151, v151
	v_cvt_u32_f32_e32 v157, v157
	v_cvt_u32_f32_sdwa v159, v159 dst_sel:WORD_1 dst_unused:UNUSED_PAD src0_sel:DWORD
	v_max_f32_e32 v161, 1.0, v161
	v_cvt_u32_f32_sdwa v163, v163 dst_sel:BYTE_3 dst_unused:UNUSED_PAD src0_sel:DWORD
	v_max_f32_e32 v165, 1.0, v165
	v_cvt_u32_f32_sdwa v161, v161 dst_sel:WORD_1 dst_unused:UNUSED_PAD src0_sel:DWORD
	v_cvt_u32_f32_sdwa v165, v165 dst_sel:BYTE_3 dst_unused:UNUSED_PAD src0_sel:DWORD
	v_lshl_add_u64 v[174:175], s[22:23], 0, v[174:175]
	v_lshl_add_u64 v[174:175], v[174:175], 0, v[172:173]
	v_lshl_or_b32 v147, v155, 8, v147
	global_store_dwordx2 v[174:175], v[176:177], off
	v_or3_b32 v176, v147, v159, v163
	v_lshl_or_b32 v147, v157, 8, v151
	v_or3_b32 v177, v147, v161, v165
	global_store_dwordx2 v[174:175], v[176:177], off offset:128
	v_lshlrev_b64 v[174:175], 12, v[142:143]
	v_mul_f32_e32 v143, v22, v140
	v_mul_f32_e32 v151, v23, v140
	v_mul_f32_e32 v147, v12, v140
	v_mul_f32_e32 v155, v13, v140
	v_mul_f32_e32 v157, v24, v140
	v_mul_f32_e32 v161, v25, v140
	v_exp_f32_e32 v143, v143
	v_exp_f32_e32 v151, v151
	v_mul_f32_e32 v159, v14, v140
	v_mul_f32_e32 v163, v15, v140
	v_exp_f32_e32 v147, v147
	v_exp_f32_e32 v155, v155
	v_exp_f32_e32 v157, v157
	v_exp_f32_e32 v161, v161
	v_exp_f32_e32 v159, v159
	v_exp_f32_e32 v163, v163
	v_add_f32_e32 v143, 1.0, v143
	v_add_f32_e32 v151, 1.0, v151
	v_rcp_f32_e32 v143, v143
	v_add_f32_e32 v147, 1.0, v147
	v_rcp_f32_e32 v151, v151
	v_add_f32_e32 v155, 1.0, v155
	v_add_f32_e32 v157, 1.0, v157
	v_add_f32_e32 v161, 1.0, v161
	v_rcp_f32_e32 v147, v147
	v_rcp_f32_e32 v155, v155
	v_rcp_f32_e32 v157, v157
	v_add_f32_e32 v159, 1.0, v159
	v_rcp_f32_e32 v161, v161
	v_add_f32_e32 v163, 1.0, v163
	v_rcp_f32_e32 v159, v159
	v_rcp_f32_e32 v163, v163
	v_fma_f32 v143, v143, s31, 0.5
	v_fma_f32 v151, v151, s31, 0.5
	v_max_f32_e32 v143, 1.0, v143
	v_fma_f32 v147, v147, s31, 0.5
	v_max_f32_e32 v151, 1.0, v151
	v_fma_f32 v155, v155, s31, 0.5
	v_fma_f32 v157, v157, s31, 0.5
	v_fma_f32 v161, v161, s31, 0.5
	v_cvt_u32_f32_e32 v143, v143
	v_max_f32_e32 v147, 1.0, v147
	v_cvt_u32_f32_e32 v151, v151
	v_max_f32_e32 v155, 1.0, v155
	v_max_f32_e32 v157, 1.0, v157
	v_fma_f32 v159, v159, s31, 0.5
	v_max_f32_e32 v161, 1.0, v161
	v_fma_f32 v163, v163, s31, 0.5
	v_cvt_u32_f32_e32 v147, v147
	v_cvt_u32_f32_e32 v155, v155
	v_cvt_u32_f32_sdwa v157, v157 dst_sel:WORD_1 dst_unused:UNUSED_PAD src0_sel:DWORD
	v_max_f32_e32 v159, 1.0, v159
	v_cvt_u32_f32_sdwa v161, v161 dst_sel:BYTE_3 dst_unused:UNUSED_PAD src0_sel:DWORD
	v_max_f32_e32 v163, 1.0, v163
	v_cvt_u32_f32_sdwa v159, v159 dst_sel:WORD_1 dst_unused:UNUSED_PAD src0_sel:DWORD
	v_cvt_u32_f32_sdwa v163, v163 dst_sel:BYTE_3 dst_unused:UNUSED_PAD src0_sel:DWORD
	v_lshl_or_b32 v143, v151, 8, v143
	v_or3_b32 v176, v143, v157, v161
	v_lshl_or_b32 v143, v155, 8, v147
	v_or3_b32 v177, v143, v159, v163
	v_mul_f32_e32 v143, v4, v140
	v_mul_f32_e32 v151, v5, v140
	v_mul_f32_e32 v147, v0, v140
	v_mul_f32_e32 v155, v1, v140
	v_mul_f32_e32 v157, v6, v140
	v_mul_f32_e32 v161, v7, v140
	v_exp_f32_e32 v143, v143
	v_exp_f32_e32 v151, v151
	v_mul_f32_e32 v159, v2, v140
	v_mul_f32_e32 v163, v3, v140
	v_exp_f32_e32 v147, v147
	v_exp_f32_e32 v155, v155
	v_exp_f32_e32 v157, v157
	v_exp_f32_e32 v161, v161
	v_exp_f32_e32 v159, v159
	v_exp_f32_e32 v163, v163
	v_add_f32_e32 v143, 1.0, v143
	v_add_f32_e32 v151, 1.0, v151
	v_rcp_f32_e32 v143, v143
	v_add_f32_e32 v147, 1.0, v147
	v_rcp_f32_e32 v151, v151
	v_add_f32_e32 v155, 1.0, v155
	v_add_f32_e32 v157, 1.0, v157
	v_add_f32_e32 v161, 1.0, v161
	v_rcp_f32_e32 v147, v147
	v_rcp_f32_e32 v155, v155
	v_rcp_f32_e32 v157, v157
	v_add_f32_e32 v159, 1.0, v159
	v_rcp_f32_e32 v161, v161
	v_add_f32_e32 v163, 1.0, v163
	v_rcp_f32_e32 v159, v159
	v_rcp_f32_e32 v163, v163
	v_fma_f32 v143, v143, s31, 0.5
	v_fma_f32 v151, v151, s31, 0.5
	v_max_f32_e32 v143, 1.0, v143
	v_fma_f32 v147, v147, s31, 0.5
	v_max_f32_e32 v151, 1.0, v151
	v_fma_f32 v155, v155, s31, 0.5
	v_fma_f32 v157, v157, s31, 0.5
	v_fma_f32 v161, v161, s31, 0.5
	v_cvt_u32_f32_e32 v143, v143
	v_max_f32_e32 v147, 1.0, v147
	v_cvt_u32_f32_e32 v151, v151
	v_max_f32_e32 v155, 1.0, v155
	v_max_f32_e32 v157, 1.0, v157
	v_fma_f32 v159, v159, s31, 0.5
	v_max_f32_e32 v161, 1.0, v161
	v_fma_f32 v163, v163, s31, 0.5
	v_cvt_u32_f32_e32 v147, v147
	v_cvt_u32_f32_e32 v155, v155
	v_cvt_u32_f32_sdwa v157, v157 dst_sel:WORD_1 dst_unused:UNUSED_PAD src0_sel:DWORD
	v_max_f32_e32 v159, 1.0, v159
	v_cvt_u32_f32_sdwa v161, v161 dst_sel:BYTE_3 dst_unused:UNUSED_PAD src0_sel:DWORD
	v_max_f32_e32 v163, 1.0, v163
	v_cvt_u32_f32_sdwa v159, v159 dst_sel:WORD_1 dst_unused:UNUSED_PAD src0_sel:DWORD
	v_cvt_u32_f32_sdwa v163, v163 dst_sel:BYTE_3 dst_unused:UNUSED_PAD src0_sel:DWORD
	v_lshl_add_u64 v[174:175], s[22:23], 0, v[174:175]
	v_lshl_add_u64 v[174:175], v[174:175], 0, v[172:173]
	v_lshl_or_b32 v143, v151, 8, v143
	global_store_dwordx2 v[174:175], v[176:177], off
	v_or3_b32 v176, v143, v157, v161
	v_lshl_or_b32 v143, v155, 8, v147
	v_or3_b32 v177, v143, v159, v163
	s_mov_b64 s[22:23], 0
	global_store_dwordx2 v[174:175], v[176:177], off offset:128
	s_branch .LBB0_674

.LBB0_961:
	s_add_u32 s12, s12, 0x40080
	s_addc_u32 s13, s13, 0
	s_add_u32 s5, s16, 0x100
	v_mov_b32_e32 v0, 0
	s_addc_u32 s7, s17, 0
	s_mov_b32 s25, -2
	v_mov_b32_e32 v1, v0
	v_mov_b32_e32 v2, v0
	v_mov_b32_e32 v3, v0
	v_mov_b32_e32 v4, v0
	v_mov_b32_e32 v5, v0
	v_mov_b32_e32 v6, v0
	v_mov_b32_e32 v7, v0
	v_mov_b32_e32 v18, v0
	v_mov_b32_e32 v19, v0
	v_mov_b32_e32 v20, v0
	v_mov_b32_e32 v21, v0
	v_mov_b32_e32 v22, v0
	v_mov_b32_e32 v23, v0
	v_mov_b32_e32 v24, v0
	v_mov_b32_e32 v25, v0
	v_mov_b32_e32 v34, v0
	v_mov_b32_e32 v35, v0
	v_mov_b32_e32 v36, v0
	v_mov_b32_e32 v37, v0
	v_mov_b32_e32 v38, v0
	v_mov_b32_e32 v39, v0
	v_mov_b32_e32 v40, v0
	v_mov_b32_e32 v41, v0
	v_mov_b32_e32 v50, v0
	v_mov_b32_e32 v51, v0
	v_mov_b32_e32 v52, v0
	v_mov_b32_e32 v53, v0
	v_mov_b32_e32 v54, v0
	v_mov_b32_e32 v55, v0
	v_mov_b32_e32 v56, v0
	v_mov_b32_e32 v57, v0
	v_mov_b32_e32 v8, v0
	v_mov_b32_e32 v9, v0
	v_mov_b32_e32 v10, v0
	v_mov_b32_e32 v11, v0
	v_mov_b32_e32 v12, v0
	v_mov_b32_e32 v13, v0
	v_mov_b32_e32 v14, v0
	v_mov_b32_e32 v15, v0
	v_mov_b32_e32 v26, v0
	v_mov_b32_e32 v27, v0
	v_mov_b32_e32 v28, v0
	v_mov_b32_e32 v29, v0
	v_mov_b32_e32 v30, v0
	v_mov_b32_e32 v31, v0
	v_mov_b32_e32 v32, v0
	v_mov_b32_e32 v33, v0
	v_mov_b32_e32 v42, v0
	v_mov_b32_e32 v43, v0
	v_mov_b32_e32 v44, v0
	v_mov_b32_e32 v45, v0
	v_mov_b32_e32 v46, v0
	v_mov_b32_e32 v47, v0
	v_mov_b32_e32 v48, v0
	v_mov_b32_e32 v49, v0
	v_mov_b32_e32 v58, v0
	v_mov_b32_e32 v59, v0
	v_mov_b32_e32 v60, v0
	v_mov_b32_e32 v61, v0
	v_mov_b32_e32 v62, v0
	v_mov_b32_e32 v63, v0
	v_mov_b32_e32 v64, v0
	v_mov_b32_e32 v65, v0
	v_mov_b32_e32 v66, v0
	v_mov_b32_e32 v67, v0
	v_mov_b32_e32 v68, v0
	v_mov_b32_e32 v69, v0
	v_mov_b32_e32 v70, v0
	v_mov_b32_e32 v71, v0
	v_mov_b32_e32 v72, v0
	v_mov_b32_e32 v73, v0
	v_mov_b32_e32 v82, v0
	v_mov_b32_e32 v83, v0
	v_mov_b32_e32 v84, v0
	v_mov_b32_e32 v85, v0
	v_mov_b32_e32 v86, v0
	v_mov_b32_e32 v87, v0
	v_mov_b32_e32 v88, v0
	v_mov_b32_e32 v89, v0
	v_mov_b32_e32 v98, v0
	v_mov_b32_e32 v99, v0
	v_mov_b32_e32 v100, v0
	v_mov_b32_e32 v101, v0
	v_mov_b32_e32 v102, v0
	v_mov_b32_e32 v103, v0
	v_mov_b32_e32 v104, v0
	v_mov_b32_e32 v105, v0
	v_mov_b32_e32 v114, v0
	v_mov_b32_e32 v115, v0
	v_mov_b32_e32 v116, v0
	v_mov_b32_e32 v117, v0
	v_mov_b32_e32 v118, v0
	v_mov_b32_e32 v119, v0
	v_mov_b32_e32 v120, v0
	v_mov_b32_e32 v121, v0
	v_mov_b32_e32 v74, v0
	v_mov_b32_e32 v75, v0
	v_mov_b32_e32 v76, v0
	v_mov_b32_e32 v77, v0
	v_mov_b32_e32 v78, v0
	v_mov_b32_e32 v79, v0
	v_mov_b32_e32 v80, v0
	v_mov_b32_e32 v81, v0
	v_mov_b32_e32 v90, v0
	v_mov_b32_e32 v91, v0
	v_mov_b32_e32 v92, v0
	v_mov_b32_e32 v93, v0
	v_mov_b32_e32 v94, v0
	v_mov_b32_e32 v95, v0
	v_mov_b32_e32 v96, v0
	v_mov_b32_e32 v97, v0
	v_mov_b32_e32 v106, v0
	v_mov_b32_e32 v107, v0
	v_mov_b32_e32 v108, v0
	v_mov_b32_e32 v109, v0
	v_mov_b32_e32 v110, v0
	v_mov_b32_e32 v111, v0
	v_mov_b32_e32 v112, v0
	v_mov_b32_e32 v113, v0
	v_mov_b32_e32 v122, v0
	v_mov_b32_e32 v123, v0
	v_mov_b32_e32 v124, v0
	v_mov_b32_e32 v125, v0
	v_mov_b32_e32 v126, v0
	v_mov_b32_e32 v127, v0
	v_mov_b32_e32 v128, v0
	v_mov_b32_e32 v129, v0
	v_readfirstlane_b32 s98, v232
	s_cmp_ge_u32 s98, 0x100
	s_cbranch_scc0 .Lsp_sk1
	s_setprio 1
.Lsp_sk1:
.LBB0_962:
	s_add_u32 s16, s12, 0xfffc0080
	s_addc_u32 s17, s13, -1
	s_add_i32 s33, 0, 0x10000
	v_add_u32_e32 v148, s33, v151
	ds_read_b128 v[140:143], v148
	ds_read_b128 v[144:147], v148 offset:1024
	ds_read_b128 v[154:157], v148 offset:2048
	ds_read_b128 v[158:161], v148 offset:3072
	s_cmp_eq_u32 s25, 12
	s_cselect_b32 s23, s9, s17
	s_cselect_b32 s22, s8, s16
	s_cselect_b32 s17, s11, s7
	s_cselect_b32 s16, s10, s5
	v_lshl_add_u64 v[148:149], s[12:13], 0, v[136:137]
	s_add_i32 m0, s38, 0xc000
	ds_read_b128 v[162:165], v153
	ds_read_b128 v[166:169], v153 offset:1024
	ds_read_b128 v[170:173], v153 offset:2048
	ds_read_b128 v[174:177], v153 offset:3072
	ds_read_b128 v[188:191], v153 offset:4096
	ds_read_b128 v[192:195], v153 offset:5120
	ds_read_b128 v[196:199], v153 offset:6144
	ds_read_b128 v[200:203], v153 offset:7168
	global_load_lds_dwordx4 v[148:149], off
	v_lshl_add_u64 v[148:149], s[12:13], 0, v[138:139]
	s_add_i32 m0, s38, 0xe000
	s_nop 0
	global_load_lds_dwordx4 v[148:149], off
	s_waitcnt lgkmcnt(8)
	s_barrier
	s_waitcnt lgkmcnt(0)
	s_waitcnt lgkmcnt(0)
	v_mfma_f32_16x16x32_bf16 v[126:129], v[140:143], v[162:165], v[126:129]
	v_mfma_f32_16x16x32_bf16 v[122:125], v[154:157], v[162:165], v[122:125]
	v_mfma_f32_16x16x32_bf16 v[110:113], v[140:143], v[170:173], v[110:113]
	v_mfma_f32_16x16x32_bf16 v[106:109], v[154:157], v[170:173], v[106:109]
	v_mfma_f32_16x16x32_bf16 v[94:97], v[140:143], v[188:191], v[94:97]
	v_mfma_f32_16x16x32_bf16 v[90:93], v[154:157], v[188:191], v[90:93]
	v_mfma_f32_16x16x32_bf16 v[78:81], v[140:143], v[196:199], v[78:81]
	v_mfma_f32_16x16x32_bf16 v[74:77], v[154:157], v[196:199], v[74:77]
	v_mfma_f32_16x16x32_bf16 v[126:129], v[144:147], v[166:169], v[126:129]
	v_mfma_f32_16x16x32_bf16 v[122:125], v[158:161], v[166:169], v[122:125]
	v_mfma_f32_16x16x32_bf16 v[110:113], v[144:147], v[174:177], v[110:113]
	v_mfma_f32_16x16x32_bf16 v[106:109], v[158:161], v[174:177], v[106:109]
	v_mfma_f32_16x16x32_bf16 v[94:97], v[144:147], v[192:195], v[94:97]
	v_mfma_f32_16x16x32_bf16 v[90:93], v[158:161], v[192:195], v[90:93]
	v_mfma_f32_16x16x32_bf16 v[78:81], v[144:147], v[200:203], v[78:81]
	v_mfma_f32_16x16x32_bf16 v[74:77], v[158:161], v[200:203], v[74:77]
	s_barrier
	s_add_i32 s45, 0, 0x14000
	v_add_u32_e32 v148, s45, v151
	s_add_i32 s33, s33, s35
	ds_read_b128 v[204:207], v148
	ds_read_b128 v[208:211], v148 offset:1024
	ds_read_b128 v[212:215], v148 offset:2048
	ds_read_b128 v[216:219], v148 offset:3072
	v_lshl_add_u64 v[148:149], s[16:17], 0, v[16:17]
	s_mov_b32 m0, s33
	v_lshl_add_u64 v[178:179], s[16:17], 0, v[130:131]
	global_load_lds_dwordx4 v[148:149], off
	s_add_i32 m0, s33, 0x2000
	s_nop 0
	global_load_lds_dwordx4 v[178:179], off
	s_barrier
	s_waitcnt lgkmcnt(0)
	s_waitcnt lgkmcnt(0)
	v_mfma_f32_16x16x32_bf16 v[118:121], v[204:207], v[162:165], v[118:121]
	v_mfma_f32_16x16x32_bf16 v[114:117], v[212:215], v[162:165], v[114:117]
	v_mfma_f32_16x16x32_bf16 v[102:105], v[204:207], v[170:173], v[102:105]
	v_mfma_f32_16x16x32_bf16 v[98:101], v[212:215], v[170:173], v[98:101]
	v_mfma_f32_16x16x32_bf16 v[86:89], v[204:207], v[188:191], v[86:89]
	v_mfma_f32_16x16x32_bf16 v[82:85], v[212:215], v[188:191], v[82:85]
	v_mfma_f32_16x16x32_bf16 v[70:73], v[204:207], v[196:199], v[70:73]
	v_mfma_f32_16x16x32_bf16 v[66:69], v[212:215], v[196:199], v[66:69]
	v_mfma_f32_16x16x32_bf16 v[118:121], v[208:211], v[166:169], v[118:121]
	v_mfma_f32_16x16x32_bf16 v[114:117], v[216:219], v[166:169], v[114:117]
	v_mfma_f32_16x16x32_bf16 v[102:105], v[208:211], v[174:177], v[102:105]
	v_mfma_f32_16x16x32_bf16 v[98:101], v[216:219], v[174:177], v[98:101]
	v_mfma_f32_16x16x32_bf16 v[86:89], v[208:211], v[192:195], v[86:89]
	v_mfma_f32_16x16x32_bf16 v[82:85], v[216:219], v[192:195], v[82:85]
	v_mfma_f32_16x16x32_bf16 v[70:73], v[208:211], v[200:203], v[70:73]
	v_mfma_f32_16x16x32_bf16 v[66:69], v[216:219], v[200:203], v[66:69]
	s_mov_b32 m0, s38
	v_lshl_add_u64 v[180:181], s[22:23], 0, v[134:135]
	s_barrier
	ds_read_b128 v[162:165], v153 offset:16384
	ds_read_b128 v[166:169], v153 offset:17408
	ds_read_b128 v[170:173], v153 offset:18432
	ds_read_b128 v[174:177], v153 offset:19456
	ds_read_b128 v[188:191], v153 offset:20480
	ds_read_b128 v[192:195], v153 offset:21504
	ds_read_b128 v[196:199], v153 offset:22528
	ds_read_b128 v[200:203], v153 offset:23552
	global_load_lds_dwordx4 v[180:181], off
	v_lshl_add_u64 v[220:221], s[22:23], 0, v[132:133]
	s_mov_b32 m0, s39
	s_nop 0
	global_load_lds_dwordx4 v[220:221], off
	s_barrier
	s_waitcnt lgkmcnt(0)
	s_waitcnt lgkmcnt(0)
	v_mfma_f32_16x16x32_bf16 v[62:65], v[140:143], v[162:165], v[62:65]
	v_mfma_f32_16x16x32_bf16 v[58:61], v[154:157], v[162:165], v[58:61]
	v_mfma_f32_16x16x32_bf16 v[46:49], v[140:143], v[170:173], v[46:49]
	v_mfma_f32_16x16x32_bf16 v[42:45], v[154:157], v[170:173], v[42:45]
	v_mfma_f32_16x16x32_bf16 v[30:33], v[140:143], v[188:191], v[30:33]
	v_mfma_f32_16x16x32_bf16 v[26:29], v[154:157], v[188:191], v[26:29]
	v_mfma_f32_16x16x32_bf16 v[12:15], v[140:143], v[196:199], v[12:15]
	v_mfma_f32_16x16x32_bf16 v[8:11], v[154:157], v[196:199], v[8:11]
	v_mfma_f32_16x16x32_bf16 v[62:65], v[144:147], v[166:169], v[62:65]
	v_mfma_f32_16x16x32_bf16 v[58:61], v[158:161], v[166:169], v[58:61]
	v_mfma_f32_16x16x32_bf16 v[46:49], v[144:147], v[174:177], v[46:49]
	v_mfma_f32_16x16x32_bf16 v[42:45], v[158:161], v[174:177], v[42:45]
	v_mfma_f32_16x16x32_bf16 v[30:33], v[144:147], v[192:195], v[30:33]
	v_mfma_f32_16x16x32_bf16 v[26:29], v[158:161], v[192:195], v[26:29]
	v_mfma_f32_16x16x32_bf16 v[12:15], v[144:147], v[200:203], v[12:15]
	v_mfma_f32_16x16x32_bf16 v[8:11], v[158:161], v[200:203], v[8:11]
	s_barrier
	s_add_u32 s46, s16, 0x40000
	s_addc_u32 s47, s17, 0
	s_add_i32 s33, s45, s35
	v_lshl_add_u64 v[140:141], s[46:47], 0, v[16:17]
	s_mov_b32 m0, s33
	s_nop 0
	global_load_lds_dwordx4 v[140:141], off
	v_lshl_add_u64 v[140:141], s[46:47], 0, v[130:131]
	s_add_i32 m0, s33, 0x2000
	s_nop 0
	global_load_lds_dwordx4 v[140:141], off
	s_waitcnt vmcnt(6)
	s_barrier
	v_mfma_f32_16x16x32_bf16 v[54:57], v[204:207], v[162:165], v[54:57]
	v_mfma_f32_16x16x32_bf16 v[50:53], v[212:215], v[162:165], v[50:53]
	v_mfma_f32_16x16x32_bf16 v[38:41], v[204:207], v[170:173], v[38:41]
	v_mfma_f32_16x16x32_bf16 v[34:37], v[212:215], v[170:173], v[34:37]
	v_mfma_f32_16x16x32_bf16 v[22:25], v[204:207], v[188:191], v[22:25]
	v_mfma_f32_16x16x32_bf16 v[18:21], v[212:215], v[188:191], v[18:21]
	v_mfma_f32_16x16x32_bf16 v[4:7], v[204:207], v[196:199], v[4:7]
	v_mfma_f32_16x16x32_bf16 v[0:3], v[212:215], v[196:199], v[0:3]
	v_mfma_f32_16x16x32_bf16 v[54:57], v[208:211], v[166:169], v[54:57]
	v_mfma_f32_16x16x32_bf16 v[50:53], v[216:219], v[166:169], v[50:53]
	v_mfma_f32_16x16x32_bf16 v[38:41], v[208:211], v[174:177], v[38:41]
	v_mfma_f32_16x16x32_bf16 v[34:37], v[216:219], v[174:177], v[34:37]
	v_mfma_f32_16x16x32_bf16 v[22:25], v[208:211], v[192:195], v[22:25]
	v_mfma_f32_16x16x32_bf16 v[18:21], v[216:219], v[192:195], v[18:21]
	v_mfma_f32_16x16x32_bf16 v[4:7], v[208:211], v[200:203], v[4:7]
	v_mfma_f32_16x16x32_bf16 v[0:3], v[216:219], v[200:203], v[0:3]
	s_add_i32 s33, 0, 0x18000
	v_add_u32_e32 v158, s33, v151
	s_barrier
	ds_read_b128 v[140:143], v158
	ds_read_b128 v[144:147], v158 offset:1024
	ds_read_b128 v[154:157], v158 offset:2048
	ds_read_b128 v[158:161], v158 offset:3072
	s_add_u32 s22, s22, 0x40000
	s_addc_u32 s23, s23, 0
	s_mov_b32 m0, s40
	v_lshl_add_u64 v[204:205], s[22:23], 0, v[134:135]
	ds_read_b128 v[162:165], v153 offset:32768
	ds_read_b128 v[166:169], v153 offset:33792
	ds_read_b128 v[170:173], v153 offset:34816
	ds_read_b128 v[174:177], v153 offset:35840
	ds_read_b128 v[188:191], v153 offset:36864
	ds_read_b128 v[192:195], v153 offset:37888
	ds_read_b128 v[196:199], v153 offset:38912
	ds_read_b128 v[200:203], v153 offset:39936
	global_load_lds_dwordx4 v[204:205], off
	v_lshl_add_u64 v[204:205], s[22:23], 0, v[132:133]
	s_mov_b32 m0, s41
	s_nop 0
	global_load_lds_dwordx4 v[204:205], off
	s_waitcnt lgkmcnt(8)
	s_barrier
	s_waitcnt lgkmcnt(0)
	s_waitcnt lgkmcnt(0)
	v_mfma_f32_16x16x32_bf16 v[126:129], v[140:143], v[162:165], v[126:129]
	v_mfma_f32_16x16x32_bf16 v[122:125], v[154:157], v[162:165], v[122:125]
	v_mfma_f32_16x16x32_bf16 v[110:113], v[140:143], v[170:173], v[110:113]
	v_mfma_f32_16x16x32_bf16 v[106:109], v[154:157], v[170:173], v[106:109]
	v_mfma_f32_16x16x32_bf16 v[94:97], v[140:143], v[188:191], v[94:97]
	v_mfma_f32_16x16x32_bf16 v[90:93], v[154:157], v[188:191], v[90:93]
	v_mfma_f32_16x16x32_bf16 v[78:81], v[140:143], v[196:199], v[78:81]
	v_mfma_f32_16x16x32_bf16 v[74:77], v[154:157], v[196:199], v[74:77]
	v_mfma_f32_16x16x32_bf16 v[126:129], v[144:147], v[166:169], v[126:129]
	v_mfma_f32_16x16x32_bf16 v[122:125], v[158:161], v[166:169], v[122:125]
	v_mfma_f32_16x16x32_bf16 v[110:113], v[144:147], v[174:177], v[110:113]
	v_mfma_f32_16x16x32_bf16 v[106:109], v[158:161], v[174:177], v[106:109]
	v_mfma_f32_16x16x32_bf16 v[94:97], v[144:147], v[192:195], v[94:97]
	v_mfma_f32_16x16x32_bf16 v[90:93], v[158:161], v[192:195], v[90:93]
	v_mfma_f32_16x16x32_bf16 v[78:81], v[144:147], v[200:203], v[78:81]
	v_mfma_f32_16x16x32_bf16 v[74:77], v[158:161], v[200:203], v[74:77]
	s_barrier
	s_add_i32 s22, 0, 0x1c000
	s_add_i32 s23, s33, s35
	v_add_u32_e32 v183, s22, v151
	v_lshl_add_u64 v[148:149], v[148:149], 0, s[14:15]
	s_mov_b32 m0, s23
	ds_read_b128 v[204:207], v183
	ds_read_b128 v[208:211], v183 offset:1024
	ds_read_b128 v[212:215], v183 offset:2048
	ds_read_b128 v[216:219], v183 offset:3072
	global_load_lds_dwordx4 v[148:149], off
	v_lshl_add_u64 v[148:149], v[178:179], 0, s[14:15]
	s_add_i32 m0, s23, 0x2000
	s_nop 0
	global_load_lds_dwordx4 v[148:149], off
	s_barrier
	s_waitcnt lgkmcnt(0)
	s_waitcnt lgkmcnt(0)
	v_mfma_f32_16x16x32_bf16 v[118:121], v[204:207], v[162:165], v[118:121]
	v_mfma_f32_16x16x32_bf16 v[114:117], v[212:215], v[162:165], v[114:117]
	v_mfma_f32_16x16x32_bf16 v[102:105], v[204:207], v[170:173], v[102:105]
	v_mfma_f32_16x16x32_bf16 v[98:101], v[212:215], v[170:173], v[98:101]
	v_mfma_f32_16x16x32_bf16 v[86:89], v[204:207], v[188:191], v[86:89]
	v_mfma_f32_16x16x32_bf16 v[82:85], v[212:215], v[188:191], v[82:85]
	v_mfma_f32_16x16x32_bf16 v[70:73], v[204:207], v[196:199], v[70:73]
	v_mfma_f32_16x16x32_bf16 v[66:69], v[212:215], v[196:199], v[66:69]
	v_mfma_f32_16x16x32_bf16 v[118:121], v[208:211], v[166:169], v[118:121]
	v_mfma_f32_16x16x32_bf16 v[114:117], v[216:219], v[166:169], v[114:117]
	v_mfma_f32_16x16x32_bf16 v[102:105], v[208:211], v[174:177], v[102:105]
	v_mfma_f32_16x16x32_bf16 v[98:101], v[216:219], v[174:177], v[98:101]
	v_mfma_f32_16x16x32_bf16 v[86:89], v[208:211], v[192:195], v[86:89]
	v_mfma_f32_16x16x32_bf16 v[82:85], v[216:219], v[192:195], v[82:85]
	v_mfma_f32_16x16x32_bf16 v[70:73], v[208:211], v[200:203], v[70:73]
	v_mfma_f32_16x16x32_bf16 v[66:69], v[216:219], v[200:203], v[66:69]
	s_mov_b32 m0, s42
	v_lshl_add_u64 v[148:149], v[180:181], 0, s[14:15]
	s_barrier
	ds_read_b128 v[162:165], v153 offset:49152
	ds_read_b128 v[166:169], v153 offset:50176
	ds_read_b128 v[170:173], v153 offset:51200
	ds_read_b128 v[174:177], v153 offset:52224
	ds_read_b128 v[188:191], v153 offset:53248
	ds_read_b128 v[192:195], v153 offset:54272
	ds_read_b128 v[196:199], v153 offset:55296
	ds_read_b128 v[200:203], v153 offset:56320
	global_load_lds_dwordx4 v[148:149], off
	v_lshl_add_u64 v[148:149], v[220:221], 0, s[14:15]
	s_mov_b32 m0, s43
	s_nop 0
	global_load_lds_dwordx4 v[148:149], off
	s_barrier
	s_waitcnt lgkmcnt(0)
	s_waitcnt lgkmcnt(0)
	v_mfma_f32_16x16x32_bf16 v[62:65], v[140:143], v[162:165], v[62:65]
	v_mfma_f32_16x16x32_bf16 v[58:61], v[154:157], v[162:165], v[58:61]
	v_mfma_f32_16x16x32_bf16 v[46:49], v[140:143], v[170:173], v[46:49]
	v_mfma_f32_16x16x32_bf16 v[42:45], v[154:157], v[170:173], v[42:45]
	v_mfma_f32_16x16x32_bf16 v[30:33], v[140:143], v[188:191], v[30:33]
	v_mfma_f32_16x16x32_bf16 v[26:29], v[154:157], v[188:191], v[26:29]
	v_mfma_f32_16x16x32_bf16 v[12:15], v[140:143], v[196:199], v[12:15]
	v_mfma_f32_16x16x32_bf16 v[8:11], v[154:157], v[196:199], v[8:11]
	v_mfma_f32_16x16x32_bf16 v[62:65], v[144:147], v[166:169], v[62:65]
	v_mfma_f32_16x16x32_bf16 v[58:61], v[158:161], v[166:169], v[58:61]
	v_mfma_f32_16x16x32_bf16 v[46:49], v[144:147], v[174:177], v[46:49]
	v_mfma_f32_16x16x32_bf16 v[42:45], v[158:161], v[174:177], v[42:45]
	v_mfma_f32_16x16x32_bf16 v[30:33], v[144:147], v[192:195], v[30:33]
	v_mfma_f32_16x16x32_bf16 v[26:29], v[158:161], v[192:195], v[26:29]
	v_mfma_f32_16x16x32_bf16 v[12:15], v[144:147], v[200:203], v[12:15]
	v_mfma_f32_16x16x32_bf16 v[8:11], v[158:161], v[200:203], v[8:11]
	s_barrier
	s_add_u32 s16, s16, 0x40080
	s_addc_u32 s17, s17, 0
	s_add_i32 s22, s22, s35
	v_lshl_add_u64 v[140:141], s[16:17], 0, v[16:17]
	s_mov_b32 m0, s22
	s_nop 0
	global_load_lds_dwordx4 v[140:141], off
	v_lshl_add_u64 v[140:141], s[16:17], 0, v[130:131]
	s_add_i32 m0, s22, 0x2000
	s_nop 0
	global_load_lds_dwordx4 v[140:141], off
	s_waitcnt vmcnt(6)
	s_barrier
	v_mfma_f32_16x16x32_bf16 v[54:57], v[204:207], v[162:165], v[54:57]
	v_mfma_f32_16x16x32_bf16 v[50:53], v[212:215], v[162:165], v[50:53]
	v_mfma_f32_16x16x32_bf16 v[38:41], v[204:207], v[170:173], v[38:41]
	v_mfma_f32_16x16x32_bf16 v[34:37], v[212:215], v[170:173], v[34:37]
	v_mfma_f32_16x16x32_bf16 v[22:25], v[204:207], v[188:191], v[22:25]
	v_mfma_f32_16x16x32_bf16 v[18:21], v[212:215], v[188:191], v[18:21]
	v_mfma_f32_16x16x32_bf16 v[4:7], v[204:207], v[196:199], v[4:7]
	v_mfma_f32_16x16x32_bf16 v[0:3], v[212:215], v[196:199], v[0:3]
	v_mfma_f32_16x16x32_bf16 v[54:57], v[208:211], v[166:169], v[54:57]
	v_mfma_f32_16x16x32_bf16 v[50:53], v[216:219], v[166:169], v[50:53]
	v_mfma_f32_16x16x32_bf16 v[38:41], v[208:211], v[174:177], v[38:41]
	v_mfma_f32_16x16x32_bf16 v[34:37], v[216:219], v[174:177], v[34:37]
	v_mfma_f32_16x16x32_bf16 v[22:25], v[208:211], v[192:195], v[22:25]
	v_mfma_f32_16x16x32_bf16 v[18:21], v[216:219], v[192:195], v[18:21]
	v_mfma_f32_16x16x32_bf16 v[4:7], v[208:211], v[200:203], v[4:7]
	v_mfma_f32_16x16x32_bf16 v[0:3], v[216:219], v[200:203], v[0:3]
	s_add_i32 s25, s25, 2
	s_add_u32 s12, s12, 0x100
	s_addc_u32 s13, s13, 0
	s_add_u32 s5, s5, 0x100
	s_addc_u32 s7, s7, 0
	s_cmp_gt_u32 s25, 13
	s_barrier
	s_cbranch_scc0 .LBB0_962
	s_setprio 0
	v_lshl_add_u32 v140, s21, 8, v150
	v_readlane_b32 s12, v252, 38
	v_ashrrev_i32_e32 v141, 31, v140
	v_readlane_b32 s13, v252, 39
	v_or_b32_e32 v148, 16, v140
	v_ashrrev_i32_e32 v149, 31, v148
	v_lshl_add_u64 v[144:145], v[140:141], 2, s[12:13]
	global_load_dword v161, v[144:145], off
	v_lshl_add_u64 v[142:143], v[148:149], 2, s[12:13]
	global_load_dword v160, v[142:143], off
	v_or_b32_e32 v146, 32, v140
	v_ashrrev_i32_e32 v147, 31, v146
	v_lshl_add_u64 v[142:143], v[146:147], 2, s[12:13]
	global_load_dword v159, v[142:143], off
	v_or_b32_e32 v142, 48, v140
	v_ashrrev_i32_e32 v143, 31, v142
	v_lshl_add_u64 v[154:155], v[142:143], 2, s[12:13]
	global_load_dword v158, v[154:155], off
	global_load_dword v157, v[144:145], off offset:512
	global_load_dword v156, v[144:145], off offset:576
	s_nop 0
	global_load_dword v155, v[144:145], off offset:640
	global_load_dword v154, v[144:145], off offset:704
	v_readlane_b32 s12, v252, 34
	v_lshl_or_b32 v144, s20, 8, v152
	v_lshlrev_b64 v[140:141], 12, v[140:141]
	v_readlane_b32 s13, v252, 35
	v_ashrrev_i32_e32 v145, 31, v144
	s_mov_b32 s5, 0x80000
	v_lshl_add_u64 v[140:141], s[12:13], 0, v[140:141]
	v_lshl_add_u64 v[140:141], v[140:141], 0, v[144:145]
	s_mov_b32 s21, s6
	s_mov_b32 s20, s4
	s_mov_b64 s[16:17], s[10:11]
	s_waitcnt vmcnt(0)
	v_mul_f32_e32 v161, 0xbfb8aa3b, v161
	v_mul_f32_e32 v160, 0xbfb8aa3b, v160
	v_mul_f32_e32 v159, 0xbfb8aa3b, v159
	v_mul_f32_e32 v158, 0xbfb8aa3b, v158
	v_mul_f32_e32 v157, 0xbfb8aa3b, v157
	v_mul_f32_e32 v156, 0xbfb8aa3b, v156
	v_mul_f32_e32 v155, 0xbfb8aa3b, v155
	v_mul_f32_e32 v154, 0xbfb8aa3b, v154
	v_mul_f32_e32 v122, v122, v161
	v_exp_f32_e32 v122, v122
	v_mul_f32_e32 v126, v126, v161
	v_mul_f32_e32 v123, v123, v161
	v_add_f32_e32 v122, 1.0, v122
	v_rcp_f32_e32 v122, v122
	v_mul_f32_e32 v124, v124, v161
	v_mul_f32_e32 v125, v125, v161
	v_fma_f32 v122, v122, s31, 0.5
	v_max_f32_e32 v122, 1.0, v122
	v_cvt_u32_f32_e32 v162, v122
	v_mul_f32_e32 v122, v127, v161
	v_mul_f32_e32 v127, v128, v161
	v_mul_f32_e32 v128, v129, v161
	v_exp_f32_e32 v126, v126
	v_exp_f32_e32 v122, v122
	v_exp_f32_e32 v123, v123
	v_exp_f32_e32 v127, v127
	v_exp_f32_e32 v124, v124
	v_exp_f32_e32 v128, v128
	v_exp_f32_e32 v125, v125
	v_add_f32_e32 v126, 1.0, v126
	v_add_f32_e32 v122, 1.0, v122
	v_add_f32_e32 v123, 1.0, v123
	v_mul_f32_e32 v114, v114, v161
	v_mul_f32_e32 v115, v115, v161
	v_rcp_f32_e32 v126, v126
	v_rcp_f32_e32 v122, v122
	v_rcp_f32_e32 v123, v123
	v_add_f32_e32 v127, 1.0, v127
	v_add_f32_e32 v124, 1.0, v124
	v_add_f32_e32 v128, 1.0, v128
	v_add_f32_e32 v125, 1.0, v125
	v_mul_f32_e32 v116, v116, v161
	v_mul_f32_e32 v117, v117, v161
	v_rcp_f32_e32 v127, v127
	v_rcp_f32_e32 v124, v124
	v_rcp_f32_e32 v128, v128
	v_rcp_f32_e32 v125, v125
	v_exp_f32_e32 v114, v114
	v_exp_f32_e32 v115, v115
	v_exp_f32_e32 v116, v116
	v_exp_f32_e32 v117, v117
	v_fma_f32 v126, v126, s31, 0.5
	v_fma_f32 v122, v122, s31, 0.5
	v_fma_f32 v123, v123, s31, 0.5
	v_mul_f32_e32 v106, v106, v160
	v_max_f32_e32 v126, 1.0, v126
	v_max_f32_e32 v122, 1.0, v122
	v_max_f32_e32 v123, 1.0, v123
	v_fma_f32 v127, v127, s31, 0.5
	v_fma_f32 v124, v124, s31, 0.5
	v_fma_f32 v128, v128, s31, 0.5
	v_fma_f32 v125, v125, s31, 0.5
	v_add_f32_e32 v114, 1.0, v114
	v_add_f32_e32 v115, 1.0, v115
	v_cvt_u32_f32_e32 v126, v126
	v_cvt_u32_f32_e32 v122, v122
	v_cvt_u32_f32_e32 v123, v123
	v_max_f32_e32 v127, 1.0, v127
	v_max_f32_e32 v124, 1.0, v124
	v_max_f32_e32 v128, 1.0, v128
	v_max_f32_e32 v125, 1.0, v125
	v_rcp_f32_e32 v114, v114
	v_rcp_f32_e32 v115, v115
	v_add_f32_e32 v116, 1.0, v116
	v_add_f32_e32 v117, 1.0, v117
	v_exp_f32_e32 v106, v106
	v_cvt_u32_f32_sdwa v127, v127 dst_sel:WORD_1 dst_unused:UNUSED_PAD src0_sel:DWORD
	v_cvt_u32_f32_sdwa v124, v124 dst_sel:WORD_1 dst_unused:UNUSED_PAD src0_sel:DWORD
	v_cvt_u32_f32_sdwa v128, v128 dst_sel:BYTE_3 dst_unused:UNUSED_PAD src0_sel:DWORD
	v_cvt_u32_f32_sdwa v125, v125 dst_sel:BYTE_3 dst_unused:UNUSED_PAD src0_sel:DWORD
	v_rcp_f32_e32 v116, v116
	v_rcp_f32_e32 v117, v117
	v_lshl_or_b32 v122, v122, 8, v126
	v_lshl_or_b32 v123, v123, 8, v162
	v_fma_f32 v114, v114, s31, 0.5
	v_fma_f32 v115, v115, s31, 0.5
	v_add_f32_e32 v106, 1.0, v106
	v_or3_b32 v122, v122, v127, v128
	v_or3_b32 v123, v123, v124, v125
	v_max_f32_e32 v114, 1.0, v114
	v_max_f32_e32 v115, 1.0, v115
	v_fma_f32 v116, v116, s31, 0.5
	v_fma_f32 v117, v117, s31, 0.5
	v_rcp_f32_e32 v106, v106
	global_store_dwordx2 v[140:141], v[122:123], off
	v_cvt_u32_f32_e32 v122, v114
	v_cvt_u32_f32_e32 v115, v115
	v_max_f32_e32 v116, 1.0, v116
	v_max_f32_e32 v117, 1.0, v117
	v_cvt_u32_f32_sdwa v116, v116 dst_sel:WORD_1 dst_unused:UNUSED_PAD src0_sel:DWORD
	v_cvt_u32_f32_sdwa v117, v117 dst_sel:BYTE_3 dst_unused:UNUSED_PAD src0_sel:DWORD
	v_mul_f32_e32 v118, v118, v161
	v_mul_f32_e32 v114, v119, v161
	v_mul_f32_e32 v119, v120, v161
	v_mul_f32_e32 v120, v121, v161
	v_fma_f32 v106, v106, s31, 0.5
	v_exp_f32_e32 v118, v118
	v_exp_f32_e32 v114, v114
	v_lshl_or_b32 v115, v115, 8, v122
	v_max_f32_e32 v106, 1.0, v106
	v_exp_f32_e32 v119, v119
	v_exp_f32_e32 v120, v120
	v_or3_b32 v115, v115, v116, v117
	v_mul_f32_e32 v110, v110, v160
	v_cvt_u32_f32_e32 v116, v106
	v_mul_f32_e32 v106, v111, v160
	v_mul_f32_e32 v107, v107, v160
	v_mul_f32_e32 v111, v112, v160
	v_mul_f32_e32 v108, v108, v160
	v_mul_f32_e32 v112, v113, v160
	v_mul_f32_e32 v109, v109, v160
	v_exp_f32_e32 v110, v110
	v_exp_f32_e32 v106, v106
	v_exp_f32_e32 v107, v107
	v_add_f32_e32 v118, 1.0, v118
	v_add_f32_e32 v114, 1.0, v114
	v_exp_f32_e32 v111, v111
	v_exp_f32_e32 v108, v108
	v_exp_f32_e32 v112, v112
	v_exp_f32_e32 v109, v109
	v_rcp_f32_e32 v118, v118
	v_rcp_f32_e32 v114, v114
	v_add_f32_e32 v119, 1.0, v119
	v_add_f32_e32 v120, 1.0, v120
	v_rcp_f32_e32 v119, v119
	v_rcp_f32_e32 v120, v120
	v_add_f32_e32 v110, 1.0, v110
	v_add_f32_e32 v106, 1.0, v106
	v_add_f32_e32 v107, 1.0, v107
	v_mul_f32_e32 v98, v98, v160
	v_mul_f32_e32 v99, v99, v160
	v_rcp_f32_e32 v110, v110
	v_rcp_f32_e32 v106, v106
	v_rcp_f32_e32 v107, v107
	v_add_f32_e32 v111, 1.0, v111
	v_add_f32_e32 v108, 1.0, v108
	v_add_f32_e32 v112, 1.0, v112
	v_add_f32_e32 v109, 1.0, v109
	v_mul_f32_e32 v100, v100, v160
	v_mul_f32_e32 v101, v101, v160
	v_fma_f32 v118, v118, s31, 0.5
	v_fma_f32 v114, v114, s31, 0.5
	v_rcp_f32_e32 v111, v111
	v_rcp_f32_e32 v108, v108
	v_rcp_f32_e32 v112, v112
	v_rcp_f32_e32 v109, v109
	v_exp_f32_e32 v98, v98
	v_exp_f32_e32 v99, v99
	v_max_f32_e32 v118, 1.0, v118
	v_max_f32_e32 v114, 1.0, v114
	v_fma_f32 v119, v119, s31, 0.5
	v_fma_f32 v120, v120, s31, 0.5
	v_exp_f32_e32 v100, v100
	v_exp_f32_e32 v101, v101
	v_cvt_u32_f32_e32 v118, v118
	v_cvt_u32_f32_e32 v114, v114
	v_max_f32_e32 v119, 1.0, v119
	v_max_f32_e32 v120, 1.0, v120
	v_cvt_u32_f32_sdwa v119, v119 dst_sel:WORD_1 dst_unused:UNUSED_PAD src0_sel:DWORD
	v_cvt_u32_f32_sdwa v120, v120 dst_sel:BYTE_3 dst_unused:UNUSED_PAD src0_sel:DWORD
	v_fma_f32 v110, v110, s31, 0.5
	v_fma_f32 v106, v106, s31, 0.5
	v_fma_f32 v107, v107, s31, 0.5
	v_mul_f32_e32 v90, v90, v159
	v_max_f32_e32 v110, 1.0, v110
	v_max_f32_e32 v106, 1.0, v106
	v_max_f32_e32 v107, 1.0, v107
	v_fma_f32 v111, v111, s31, 0.5
	v_fma_f32 v108, v108, s31, 0.5
	v_fma_f32 v112, v112, s31, 0.5
	v_fma_f32 v109, v109, s31, 0.5
	v_add_f32_e32 v98, 1.0, v98
	v_add_f32_e32 v99, 1.0, v99
	v_cvt_u32_f32_e32 v110, v110
	v_cvt_u32_f32_e32 v106, v106
	v_cvt_u32_f32_e32 v107, v107
	v_max_f32_e32 v111, 1.0, v111
	v_max_f32_e32 v108, 1.0, v108
	v_max_f32_e32 v112, 1.0, v112
	v_max_f32_e32 v109, 1.0, v109
	v_rcp_f32_e32 v98, v98
	v_rcp_f32_e32 v99, v99
	v_add_f32_e32 v100, 1.0, v100
	v_add_f32_e32 v101, 1.0, v101
	v_exp_f32_e32 v90, v90
	v_lshl_or_b32 v114, v114, 8, v118
	v_cvt_u32_f32_sdwa v111, v111 dst_sel:WORD_1 dst_unused:UNUSED_PAD src0_sel:DWORD
	v_cvt_u32_f32_sdwa v108, v108 dst_sel:WORD_1 dst_unused:UNUSED_PAD src0_sel:DWORD
	v_cvt_u32_f32_sdwa v112, v112 dst_sel:BYTE_3 dst_unused:UNUSED_PAD src0_sel:DWORD
	v_cvt_u32_f32_sdwa v109, v109 dst_sel:BYTE_3 dst_unused:UNUSED_PAD src0_sel:DWORD
	v_rcp_f32_e32 v100, v100
	v_rcp_f32_e32 v101, v101
	v_or3_b32 v114, v114, v119, v120
	global_store_dwordx2 v[140:141], v[114:115], off offset:128
	v_lshlrev_b64 v[114:115], 12, v[148:149]
	v_lshl_add_u64 v[114:115], s[12:13], 0, v[114:115]
	v_lshl_or_b32 v106, v106, 8, v110
	v_lshl_or_b32 v107, v107, 8, v116
	v_fma_f32 v98, v98, s31, 0.5
	v_fma_f32 v99, v99, s31, 0.5
	v_add_f32_e32 v90, 1.0, v90
	v_lshl_add_u64 v[114:115], v[114:115], 0, v[144:145]
	v_or3_b32 v106, v106, v111, v112
	v_or3_b32 v107, v107, v108, v109
	v_max_f32_e32 v98, 1.0, v98
	v_max_f32_e32 v99, 1.0, v99
	v_fma_f32 v100, v100, s31, 0.5
	v_fma_f32 v101, v101, s31, 0.5
	v_rcp_f32_e32 v90, v90
	global_store_dwordx2 v[114:115], v[106:107], off
	v_cvt_u32_f32_e32 v106, v98
	v_cvt_u32_f32_e32 v99, v99
	v_max_f32_e32 v100, 1.0, v100
	v_max_f32_e32 v101, 1.0, v101
	v_cvt_u32_f32_sdwa v100, v100 dst_sel:WORD_1 dst_unused:UNUSED_PAD src0_sel:DWORD
	v_cvt_u32_f32_sdwa v101, v101 dst_sel:BYTE_3 dst_unused:UNUSED_PAD src0_sel:DWORD
	v_mul_f32_e32 v102, v102, v160
	v_mul_f32_e32 v98, v103, v160
	v_mul_f32_e32 v103, v104, v160
	v_mul_f32_e32 v104, v105, v160
	v_fma_f32 v90, v90, s31, 0.5
	v_exp_f32_e32 v102, v102
	v_exp_f32_e32 v98, v98
	v_lshl_or_b32 v99, v99, 8, v106
	v_max_f32_e32 v90, 1.0, v90
	v_exp_f32_e32 v103, v103
	v_exp_f32_e32 v104, v104
	v_or3_b32 v99, v99, v100, v101
	v_mul_f32_e32 v94, v94, v159
	v_cvt_u32_f32_e32 v100, v90
	v_mul_f32_e32 v90, v95, v159
	v_mul_f32_e32 v91, v91, v159
	v_mul_f32_e32 v95, v96, v159
	v_mul_f32_e32 v92, v92, v159
	v_mul_f32_e32 v96, v97, v159
	v_mul_f32_e32 v93, v93, v159
	v_exp_f32_e32 v94, v94
	v_exp_f32_e32 v90, v90
	v_exp_f32_e32 v91, v91
	v_add_f32_e32 v102, 1.0, v102
	v_add_f32_e32 v98, 1.0, v98
	v_exp_f32_e32 v95, v95
	v_exp_f32_e32 v92, v92
	v_exp_f32_e32 v96, v96
	v_exp_f32_e32 v93, v93
	v_rcp_f32_e32 v102, v102
	v_rcp_f32_e32 v98, v98
	v_add_f32_e32 v103, 1.0, v103
	v_add_f32_e32 v104, 1.0, v104
	v_rcp_f32_e32 v103, v103
	v_rcp_f32_e32 v104, v104
	v_add_f32_e32 v94, 1.0, v94
	v_add_f32_e32 v90, 1.0, v90
	v_add_f32_e32 v91, 1.0, v91
	v_mul_f32_e32 v82, v82, v159
	v_mul_f32_e32 v83, v83, v159
	v_rcp_f32_e32 v94, v94
	v_rcp_f32_e32 v90, v90
	v_rcp_f32_e32 v91, v91
	v_add_f32_e32 v95, 1.0, v95
	v_add_f32_e32 v92, 1.0, v92
	v_add_f32_e32 v96, 1.0, v96
	v_add_f32_e32 v93, 1.0, v93
	v_mul_f32_e32 v84, v84, v159
	v_mul_f32_e32 v85, v85, v159
	v_fma_f32 v102, v102, s31, 0.5
	v_fma_f32 v98, v98, s31, 0.5
	v_rcp_f32_e32 v95, v95
	v_rcp_f32_e32 v92, v92
	v_rcp_f32_e32 v96, v96
	v_rcp_f32_e32 v93, v93
	v_exp_f32_e32 v82, v82
	v_exp_f32_e32 v83, v83
	v_max_f32_e32 v102, 1.0, v102
	v_max_f32_e32 v98, 1.0, v98
	v_fma_f32 v103, v103, s31, 0.5
	v_fma_f32 v104, v104, s31, 0.5
	v_exp_f32_e32 v84, v84
	v_exp_f32_e32 v85, v85
	v_cvt_u32_f32_e32 v102, v102
	v_cvt_u32_f32_e32 v98, v98
	v_max_f32_e32 v103, 1.0, v103
	v_max_f32_e32 v104, 1.0, v104
	v_cvt_u32_f32_sdwa v103, v103 dst_sel:WORD_1 dst_unused:UNUSED_PAD src0_sel:DWORD
	v_cvt_u32_f32_sdwa v104, v104 dst_sel:BYTE_3 dst_unused:UNUSED_PAD src0_sel:DWORD
	v_fma_f32 v94, v94, s31, 0.5
	v_fma_f32 v90, v90, s31, 0.5
	v_fma_f32 v91, v91, s31, 0.5
	v_mul_f32_e32 v74, v74, v158
	v_max_f32_e32 v94, 1.0, v94
	v_max_f32_e32 v90, 1.0, v90
	v_max_f32_e32 v91, 1.0, v91
	v_fma_f32 v95, v95, s31, 0.5
	v_fma_f32 v92, v92, s31, 0.5
	v_fma_f32 v96, v96, s31, 0.5
	v_fma_f32 v93, v93, s31, 0.5
	v_add_f32_e32 v82, 1.0, v82
	v_add_f32_e32 v83, 1.0, v83
	v_cvt_u32_f32_e32 v94, v94
	v_cvt_u32_f32_e32 v90, v90
	v_cvt_u32_f32_e32 v91, v91
	v_max_f32_e32 v95, 1.0, v95
	v_max_f32_e32 v92, 1.0, v92
	v_max_f32_e32 v96, 1.0, v96
	v_max_f32_e32 v93, 1.0, v93
	v_rcp_f32_e32 v82, v82
	v_rcp_f32_e32 v83, v83
	v_add_f32_e32 v84, 1.0, v84
	v_add_f32_e32 v85, 1.0, v85
	v_exp_f32_e32 v74, v74
	v_lshl_or_b32 v98, v98, 8, v102
	v_cvt_u32_f32_sdwa v95, v95 dst_sel:WORD_1 dst_unused:UNUSED_PAD src0_sel:DWORD
	v_cvt_u32_f32_sdwa v92, v92 dst_sel:WORD_1 dst_unused:UNUSED_PAD src0_sel:DWORD
	v_cvt_u32_f32_sdwa v96, v96 dst_sel:BYTE_3 dst_unused:UNUSED_PAD src0_sel:DWORD
	v_cvt_u32_f32_sdwa v93, v93 dst_sel:BYTE_3 dst_unused:UNUSED_PAD src0_sel:DWORD
	v_rcp_f32_e32 v84, v84
	v_rcp_f32_e32 v85, v85
	v_or3_b32 v98, v98, v103, v104
	global_store_dwordx2 v[114:115], v[98:99], off offset:128
	v_lshlrev_b64 v[98:99], 12, v[146:147]
	v_lshl_add_u64 v[98:99], s[12:13], 0, v[98:99]
	v_lshl_or_b32 v90, v90, 8, v94
	v_lshl_or_b32 v91, v91, 8, v100
	v_fma_f32 v82, v82, s31, 0.5
	v_fma_f32 v83, v83, s31, 0.5
	v_add_f32_e32 v74, 1.0, v74
	v_lshl_add_u64 v[98:99], v[98:99], 0, v[144:145]
	v_or3_b32 v90, v90, v95, v96
	v_or3_b32 v91, v91, v92, v93
	v_max_f32_e32 v82, 1.0, v82
	v_max_f32_e32 v83, 1.0, v83
	v_fma_f32 v84, v84, s31, 0.5
	v_fma_f32 v85, v85, s31, 0.5
	v_rcp_f32_e32 v74, v74
	global_store_dwordx2 v[98:99], v[90:91], off
	v_cvt_u32_f32_e32 v90, v82
	v_cvt_u32_f32_e32 v83, v83
	v_max_f32_e32 v84, 1.0, v84
	v_max_f32_e32 v85, 1.0, v85
	v_cvt_u32_f32_sdwa v84, v84 dst_sel:WORD_1 dst_unused:UNUSED_PAD src0_sel:DWORD
	v_cvt_u32_f32_sdwa v85, v85 dst_sel:BYTE_3 dst_unused:UNUSED_PAD src0_sel:DWORD
	v_mul_f32_e32 v86, v86, v159
	v_mul_f32_e32 v82, v87, v159
	v_mul_f32_e32 v87, v88, v159
	v_mul_f32_e32 v88, v89, v159
	v_fma_f32 v74, v74, s31, 0.5
	v_exp_f32_e32 v86, v86
	v_exp_f32_e32 v82, v82
	v_lshl_or_b32 v83, v83, 8, v90
	v_max_f32_e32 v74, 1.0, v74
	v_exp_f32_e32 v87, v87
	v_exp_f32_e32 v88, v88
	v_or3_b32 v83, v83, v84, v85
	v_mul_f32_e32 v78, v78, v158
	v_cvt_u32_f32_e32 v84, v74
	v_mul_f32_e32 v74, v79, v158
	v_mul_f32_e32 v75, v75, v158
	v_mul_f32_e32 v79, v80, v158
	v_mul_f32_e32 v76, v76, v158
	v_mul_f32_e32 v80, v81, v158
	v_mul_f32_e32 v77, v77, v158
	v_exp_f32_e32 v78, v78
	v_exp_f32_e32 v74, v74
	v_exp_f32_e32 v75, v75
	v_add_f32_e32 v86, 1.0, v86
	v_add_f32_e32 v82, 1.0, v82
	v_exp_f32_e32 v79, v79
	v_exp_f32_e32 v76, v76
	v_exp_f32_e32 v80, v80
	v_exp_f32_e32 v77, v77
	v_rcp_f32_e32 v86, v86
	v_rcp_f32_e32 v82, v82
	v_add_f32_e32 v87, 1.0, v87
	v_add_f32_e32 v88, 1.0, v88
	v_rcp_f32_e32 v87, v87
	v_rcp_f32_e32 v88, v88
	v_add_f32_e32 v78, 1.0, v78
	v_add_f32_e32 v74, 1.0, v74
	v_add_f32_e32 v75, 1.0, v75
	v_mul_f32_e32 v66, v66, v158
	v_mul_f32_e32 v67, v67, v158
	v_rcp_f32_e32 v78, v78
	v_rcp_f32_e32 v74, v74
	v_rcp_f32_e32 v75, v75
	v_add_f32_e32 v79, 1.0, v79
	v_add_f32_e32 v76, 1.0, v76
	v_add_f32_e32 v80, 1.0, v80
	v_add_f32_e32 v77, 1.0, v77
	v_mul_f32_e32 v68, v68, v158
	v_mul_f32_e32 v69, v69, v158
	v_fma_f32 v86, v86, s31, 0.5
	v_fma_f32 v82, v82, s31, 0.5
	v_rcp_f32_e32 v79, v79
	v_rcp_f32_e32 v76, v76
	v_rcp_f32_e32 v80, v80
	v_rcp_f32_e32 v77, v77
	v_exp_f32_e32 v66, v66
	v_exp_f32_e32 v67, v67
	v_max_f32_e32 v86, 1.0, v86
	v_max_f32_e32 v82, 1.0, v82
	v_fma_f32 v87, v87, s31, 0.5
	v_fma_f32 v88, v88, s31, 0.5
	v_exp_f32_e32 v68, v68
	v_exp_f32_e32 v69, v69
	v_cvt_u32_f32_e32 v86, v86
	v_cvt_u32_f32_e32 v82, v82
	v_max_f32_e32 v87, 1.0, v87
	v_max_f32_e32 v88, 1.0, v88
	v_cvt_u32_f32_sdwa v87, v87 dst_sel:WORD_1 dst_unused:UNUSED_PAD src0_sel:DWORD
	v_cvt_u32_f32_sdwa v88, v88 dst_sel:BYTE_3 dst_unused:UNUSED_PAD src0_sel:DWORD
	v_fma_f32 v78, v78, s31, 0.5
	v_fma_f32 v74, v74, s31, 0.5
	v_fma_f32 v75, v75, s31, 0.5
	v_mul_f32_e32 v58, v58, v157
	v_max_f32_e32 v78, 1.0, v78
	v_max_f32_e32 v74, 1.0, v74
	v_max_f32_e32 v75, 1.0, v75
	v_fma_f32 v79, v79, s31, 0.5
	v_fma_f32 v76, v76, s31, 0.5
	v_fma_f32 v80, v80, s31, 0.5
	v_fma_f32 v77, v77, s31, 0.5
	v_add_f32_e32 v66, 1.0, v66
	v_add_f32_e32 v67, 1.0, v67
	v_cvt_u32_f32_e32 v78, v78
	v_cvt_u32_f32_e32 v74, v74
	v_cvt_u32_f32_e32 v75, v75
	v_max_f32_e32 v79, 1.0, v79
	v_max_f32_e32 v76, 1.0, v76
	v_max_f32_e32 v80, 1.0, v80
	v_max_f32_e32 v77, 1.0, v77
	v_rcp_f32_e32 v66, v66
	v_rcp_f32_e32 v67, v67
	v_add_f32_e32 v68, 1.0, v68
	v_add_f32_e32 v69, 1.0, v69
	v_exp_f32_e32 v58, v58
	v_lshl_or_b32 v82, v82, 8, v86
	v_cvt_u32_f32_sdwa v79, v79 dst_sel:WORD_1 dst_unused:UNUSED_PAD src0_sel:DWORD
	v_cvt_u32_f32_sdwa v76, v76 dst_sel:WORD_1 dst_unused:UNUSED_PAD src0_sel:DWORD
	v_cvt_u32_f32_sdwa v80, v80 dst_sel:BYTE_3 dst_unused:UNUSED_PAD src0_sel:DWORD
	v_cvt_u32_f32_sdwa v77, v77 dst_sel:BYTE_3 dst_unused:UNUSED_PAD src0_sel:DWORD
	v_rcp_f32_e32 v68, v68
	v_rcp_f32_e32 v69, v69
	v_or3_b32 v82, v82, v87, v88
	global_store_dwordx2 v[98:99], v[82:83], off offset:128
	v_lshlrev_b64 v[82:83], 12, v[142:143]
	v_lshl_add_u64 v[82:83], s[12:13], 0, v[82:83]
	v_lshl_or_b32 v74, v74, 8, v78
	v_lshl_or_b32 v75, v75, 8, v84
	v_fma_f32 v66, v66, s31, 0.5
	v_fma_f32 v67, v67, s31, 0.5
	v_add_f32_e32 v58, 1.0, v58
	v_lshl_add_u64 v[82:83], v[82:83], 0, v[144:145]
	v_or3_b32 v74, v74, v79, v80
	v_or3_b32 v75, v75, v76, v77
	v_max_f32_e32 v66, 1.0, v66
	v_max_f32_e32 v67, 1.0, v67
	v_fma_f32 v68, v68, s31, 0.5
	v_fma_f32 v69, v69, s31, 0.5
	v_rcp_f32_e32 v58, v58
	global_store_dwordx2 v[82:83], v[74:75], off
	v_cvt_u32_f32_e32 v74, v66
	v_cvt_u32_f32_e32 v67, v67
	v_max_f32_e32 v68, 1.0, v68
	v_max_f32_e32 v69, 1.0, v69
	v_cvt_u32_f32_sdwa v68, v68 dst_sel:WORD_1 dst_unused:UNUSED_PAD src0_sel:DWORD
	v_cvt_u32_f32_sdwa v69, v69 dst_sel:BYTE_3 dst_unused:UNUSED_PAD src0_sel:DWORD
	v_fma_f32 v58, v58, s31, 0.5
	v_lshl_or_b32 v67, v67, 8, v74
	v_max_f32_e32 v58, 1.0, v58
	v_mul_f32_e32 v59, v59, v157
	v_or3_b32 v67, v67, v68, v69
	v_mul_f32_e32 v62, v62, v157
	v_cvt_u32_f32_e32 v68, v58
	v_mul_f32_e32 v58, v63, v157
	v_mul_f32_e32 v60, v60, v157
	v_mul_f32_e32 v61, v61, v157
	v_exp_f32_e32 v59, v59
	v_mul_f32_e32 v63, v64, v157
	v_mul_f32_e32 v64, v65, v157
	v_exp_f32_e32 v62, v62
	v_exp_f32_e32 v58, v58
	v_exp_f32_e32 v60, v60
	v_exp_f32_e32 v61, v61
	v_exp_f32_e32 v63, v63
	v_exp_f32_e32 v64, v64
	v_add_f32_e32 v59, 1.0, v59
	v_add_f32_e32 v62, 1.0, v62
	v_add_f32_e32 v58, 1.0, v58
	v_rcp_f32_e32 v59, v59
	v_add_f32_e32 v60, 1.0, v60
	v_add_f32_e32 v61, 1.0, v61
	v_mul_f32_e32 v50, v50, v157
	v_mul_f32_e32 v51, v51, v157
	v_rcp_f32_e32 v62, v62
	v_rcp_f32_e32 v58, v58
	v_add_f32_e32 v63, 1.0, v63
	v_rcp_f32_e32 v60, v60
	v_add_f32_e32 v64, 1.0, v64
	v_rcp_f32_e32 v61, v61
	v_mul_f32_e32 v52, v52, v157
	v_mul_f32_e32 v53, v53, v157
	v_rcp_f32_e32 v63, v63
	v_rcp_f32_e32 v64, v64
	v_exp_f32_e32 v50, v50
	v_exp_f32_e32 v51, v51
	v_exp_f32_e32 v52, v52
	v_exp_f32_e32 v53, v53
	v_fma_f32 v59, v59, s31, 0.5
	v_fma_f32 v62, v62, s31, 0.5
	v_fma_f32 v58, v58, s31, 0.5
	v_max_f32_e32 v59, 1.0, v59
	v_fma_f32 v60, v60, s31, 0.5
	v_fma_f32 v61, v61, s31, 0.5
	v_mul_f32_e32 v42, v42, v156
	v_max_f32_e32 v62, 1.0, v62
	v_max_f32_e32 v58, 1.0, v58
	v_cvt_u32_f32_e32 v59, v59
	v_fma_f32 v63, v63, s31, 0.5
	v_max_f32_e32 v60, 1.0, v60
	v_fma_f32 v64, v64, s31, 0.5
	v_max_f32_e32 v61, 1.0, v61
	v_add_f32_e32 v50, 1.0, v50
	v_add_f32_e32 v51, 1.0, v51
	v_cvt_u32_f32_e32 v62, v62
	v_cvt_u32_f32_e32 v58, v58
	v_max_f32_e32 v63, 1.0, v63
	v_cvt_u32_f32_sdwa v60, v60 dst_sel:WORD_1 dst_unused:UNUSED_PAD src0_sel:DWORD
	v_max_f32_e32 v64, 1.0, v64
	v_cvt_u32_f32_sdwa v61, v61 dst_sel:BYTE_3 dst_unused:UNUSED_PAD src0_sel:DWORD
	v_rcp_f32_e32 v50, v50
	v_rcp_f32_e32 v51, v51
	v_add_f32_e32 v52, 1.0, v52
	v_add_f32_e32 v53, 1.0, v53
	v_exp_f32_e32 v42, v42
	v_cvt_u32_f32_sdwa v63, v63 dst_sel:WORD_1 dst_unused:UNUSED_PAD src0_sel:DWORD
	v_cvt_u32_f32_sdwa v64, v64 dst_sel:BYTE_3 dst_unused:UNUSED_PAD src0_sel:DWORD
	v_rcp_f32_e32 v52, v52
	v_rcp_f32_e32 v53, v53
	v_lshl_or_b32 v59, v59, 8, v68
	v_lshl_or_b32 v58, v58, 8, v62
	v_or3_b32 v59, v59, v60, v61
	v_add_co_u32_e32 v60, vcc, s5, v140
	v_fma_f32 v50, v50, s31, 0.5
	v_fma_f32 v51, v51, s31, 0.5
	v_add_f32_e32 v42, 1.0, v42
	v_or3_b32 v58, v58, v63, v64
	v_addc_co_u32_e32 v61, vcc, 0, v141, vcc
	v_max_f32_e32 v50, 1.0, v50
	v_max_f32_e32 v51, 1.0, v51
	v_fma_f32 v52, v52, s31, 0.5
	v_fma_f32 v53, v53, s31, 0.5
	v_rcp_f32_e32 v42, v42
	global_store_dwordx2 v[60:61], v[58:59], off
	v_cvt_u32_f32_e32 v58, v50
	v_cvt_u32_f32_e32 v51, v51
	v_max_f32_e32 v52, 1.0, v52
	v_max_f32_e32 v53, 1.0, v53
	v_cvt_u32_f32_sdwa v52, v52 dst_sel:WORD_1 dst_unused:UNUSED_PAD src0_sel:DWORD
	v_cvt_u32_f32_sdwa v53, v53 dst_sel:BYTE_3 dst_unused:UNUSED_PAD src0_sel:DWORD
	v_fma_f32 v42, v42, s31, 0.5
	v_lshl_or_b32 v51, v51, 8, v58
	v_max_f32_e32 v42, 1.0, v42
	v_mul_f32_e32 v43, v43, v156
	v_or3_b32 v51, v51, v52, v53
	v_mul_f32_e32 v46, v46, v156
	v_cvt_u32_f32_e32 v52, v42
	v_mul_f32_e32 v42, v47, v156
	v_mul_f32_e32 v44, v44, v156
	v_mul_f32_e32 v45, v45, v156
	v_exp_f32_e32 v43, v43
	v_mul_f32_e32 v47, v48, v156
	v_mul_f32_e32 v48, v49, v156
	v_exp_f32_e32 v46, v46
	v_exp_f32_e32 v42, v42
	v_exp_f32_e32 v44, v44
	v_exp_f32_e32 v45, v45
	v_exp_f32_e32 v47, v47
	v_exp_f32_e32 v48, v48
	v_add_f32_e32 v43, 1.0, v43
	v_add_f32_e32 v46, 1.0, v46
	v_add_f32_e32 v42, 1.0, v42
	v_rcp_f32_e32 v43, v43
	v_add_f32_e32 v44, 1.0, v44
	v_add_f32_e32 v45, 1.0, v45
	v_mul_f32_e32 v34, v34, v156
	v_mul_f32_e32 v35, v35, v156
	v_rcp_f32_e32 v46, v46
	v_rcp_f32_e32 v42, v42
	v_add_f32_e32 v47, 1.0, v47
	v_rcp_f32_e32 v44, v44
	v_add_f32_e32 v48, 1.0, v48
	v_rcp_f32_e32 v45, v45
	v_mul_f32_e32 v36, v36, v156
	v_mul_f32_e32 v37, v37, v156
	v_rcp_f32_e32 v47, v47
	v_rcp_f32_e32 v48, v48
	v_exp_f32_e32 v34, v34
	v_exp_f32_e32 v35, v35
	v_exp_f32_e32 v36, v36
	v_exp_f32_e32 v37, v37
	v_fma_f32 v43, v43, s31, 0.5
	v_fma_f32 v46, v46, s31, 0.5
	v_fma_f32 v42, v42, s31, 0.5
	v_max_f32_e32 v43, 1.0, v43
	v_fma_f32 v44, v44, s31, 0.5
	v_fma_f32 v45, v45, s31, 0.5
	v_mul_f32_e32 v26, v26, v155
	v_max_f32_e32 v46, 1.0, v46
	v_max_f32_e32 v42, 1.0, v42
	v_cvt_u32_f32_e32 v43, v43
	v_fma_f32 v47, v47, s31, 0.5
	v_max_f32_e32 v44, 1.0, v44
	v_fma_f32 v48, v48, s31, 0.5
	v_max_f32_e32 v45, 1.0, v45
	v_add_f32_e32 v34, 1.0, v34
	v_add_f32_e32 v35, 1.0, v35
	v_cvt_u32_f32_e32 v46, v46
	v_cvt_u32_f32_e32 v42, v42
	v_max_f32_e32 v47, 1.0, v47
	v_cvt_u32_f32_sdwa v44, v44 dst_sel:WORD_1 dst_unused:UNUSED_PAD src0_sel:DWORD
	v_max_f32_e32 v48, 1.0, v48
	v_cvt_u32_f32_sdwa v45, v45 dst_sel:BYTE_3 dst_unused:UNUSED_PAD src0_sel:DWORD
	v_rcp_f32_e32 v34, v34
	v_rcp_f32_e32 v35, v35
	v_add_f32_e32 v36, 1.0, v36
	v_add_f32_e32 v37, 1.0, v37
	v_exp_f32_e32 v26, v26
	v_cvt_u32_f32_sdwa v47, v47 dst_sel:WORD_1 dst_unused:UNUSED_PAD src0_sel:DWORD
	v_cvt_u32_f32_sdwa v48, v48 dst_sel:BYTE_3 dst_unused:UNUSED_PAD src0_sel:DWORD
	v_rcp_f32_e32 v36, v36
	v_rcp_f32_e32 v37, v37
	v_lshl_or_b32 v43, v43, 8, v52
	s_mov_b32 s5, 0x90000
	v_lshl_or_b32 v42, v42, 8, v46
	v_or3_b32 v43, v43, v44, v45
	v_add_co_u32_e32 v44, vcc, s5, v140
	v_fma_f32 v34, v34, s31, 0.5
	v_fma_f32 v35, v35, s31, 0.5
	v_add_f32_e32 v26, 1.0, v26
	v_or3_b32 v42, v42, v47, v48
	v_addc_co_u32_e32 v45, vcc, 0, v141, vcc
	v_max_f32_e32 v34, 1.0, v34
	v_max_f32_e32 v35, 1.0, v35
	v_fma_f32 v36, v36, s31, 0.5
	v_fma_f32 v37, v37, s31, 0.5
	v_rcp_f32_e32 v26, v26
	global_store_dwordx2 v[44:45], v[42:43], off
	v_cvt_u32_f32_e32 v42, v34
	v_cvt_u32_f32_e32 v35, v35
	v_max_f32_e32 v36, 1.0, v36
	v_max_f32_e32 v37, 1.0, v37
	v_cvt_u32_f32_sdwa v36, v36 dst_sel:WORD_1 dst_unused:UNUSED_PAD src0_sel:DWORD
	v_cvt_u32_f32_sdwa v37, v37 dst_sel:BYTE_3 dst_unused:UNUSED_PAD src0_sel:DWORD
	v_fma_f32 v26, v26, s31, 0.5
	v_lshl_or_b32 v35, v35, 8, v42
	v_max_f32_e32 v26, 1.0, v26
	v_mul_f32_e32 v27, v27, v155
	v_or3_b32 v35, v35, v36, v37
	v_mul_f32_e32 v30, v30, v155
	v_cvt_u32_f32_e32 v36, v26
	v_mul_f32_e32 v26, v31, v155
	v_mul_f32_e32 v28, v28, v155
	v_mul_f32_e32 v29, v29, v155
	v_exp_f32_e32 v27, v27
	v_mul_f32_e32 v31, v32, v155
	v_mul_f32_e32 v32, v33, v155
	v_exp_f32_e32 v30, v30
	v_exp_f32_e32 v26, v26
	v_exp_f32_e32 v28, v28
	v_exp_f32_e32 v29, v29
	v_exp_f32_e32 v31, v31
	v_exp_f32_e32 v32, v32
	v_add_f32_e32 v27, 1.0, v27
	v_add_f32_e32 v30, 1.0, v30
	v_add_f32_e32 v26, 1.0, v26
	v_rcp_f32_e32 v27, v27
	v_add_f32_e32 v28, 1.0, v28
	v_add_f32_e32 v29, 1.0, v29
	v_mul_f32_e32 v18, v18, v155
	v_mul_f32_e32 v19, v19, v155
	v_rcp_f32_e32 v30, v30
	v_rcp_f32_e32 v26, v26
	v_add_f32_e32 v31, 1.0, v31
	v_rcp_f32_e32 v28, v28
	v_add_f32_e32 v32, 1.0, v32
	v_rcp_f32_e32 v29, v29
	v_mul_f32_e32 v20, v20, v155
	v_mul_f32_e32 v21, v21, v155
	v_rcp_f32_e32 v31, v31
	v_rcp_f32_e32 v32, v32
	v_exp_f32_e32 v18, v18
	v_exp_f32_e32 v19, v19
	v_exp_f32_e32 v20, v20
	v_exp_f32_e32 v21, v21
	v_fma_f32 v27, v27, s31, 0.5
	v_fma_f32 v30, v30, s31, 0.5
	v_fma_f32 v26, v26, s31, 0.5
	v_max_f32_e32 v27, 1.0, v27
	v_fma_f32 v28, v28, s31, 0.5
	v_fma_f32 v29, v29, s31, 0.5
	v_mul_f32_e32 v8, v8, v154
	v_max_f32_e32 v30, 1.0, v30
	v_max_f32_e32 v26, 1.0, v26
	v_cvt_u32_f32_e32 v27, v27
	v_fma_f32 v31, v31, s31, 0.5
	v_max_f32_e32 v28, 1.0, v28
	v_fma_f32 v32, v32, s31, 0.5
	v_max_f32_e32 v29, 1.0, v29
	v_add_f32_e32 v18, 1.0, v18
	v_add_f32_e32 v19, 1.0, v19
	v_cvt_u32_f32_e32 v30, v30
	v_cvt_u32_f32_e32 v26, v26
	v_max_f32_e32 v31, 1.0, v31
	v_cvt_u32_f32_sdwa v28, v28 dst_sel:WORD_1 dst_unused:UNUSED_PAD src0_sel:DWORD
	v_max_f32_e32 v32, 1.0, v32
	v_cvt_u32_f32_sdwa v29, v29 dst_sel:BYTE_3 dst_unused:UNUSED_PAD src0_sel:DWORD
	v_rcp_f32_e32 v18, v18
	v_rcp_f32_e32 v19, v19
	v_add_f32_e32 v20, 1.0, v20
	v_add_f32_e32 v21, 1.0, v21
	v_exp_f32_e32 v8, v8
	v_cvt_u32_f32_sdwa v31, v31 dst_sel:WORD_1 dst_unused:UNUSED_PAD src0_sel:DWORD
	v_cvt_u32_f32_sdwa v32, v32 dst_sel:BYTE_3 dst_unused:UNUSED_PAD src0_sel:DWORD
	v_rcp_f32_e32 v20, v20
	v_rcp_f32_e32 v21, v21
	v_lshl_or_b32 v27, v27, 8, v36
	s_mov_b32 s5, 0xa0000
	v_lshl_or_b32 v26, v26, 8, v30
	v_or3_b32 v27, v27, v28, v29
	v_add_co_u32_e32 v28, vcc, s5, v140
	v_fma_f32 v18, v18, s31, 0.5
	v_fma_f32 v19, v19, s31, 0.5
	v_add_f32_e32 v8, 1.0, v8
	v_or3_b32 v26, v26, v31, v32
	v_addc_co_u32_e32 v29, vcc, 0, v141, vcc
	v_max_f32_e32 v18, 1.0, v18
	v_max_f32_e32 v19, 1.0, v19
	v_fma_f32 v20, v20, s31, 0.5
	v_fma_f32 v21, v21, s31, 0.5
	v_rcp_f32_e32 v8, v8
	global_store_dwordx2 v[28:29], v[26:27], off
	v_cvt_u32_f32_e32 v26, v18
	v_cvt_u32_f32_e32 v19, v19
	v_max_f32_e32 v20, 1.0, v20
	v_max_f32_e32 v21, 1.0, v21
	v_cvt_u32_f32_sdwa v20, v20 dst_sel:WORD_1 dst_unused:UNUSED_PAD src0_sel:DWORD
	v_cvt_u32_f32_sdwa v21, v21 dst_sel:BYTE_3 dst_unused:UNUSED_PAD src0_sel:DWORD
	v_fma_f32 v8, v8, s31, 0.5
	v_lshl_or_b32 v19, v19, 8, v26
	v_max_f32_e32 v8, 1.0, v8
	v_mul_f32_e32 v9, v9, v154
	v_or3_b32 v19, v19, v20, v21
	v_mul_f32_e32 v12, v12, v154
	v_cvt_u32_f32_e32 v20, v8
	v_mul_f32_e32 v8, v13, v154
	v_mul_f32_e32 v10, v10, v154
	v_mul_f32_e32 v11, v11, v154
	v_exp_f32_e32 v9, v9
	v_mul_f32_e32 v13, v14, v154
	v_mul_f32_e32 v14, v15, v154
	v_exp_f32_e32 v12, v12
	v_exp_f32_e32 v8, v8
	v_exp_f32_e32 v10, v10
	v_exp_f32_e32 v11, v11
	v_exp_f32_e32 v13, v13
	v_exp_f32_e32 v14, v14
	v_add_f32_e32 v9, 1.0, v9
	v_add_f32_e32 v12, 1.0, v12
	v_add_f32_e32 v8, 1.0, v8
	v_rcp_f32_e32 v9, v9
	v_add_f32_e32 v10, 1.0, v10
	v_add_f32_e32 v11, 1.0, v11
	v_mul_f32_e32 v0, v0, v154
	v_rcp_f32_e32 v12, v12
	v_rcp_f32_e32 v8, v8
	v_add_f32_e32 v13, 1.0, v13
	v_rcp_f32_e32 v10, v10
	v_add_f32_e32 v14, 1.0, v14
	v_rcp_f32_e32 v11, v11
	v_rcp_f32_e32 v13, v13
	v_rcp_f32_e32 v14, v14
	v_exp_f32_e32 v0, v0
	v_fma_f32 v9, v9, s31, 0.5
	v_fma_f32 v12, v12, s31, 0.5
	v_fma_f32 v8, v8, s31, 0.5
	v_max_f32_e32 v9, 1.0, v9
	v_fma_f32 v10, v10, s31, 0.5
	v_fma_f32 v11, v11, s31, 0.5
	v_max_f32_e32 v12, 1.0, v12
	v_max_f32_e32 v8, 1.0, v8
	v_cvt_u32_f32_e32 v9, v9
	v_fma_f32 v13, v13, s31, 0.5
	v_max_f32_e32 v10, 1.0, v10
	v_fma_f32 v14, v14, s31, 0.5
	v_max_f32_e32 v11, 1.0, v11
	v_add_f32_e32 v0, 1.0, v0
	v_cvt_u32_f32_e32 v12, v12
	v_cvt_u32_f32_e32 v8, v8
	v_max_f32_e32 v13, 1.0, v13
	v_cvt_u32_f32_sdwa v10, v10 dst_sel:WORD_1 dst_unused:UNUSED_PAD src0_sel:DWORD
	v_max_f32_e32 v14, 1.0, v14
	v_cvt_u32_f32_sdwa v11, v11 dst_sel:BYTE_3 dst_unused:UNUSED_PAD src0_sel:DWORD
	v_rcp_f32_e32 v0, v0
	v_cvt_u32_f32_sdwa v13, v13 dst_sel:WORD_1 dst_unused:UNUSED_PAD src0_sel:DWORD
	v_cvt_u32_f32_sdwa v14, v14 dst_sel:BYTE_3 dst_unused:UNUSED_PAD src0_sel:DWORD
	v_mul_f32_e32 v70, v70, v158
	v_mul_f32_e32 v66, v71, v158
	v_mul_f32_e32 v71, v72, v158
	v_mul_f32_e32 v72, v73, v158
	v_mul_f32_e32 v54, v54, v157
	v_mul_f32_e32 v50, v55, v157
	v_lshl_or_b32 v9, v9, 8, v20
	s_mov_b32 s5, 0xb0000
	v_exp_f32_e32 v70, v70
	v_exp_f32_e32 v66, v66
	v_mul_f32_e32 v55, v56, v157
	v_mul_f32_e32 v56, v57, v157
	v_mul_f32_e32 v38, v38, v156
	v_mul_f32_e32 v34, v39, v156
	v_lshl_or_b32 v8, v8, 8, v12
	v_or3_b32 v9, v9, v10, v11
	v_add_co_u32_e32 v10, vcc, s5, v140
	v_fma_f32 v0, v0, s31, 0.5
	v_exp_f32_e32 v71, v71
	v_exp_f32_e32 v72, v72
	v_exp_f32_e32 v54, v54
	v_exp_f32_e32 v50, v50
	v_mul_f32_e32 v39, v40, v156
	v_mul_f32_e32 v40, v41, v156
	v_mul_f32_e32 v22, v22, v155
	v_mul_f32_e32 v18, v23, v155
	v_or3_b32 v8, v8, v13, v14
	v_addc_co_u32_e32 v11, vcc, 0, v141, vcc
	v_max_f32_e32 v0, 1.0, v0
	v_exp_f32_e32 v55, v55
	v_exp_f32_e32 v56, v56
	v_exp_f32_e32 v38, v38
	v_exp_f32_e32 v34, v34
	v_mul_f32_e32 v23, v24, v155
	v_mul_f32_e32 v24, v25, v155
	global_store_dwordx2 v[10:11], v[8:9], off
	v_mul_f32_e32 v4, v4, v154
	v_cvt_u32_f32_e32 v8, v0
	v_mul_f32_e32 v0, v5, v154
	v_mul_f32_e32 v1, v1, v154
	v_exp_f32_e32 v39, v39
	v_exp_f32_e32 v40, v40
	v_exp_f32_e32 v22, v22
	v_exp_f32_e32 v18, v18
	v_mul_f32_e32 v5, v6, v154
	v_mul_f32_e32 v2, v2, v154
	v_mul_f32_e32 v6, v7, v154
	v_mul_f32_e32 v3, v3, v154
	v_add_f32_e32 v70, 1.0, v70
	v_add_f32_e32 v66, 1.0, v66
	v_exp_f32_e32 v23, v23
	v_exp_f32_e32 v24, v24
	v_exp_f32_e32 v4, v4
	v_exp_f32_e32 v0, v0
	v_exp_f32_e32 v1, v1
	v_rcp_f32_e32 v70, v70
	v_rcp_f32_e32 v66, v66
	v_add_f32_e32 v71, 1.0, v71
	v_add_f32_e32 v72, 1.0, v72
	v_add_f32_e32 v54, 1.0, v54
	v_add_f32_e32 v50, 1.0, v50
	v_exp_f32_e32 v5, v5
	v_exp_f32_e32 v2, v2
	v_exp_f32_e32 v6, v6
	v_exp_f32_e32 v3, v3
	v_rcp_f32_e32 v71, v71
	v_rcp_f32_e32 v72, v72
	v_rcp_f32_e32 v54, v54
	v_rcp_f32_e32 v50, v50
	v_add_f32_e32 v55, 1.0, v55
	v_add_f32_e32 v56, 1.0, v56
	v_add_f32_e32 v38, 1.0, v38
	v_add_f32_e32 v34, 1.0, v34
	v_rcp_f32_e32 v55, v55
	v_rcp_f32_e32 v56, v56
	v_rcp_f32_e32 v38, v38
	v_rcp_f32_e32 v34, v34
	v_add_f32_e32 v39, 1.0, v39
	v_add_f32_e32 v40, 1.0, v40
	v_add_f32_e32 v22, 1.0, v22
	v_add_f32_e32 v18, 1.0, v18
	v_rcp_f32_e32 v39, v39
	v_rcp_f32_e32 v40, v40
	v_rcp_f32_e32 v22, v22
	v_rcp_f32_e32 v18, v18
	v_add_f32_e32 v23, 1.0, v23
	v_add_f32_e32 v24, 1.0, v24
	v_add_f32_e32 v4, 1.0, v4
	v_add_f32_e32 v0, 1.0, v0
	v_add_f32_e32 v1, 1.0, v1
	v_fma_f32 v70, v70, s31, 0.5
	v_fma_f32 v66, v66, s31, 0.5
	v_rcp_f32_e32 v23, v23
	v_rcp_f32_e32 v24, v24
	v_rcp_f32_e32 v4, v4
	v_rcp_f32_e32 v0, v0
	v_rcp_f32_e32 v1, v1
	v_add_f32_e32 v5, 1.0, v5
	v_add_f32_e32 v2, 1.0, v2
	v_add_f32_e32 v6, 1.0, v6
	v_add_f32_e32 v3, 1.0, v3
	v_max_f32_e32 v70, 1.0, v70
	v_max_f32_e32 v66, 1.0, v66
	v_fma_f32 v71, v71, s31, 0.5
	v_fma_f32 v72, v72, s31, 0.5
	v_fma_f32 v54, v54, s31, 0.5
	v_fma_f32 v50, v50, s31, 0.5
	v_rcp_f32_e32 v5, v5
	v_rcp_f32_e32 v2, v2
	v_rcp_f32_e32 v6, v6
	v_rcp_f32_e32 v3, v3
	v_cvt_u32_f32_e32 v70, v70
	v_cvt_u32_f32_e32 v66, v66
	v_max_f32_e32 v71, 1.0, v71
	v_max_f32_e32 v72, 1.0, v72
	v_max_f32_e32 v54, 1.0, v54
	v_max_f32_e32 v50, 1.0, v50
	v_fma_f32 v55, v55, s31, 0.5
	v_fma_f32 v56, v56, s31, 0.5
	v_fma_f32 v38, v38, s31, 0.5
	v_fma_f32 v34, v34, s31, 0.5
	v_cvt_u32_f32_sdwa v71, v71 dst_sel:WORD_1 dst_unused:UNUSED_PAD src0_sel:DWORD
	v_cvt_u32_f32_sdwa v72, v72 dst_sel:BYTE_3 dst_unused:UNUSED_PAD src0_sel:DWORD
	v_cvt_u32_f32_e32 v54, v54
	v_cvt_u32_f32_e32 v50, v50
	v_max_f32_e32 v55, 1.0, v55
	v_max_f32_e32 v56, 1.0, v56
	v_max_f32_e32 v38, 1.0, v38
	v_max_f32_e32 v34, 1.0, v34
	v_fma_f32 v39, v39, s31, 0.5
	v_fma_f32 v40, v40, s31, 0.5
	v_fma_f32 v22, v22, s31, 0.5
	v_fma_f32 v18, v18, s31, 0.5
	v_cvt_u32_f32_sdwa v55, v55 dst_sel:WORD_1 dst_unused:UNUSED_PAD src0_sel:DWORD
	v_cvt_u32_f32_sdwa v56, v56 dst_sel:BYTE_3 dst_unused:UNUSED_PAD src0_sel:DWORD
	v_cvt_u32_f32_e32 v38, v38
	v_cvt_u32_f32_e32 v34, v34
	v_max_f32_e32 v39, 1.0, v39
	v_max_f32_e32 v40, 1.0, v40
	v_max_f32_e32 v22, 1.0, v22
	v_max_f32_e32 v18, 1.0, v18
	v_fma_f32 v23, v23, s31, 0.5
	v_fma_f32 v24, v24, s31, 0.5
	v_fma_f32 v4, v4, s31, 0.5
	v_fma_f32 v0, v0, s31, 0.5
	v_fma_f32 v1, v1, s31, 0.5
	v_cvt_u32_f32_sdwa v39, v39 dst_sel:WORD_1 dst_unused:UNUSED_PAD src0_sel:DWORD
	v_cvt_u32_f32_sdwa v40, v40 dst_sel:BYTE_3 dst_unused:UNUSED_PAD src0_sel:DWORD
	v_cvt_u32_f32_e32 v22, v22
	v_cvt_u32_f32_e32 v18, v18
	v_max_f32_e32 v23, 1.0, v23
	v_max_f32_e32 v24, 1.0, v24
	v_max_f32_e32 v4, 1.0, v4
	v_max_f32_e32 v0, 1.0, v0
	v_max_f32_e32 v1, 1.0, v1
	v_fma_f32 v5, v5, s31, 0.5
	v_fma_f32 v2, v2, s31, 0.5
	v_fma_f32 v6, v6, s31, 0.5
	v_fma_f32 v3, v3, s31, 0.5
	v_lshl_or_b32 v66, v66, 8, v70
	v_cvt_u32_f32_sdwa v23, v23 dst_sel:WORD_1 dst_unused:UNUSED_PAD src0_sel:DWORD
	v_cvt_u32_f32_sdwa v24, v24 dst_sel:BYTE_3 dst_unused:UNUSED_PAD src0_sel:DWORD
	v_cvt_u32_f32_e32 v4, v4
	v_cvt_u32_f32_e32 v0, v0
	v_cvt_u32_f32_e32 v1, v1
	v_max_f32_e32 v5, 1.0, v5
	v_max_f32_e32 v2, 1.0, v2
	v_max_f32_e32 v6, 1.0, v6
	v_max_f32_e32 v3, 1.0, v3
	v_or3_b32 v66, v66, v71, v72
	s_mov_b64 s[12:13], 0x80000
	v_lshl_or_b32 v50, v50, 8, v54
	v_cvt_u32_f32_sdwa v5, v5 dst_sel:WORD_1 dst_unused:UNUSED_PAD src0_sel:DWORD
	v_cvt_u32_f32_sdwa v2, v2 dst_sel:WORD_1 dst_unused:UNUSED_PAD src0_sel:DWORD
	v_cvt_u32_f32_sdwa v6, v6 dst_sel:BYTE_3 dst_unused:UNUSED_PAD src0_sel:DWORD
	v_cvt_u32_f32_sdwa v3, v3 dst_sel:BYTE_3 dst_unused:UNUSED_PAD src0_sel:DWORD
	global_store_dwordx2 v[82:83], v[66:67], off offset:128
	v_lshl_add_u64 v[66:67], v[140:141], 0, s[12:13]
	v_or3_b32 v50, v50, v55, v56
	s_mov_b64 s[12:13], 0x90000
	v_lshl_or_b32 v34, v34, 8, v38
	global_store_dwordx2 v[66:67], v[50:51], off offset:128
	v_lshl_add_u64 v[50:51], v[140:141], 0, s[12:13]
	v_or3_b32 v34, v34, v39, v40
	s_mov_b64 s[12:13], 0xa0000
	v_lshl_or_b32 v18, v18, 8, v22
	global_store_dwordx2 v[50:51], v[34:35], off offset:128
	v_lshl_add_u64 v[34:35], v[140:141], 0, s[12:13]
	v_or3_b32 v18, v18, v23, v24
	s_mov_b64 s[12:13], 0xb0000
	v_lshl_or_b32 v0, v0, 8, v4
	v_lshl_or_b32 v1, v1, 8, v8
	global_store_dwordx2 v[34:35], v[18:19], off offset:128
	v_lshl_add_u64 v[18:19], v[140:141], 0, s[12:13]
	v_or3_b32 v0, v0, v5, v6
	v_or3_b32 v1, v1, v2, v3
	s_and_b64 vcc, exec, s[0:1]
	s_mov_b64 s[12:13], s[8:9]
	global_store_dwordx2 v[18:19], v[0:1], off offset:128
	s_cbranch_vccz .LBB0_955
	s_waitcnt vmcnt(0)
	s_cmpk_gt_u32 s34, 0xff
	s_cbranch_scc1 .LBB0_966
	s_barrier

.LBB0_1167:
	s_add_u32 s39, s12, 0x100
	s_addc_u32 s40, s13, 0
	s_mov_b32 s41, -2
	v_readfirstlane_b32 s98, v232
	s_cmp_ge_u32 s98, 0x100
	s_cbranch_scc0 .Lsp_sk2
	s_setprio 1
.Lsp_sk2:
.LBB0_1168:
	s_add_u32 s12, s10, 0x100
	s_addc_u32 s13, s11, 0
	s_add_i32 s51, 0, 0x10000
	v_add_u32_e32 v16, s51, v250
	ds_read_b128 v[132:135], v16
	ds_read_b128 v[136:139], v16 offset:1024
	ds_read_b128 v[140:143], v16 offset:2048
	ds_read_b128 v[144:147], v16 offset:3072
	s_cmp_eq_u32 s41, 4
	s_cselect_b32 s23, s5, s13
	s_cselect_b32 s22, s4, s12
	s_cselect_b32 s17, s7, s40
	s_cselect_b32 s16, s6, s39
	v_lshl_add_u64 v[18:19], s[10:11], 0, v[172:173]
	s_add_i32 m0, s43, 0xc000
	ds_read_b128 v[148:151], v233
	ds_read_b128 v[152:155], v233 offset:1024
	ds_read_b128 v[156:159], v233 offset:2048
	ds_read_b128 v[160:163], v233 offset:3072
	ds_read_b128 v[176:179], v233 offset:4096
	ds_read_b128 v[188:191], v233 offset:5120
	ds_read_b128 v[192:195], v233 offset:6144
	ds_read_b128 v[196:199], v233 offset:7168
	global_load_lds_dwordx4 v[18:19], off
	v_lshl_add_u64 v[18:19], s[10:11], 0, v[174:175]
	s_add_i32 m0, s43, 0xe000
	s_nop 0
	global_load_lds_dwordx4 v[18:19], off
	s_waitcnt lgkmcnt(8)
	s_barrier
	s_waitcnt lgkmcnt(0)
	s_waitcnt lgkmcnt(0)
	v_mfma_f32_16x16x32_bf16 v[0:3], v[132:135], v[148:151], v[0:3]
	v_mfma_f32_16x16x32_bf16 v[4:7], v[140:143], v[148:151], v[4:7]
	v_mfma_f32_16x16x32_bf16 v[8:11], v[132:135], v[156:159], v[8:11]
	v_mfma_f32_16x16x32_bf16 v[12:15], v[140:143], v[156:159], v[12:15]
	v_mfma_f32_16x16x32_bf16 v[18:21], v[132:135], v[176:179], v[20:23]
	v_mfma_f32_16x16x32_bf16 v[22:25], v[140:143], v[176:179], v[24:27]
	v_mfma_f32_16x16x32_bf16 v[28:31], v[132:135], v[192:195], v[28:31]
	v_mfma_f32_16x16x32_bf16 v[32:35], v[140:143], v[192:195], v[32:35]
	v_mfma_f32_16x16x32_bf16 v[0:3], v[136:139], v[152:155], v[0:3]
	v_mfma_f32_16x16x32_bf16 v[4:7], v[144:147], v[152:155], v[4:7]
	v_mfma_f32_16x16x32_bf16 v[8:11], v[136:139], v[160:163], v[8:11]
	v_mfma_f32_16x16x32_bf16 v[12:15], v[144:147], v[160:163], v[12:15]
	v_mfma_f32_16x16x32_bf16 v[18:21], v[136:139], v[188:191], v[18:21]
	v_mfma_f32_16x16x32_bf16 v[24:27], v[144:147], v[188:191], v[22:25]
	v_mfma_f32_16x16x32_bf16 v[28:31], v[136:139], v[196:199], v[28:31]
	v_mfma_f32_16x16x32_bf16 v[32:35], v[144:147], v[196:199], v[32:35]
	s_barrier
	s_add_i32 s52, 0, 0x14000
	s_add_i32 s10, s51, s42
	v_add_u32_e32 v16, s52, v250
	v_lshl_add_u64 v[180:181], s[16:17], 0, v[166:167]
	s_mov_b32 m0, s10
	ds_read_b128 v[200:203], v16
	ds_read_b128 v[204:207], v16 offset:1024
	ds_read_b128 v[208:211], v16 offset:2048
	ds_read_b128 v[212:215], v16 offset:3072
	global_load_lds_dwordx4 v[180:181], off
	v_lshl_add_u64 v[216:217], s[16:17], 0, v[170:171]
	s_add_i32 m0, s10, 0x2000
	s_nop 0
	global_load_lds_dwordx4 v[216:217], off
	s_barrier
	s_waitcnt lgkmcnt(0)
	s_waitcnt lgkmcnt(0)
	v_mfma_f32_16x16x32_bf16 v[36:39], v[200:203], v[148:151], v[36:39]
	v_mfma_f32_16x16x32_bf16 v[40:43], v[208:211], v[148:151], v[40:43]
	v_mfma_f32_16x16x32_bf16 v[44:47], v[200:203], v[156:159], v[44:47]
	v_mfma_f32_16x16x32_bf16 v[48:51], v[208:211], v[156:159], v[48:51]
	v_mfma_f32_16x16x32_bf16 v[52:55], v[200:203], v[176:179], v[52:55]
	v_mfma_f32_16x16x32_bf16 v[56:59], v[208:211], v[176:179], v[56:59]
	v_mfma_f32_16x16x32_bf16 v[60:63], v[200:203], v[192:195], v[60:63]
	v_mfma_f32_16x16x32_bf16 v[64:67], v[208:211], v[192:195], v[64:67]
	v_mfma_f32_16x16x32_bf16 v[36:39], v[204:207], v[152:155], v[36:39]
	v_mfma_f32_16x16x32_bf16 v[40:43], v[212:215], v[152:155], v[40:43]
	v_mfma_f32_16x16x32_bf16 v[44:47], v[204:207], v[160:163], v[44:47]
	v_mfma_f32_16x16x32_bf16 v[48:51], v[212:215], v[160:163], v[48:51]
	v_mfma_f32_16x16x32_bf16 v[52:55], v[204:207], v[188:191], v[52:55]
	v_mfma_f32_16x16x32_bf16 v[56:59], v[212:215], v[188:191], v[56:59]
	v_mfma_f32_16x16x32_bf16 v[60:63], v[204:207], v[196:199], v[60:63]
	v_mfma_f32_16x16x32_bf16 v[64:67], v[212:215], v[196:199], v[64:67]
	s_mov_b32 m0, s43
	v_lshl_add_u64 v[218:219], s[22:23], 0, v[164:165]
	s_barrier
	ds_read_b128 v[148:151], v233 offset:16384
	ds_read_b128 v[152:155], v233 offset:17408
	ds_read_b128 v[156:159], v233 offset:18432
	ds_read_b128 v[160:163], v233 offset:19456
	ds_read_b128 v[176:179], v233 offset:20480
	ds_read_b128 v[188:191], v233 offset:21504
	ds_read_b128 v[192:195], v233 offset:22528
	ds_read_b128 v[196:199], v233 offset:23552
	global_load_lds_dwordx4 v[218:219], off
	v_lshl_add_u64 v[220:221], s[22:23], 0, v[168:169]
	s_mov_b32 m0, s44
	s_nop 0
	global_load_lds_dwordx4 v[220:221], off
	s_barrier
	s_waitcnt lgkmcnt(0)
	s_waitcnt lgkmcnt(0)
	v_mfma_f32_16x16x32_bf16 v[68:71], v[132:135], v[148:151], v[68:71]
	v_mfma_f32_16x16x32_bf16 v[72:75], v[140:143], v[148:151], v[72:75]
	v_mfma_f32_16x16x32_bf16 v[76:79], v[132:135], v[156:159], v[76:79]
	v_mfma_f32_16x16x32_bf16 v[80:83], v[140:143], v[156:159], v[80:83]
	v_mfma_f32_16x16x32_bf16 v[84:87], v[132:135], v[176:179], v[84:87]
	v_mfma_f32_16x16x32_bf16 v[88:91], v[140:143], v[176:179], v[88:91]
	v_mfma_f32_16x16x32_bf16 v[92:95], v[132:135], v[192:195], v[92:95]
	v_mfma_f32_16x16x32_bf16 v[96:99], v[140:143], v[192:195], v[96:99]
	v_mfma_f32_16x16x32_bf16 v[68:71], v[136:139], v[152:155], v[68:71]
	v_mfma_f32_16x16x32_bf16 v[72:75], v[144:147], v[152:155], v[72:75]
	v_mfma_f32_16x16x32_bf16 v[76:79], v[136:139], v[160:163], v[76:79]
	v_mfma_f32_16x16x32_bf16 v[80:83], v[144:147], v[160:163], v[80:83]
	v_mfma_f32_16x16x32_bf16 v[84:87], v[136:139], v[188:191], v[84:87]
	v_mfma_f32_16x16x32_bf16 v[88:91], v[144:147], v[188:191], v[88:91]
	v_mfma_f32_16x16x32_bf16 v[92:95], v[136:139], v[196:199], v[92:95]
	v_mfma_f32_16x16x32_bf16 v[96:99], v[144:147], v[196:199], v[96:99]
	s_barrier
	s_add_u32 s10, s16, 0x80000
	s_addc_u32 s11, s17, 0
	s_add_i32 s51, s52, s42
	v_lshl_add_u64 v[22:23], s[10:11], 0, v[166:167]
	s_mov_b32 m0, s51
	s_nop 0
	global_load_lds_dwordx4 v[22:23], off
	v_lshl_add_u64 v[22:23], s[10:11], 0, v[170:171]
	s_add_i32 m0, s51, 0x2000
	s_nop 0
	global_load_lds_dwordx4 v[22:23], off
	s_waitcnt vmcnt(6)
	s_barrier
	v_mfma_f32_16x16x32_bf16 v[100:103], v[200:203], v[148:151], v[100:103]
	v_mfma_f32_16x16x32_bf16 v[104:107], v[208:211], v[148:151], v[104:107]
	v_mfma_f32_16x16x32_bf16 v[108:111], v[200:203], v[156:159], v[108:111]
	v_mfma_f32_16x16x32_bf16 v[112:115], v[208:211], v[156:159], v[112:115]
	v_mfma_f32_16x16x32_bf16 v[116:119], v[200:203], v[176:179], v[116:119]
	v_mfma_f32_16x16x32_bf16 v[120:123], v[208:211], v[176:179], v[120:123]
	v_mfma_f32_16x16x32_bf16 v[124:127], v[200:203], v[192:195], v[124:127]
	v_mfma_f32_16x16x32_bf16 v[128:131], v[208:211], v[192:195], v[128:131]
	v_mfma_f32_16x16x32_bf16 v[100:103], v[204:207], v[152:155], v[100:103]
	v_mfma_f32_16x16x32_bf16 v[104:107], v[212:215], v[152:155], v[104:107]
	v_mfma_f32_16x16x32_bf16 v[108:111], v[204:207], v[160:163], v[108:111]
	v_mfma_f32_16x16x32_bf16 v[112:115], v[212:215], v[160:163], v[112:115]
	v_mfma_f32_16x16x32_bf16 v[116:119], v[204:207], v[188:191], v[116:119]
	v_mfma_f32_16x16x32_bf16 v[120:123], v[212:215], v[188:191], v[120:123]
	v_mfma_f32_16x16x32_bf16 v[124:127], v[204:207], v[196:199], v[124:127]
	v_mfma_f32_16x16x32_bf16 v[128:131], v[212:215], v[196:199], v[128:131]
	s_add_i32 s51, 0, 0x18000
	v_add_u32_e32 v16, s51, v250
	s_barrier
	ds_read_b128 v[132:135], v16
	ds_read_b128 v[136:139], v16 offset:1024
	ds_read_b128 v[140:143], v16 offset:2048
	ds_read_b128 v[144:147], v16 offset:3072
	s_add_u32 s10, s22, 0x1c0000
	s_addc_u32 s11, s23, 0
	s_mov_b32 m0, s45
	v_lshl_add_u64 v[22:23], s[10:11], 0, v[164:165]
	ds_read_b128 v[148:151], v233 offset:32768
	ds_read_b128 v[152:155], v233 offset:33792
	ds_read_b128 v[156:159], v233 offset:34816
	ds_read_b128 v[160:163], v233 offset:35840
	ds_read_b128 v[176:179], v233 offset:36864
	ds_read_b128 v[188:191], v233 offset:37888
	ds_read_b128 v[192:195], v233 offset:38912
	ds_read_b128 v[196:199], v233 offset:39936
	global_load_lds_dwordx4 v[22:23], off
	v_lshl_add_u64 v[22:23], s[10:11], 0, v[168:169]
	s_mov_b32 m0, s46
	s_nop 0
	global_load_lds_dwordx4 v[22:23], off
	s_waitcnt lgkmcnt(8)
	s_barrier
	s_waitcnt lgkmcnt(0)
	s_waitcnt lgkmcnt(0)
	v_mfma_f32_16x16x32_bf16 v[0:3], v[132:135], v[148:151], v[0:3]
	v_mfma_f32_16x16x32_bf16 v[4:7], v[140:143], v[148:151], v[4:7]
	v_mfma_f32_16x16x32_bf16 v[8:11], v[132:135], v[156:159], v[8:11]
	v_mfma_f32_16x16x32_bf16 v[12:15], v[140:143], v[156:159], v[12:15]
	v_mfma_f32_16x16x32_bf16 v[18:21], v[132:135], v[176:179], v[18:21]
	v_mfma_f32_16x16x32_bf16 v[24:27], v[140:143], v[176:179], v[24:27]
	v_mfma_f32_16x16x32_bf16 v[28:31], v[132:135], v[192:195], v[28:31]
	v_mfma_f32_16x16x32_bf16 v[32:35], v[140:143], v[192:195], v[32:35]
	v_mfma_f32_16x16x32_bf16 v[0:3], v[136:139], v[152:155], v[0:3]
	v_mfma_f32_16x16x32_bf16 v[4:7], v[144:147], v[152:155], v[4:7]
	v_mfma_f32_16x16x32_bf16 v[8:11], v[136:139], v[160:163], v[8:11]
	v_mfma_f32_16x16x32_bf16 v[12:15], v[144:147], v[160:163], v[12:15]
	v_mfma_f32_16x16x32_bf16 v[20:23], v[136:139], v[188:191], v[18:21]
	v_mfma_f32_16x16x32_bf16 v[24:27], v[144:147], v[188:191], v[24:27]
	v_mfma_f32_16x16x32_bf16 v[28:31], v[136:139], v[196:199], v[28:31]
	v_mfma_f32_16x16x32_bf16 v[32:35], v[144:147], v[196:199], v[32:35]
	s_barrier
	s_add_i32 s22, 0, 0x1c000
	s_add_i32 s10, s51, s42
	v_add_u32_e32 v16, s22, v250
	v_lshl_add_u64 v[18:19], v[180:181], 0, s[14:15]
	s_mov_b32 m0, s10
	ds_read_b128 v[200:203], v16
	ds_read_b128 v[204:207], v16 offset:1024
	ds_read_b128 v[208:211], v16 offset:2048
	ds_read_b128 v[212:215], v16 offset:3072
	global_load_lds_dwordx4 v[18:19], off
	v_lshl_add_u64 v[18:19], v[216:217], 0, s[14:15]
	s_add_i32 m0, s10, 0x2000
	s_nop 0
	global_load_lds_dwordx4 v[18:19], off
	s_barrier
	s_waitcnt lgkmcnt(0)
	s_waitcnt lgkmcnt(0)
	v_mfma_f32_16x16x32_bf16 v[36:39], v[200:203], v[148:151], v[36:39]
	v_mfma_f32_16x16x32_bf16 v[40:43], v[208:211], v[148:151], v[40:43]
	v_mfma_f32_16x16x32_bf16 v[44:47], v[200:203], v[156:159], v[44:47]
	v_mfma_f32_16x16x32_bf16 v[48:51], v[208:211], v[156:159], v[48:51]
	v_mfma_f32_16x16x32_bf16 v[52:55], v[200:203], v[176:179], v[52:55]
	v_mfma_f32_16x16x32_bf16 v[56:59], v[208:211], v[176:179], v[56:59]
	v_mfma_f32_16x16x32_bf16 v[60:63], v[200:203], v[192:195], v[60:63]
	v_mfma_f32_16x16x32_bf16 v[64:67], v[208:211], v[192:195], v[64:67]
	v_mfma_f32_16x16x32_bf16 v[36:39], v[204:207], v[152:155], v[36:39]
	v_mfma_f32_16x16x32_bf16 v[40:43], v[212:215], v[152:155], v[40:43]
	v_mfma_f32_16x16x32_bf16 v[44:47], v[204:207], v[160:163], v[44:47]
	v_mfma_f32_16x16x32_bf16 v[48:51], v[212:215], v[160:163], v[48:51]
	v_mfma_f32_16x16x32_bf16 v[52:55], v[204:207], v[188:191], v[52:55]
	v_mfma_f32_16x16x32_bf16 v[56:59], v[212:215], v[188:191], v[56:59]
	v_mfma_f32_16x16x32_bf16 v[60:63], v[204:207], v[196:199], v[60:63]
	v_mfma_f32_16x16x32_bf16 v[64:67], v[212:215], v[196:199], v[64:67]
	s_mov_b32 m0, s47
	v_lshl_add_u64 v[18:19], v[218:219], 0, s[14:15]
	s_barrier
	ds_read_b128 v[148:151], v233 offset:49152
	ds_read_b128 v[152:155], v233 offset:50176
	ds_read_b128 v[156:159], v233 offset:51200
	ds_read_b128 v[160:163], v233 offset:52224
	ds_read_b128 v[176:179], v233 offset:53248
	ds_read_b128 v[188:191], v233 offset:54272
	ds_read_b128 v[192:195], v233 offset:55296
	ds_read_b128 v[196:199], v233 offset:56320
	global_load_lds_dwordx4 v[18:19], off
	v_lshl_add_u64 v[18:19], v[220:221], 0, s[14:15]
	s_mov_b32 m0, s48
	s_nop 0
	global_load_lds_dwordx4 v[18:19], off
	s_barrier
	s_waitcnt lgkmcnt(0)
	s_waitcnt lgkmcnt(0)
	v_mfma_f32_16x16x32_bf16 v[68:71], v[132:135], v[148:151], v[68:71]
	v_mfma_f32_16x16x32_bf16 v[72:75], v[140:143], v[148:151], v[72:75]
	v_mfma_f32_16x16x32_bf16 v[76:79], v[132:135], v[156:159], v[76:79]
	v_mfma_f32_16x16x32_bf16 v[80:83], v[140:143], v[156:159], v[80:83]
	v_mfma_f32_16x16x32_bf16 v[84:87], v[132:135], v[176:179], v[84:87]
	v_mfma_f32_16x16x32_bf16 v[88:91], v[140:143], v[176:179], v[88:91]
	v_mfma_f32_16x16x32_bf16 v[92:95], v[132:135], v[192:195], v[92:95]
	v_mfma_f32_16x16x32_bf16 v[96:99], v[140:143], v[192:195], v[96:99]
	v_mfma_f32_16x16x32_bf16 v[68:71], v[136:139], v[152:155], v[68:71]
	v_mfma_f32_16x16x32_bf16 v[72:75], v[144:147], v[152:155], v[72:75]
	v_mfma_f32_16x16x32_bf16 v[76:79], v[136:139], v[160:163], v[76:79]
	v_mfma_f32_16x16x32_bf16 v[80:83], v[144:147], v[160:163], v[80:83]
	v_mfma_f32_16x16x32_bf16 v[84:87], v[136:139], v[188:191], v[84:87]
	v_mfma_f32_16x16x32_bf16 v[88:91], v[144:147], v[188:191], v[88:91]
	v_mfma_f32_16x16x32_bf16 v[92:95], v[136:139], v[196:199], v[92:95]
	v_mfma_f32_16x16x32_bf16 v[96:99], v[144:147], v[196:199], v[96:99]
	s_barrier
	s_add_u32 s10, s16, 0x80080
	s_addc_u32 s11, s17, 0
	s_add_i32 s16, s22, s42
	v_lshl_add_u64 v[18:19], s[10:11], 0, v[166:167]
	s_mov_b32 m0, s16
	s_nop 0
	global_load_lds_dwordx4 v[18:19], off
	v_lshl_add_u64 v[18:19], s[10:11], 0, v[170:171]
	s_add_i32 m0, s16, 0x2000
	s_nop 0
	global_load_lds_dwordx4 v[18:19], off
	s_waitcnt vmcnt(6)
	s_barrier
	v_mfma_f32_16x16x32_bf16 v[100:103], v[200:203], v[148:151], v[100:103]
	v_mfma_f32_16x16x32_bf16 v[104:107], v[208:211], v[148:151], v[104:107]
	v_mfma_f32_16x16x32_bf16 v[108:111], v[200:203], v[156:159], v[108:111]
	v_mfma_f32_16x16x32_bf16 v[112:115], v[208:211], v[156:159], v[112:115]
	v_mfma_f32_16x16x32_bf16 v[116:119], v[200:203], v[176:179], v[116:119]
	v_mfma_f32_16x16x32_bf16 v[120:123], v[208:211], v[176:179], v[120:123]
	v_mfma_f32_16x16x32_bf16 v[124:127], v[200:203], v[192:195], v[124:127]
	v_mfma_f32_16x16x32_bf16 v[128:131], v[208:211], v[192:195], v[128:131]
	v_mfma_f32_16x16x32_bf16 v[100:103], v[204:207], v[152:155], v[100:103]
	v_mfma_f32_16x16x32_bf16 v[104:107], v[212:215], v[152:155], v[104:107]
	v_mfma_f32_16x16x32_bf16 v[108:111], v[204:207], v[160:163], v[108:111]
	v_mfma_f32_16x16x32_bf16 v[112:115], v[212:215], v[160:163], v[112:115]
	v_mfma_f32_16x16x32_bf16 v[116:119], v[204:207], v[188:191], v[116:119]
	v_mfma_f32_16x16x32_bf16 v[120:123], v[212:215], v[188:191], v[120:123]
	v_mfma_f32_16x16x32_bf16 v[124:127], v[204:207], v[196:199], v[124:127]
	v_mfma_f32_16x16x32_bf16 v[128:131], v[212:215], v[196:199], v[128:131]
	s_add_i32 s41, s41, 2
	s_add_u32 s39, s39, 0x100
	s_addc_u32 s40, s40, 0
	s_cmp_gt_u32 s41, 5
	s_mov_b64 s[10:11], s[12:13]
	s_barrier
	s_cbranch_scc0 .LBB0_1168
	s_setprio 0
	s_and_b32 s12, s25, 1
	s_bitcmp1_b32 s25, 0
	s_cselect_b64 s[10:11], -1, 0
	s_lshl_b32 s22, s25, 10
	v_lshl_add_u32 v18, s38, 8, v183
	v_lshl_or_b32 v176, s33, 8, v251
	s_ashr_i32 s23, s22, 31
	s_cmp_eq_u32 s12, 0
	v_ashrrev_i32_e32 v177, 31, v176
	s_mov_b64 s[12:13], -1
	v_ashrrev_i32_e32 v19, 31, v18
	s_cbranch_scc0 .LBB0_1172
	s_and_b64 vcc, exec, s[12:13]
	s_cbranch_vccnz .LBB0_1287

.LBB0_1374:
	s_add_u32 s5, s12, 0x100
	v_mov_b32_e32 v0, 0
	s_addc_u32 s48, s13, 0
	s_mov_b32 s49, -2
	v_mov_b32_e32 v1, v0
	v_mov_b32_e32 v2, v0
	v_mov_b32_e32 v3, v0
	v_mov_b32_e32 v4, v0
	v_mov_b32_e32 v5, v0
	v_mov_b32_e32 v6, v0
	v_mov_b32_e32 v7, v0
	v_mov_b32_e32 v12, v0
	v_mov_b32_e32 v13, v0
	v_mov_b32_e32 v14, v0
	v_mov_b32_e32 v15, v0
	v_mov_b32_e32 v22, v0
	v_mov_b32_e32 v23, v0
	v_mov_b32_e32 v24, v0
	v_mov_b32_e32 v25, v0
	v_mov_b32_e32 v30, v0
	v_mov_b32_e32 v31, v0
	v_mov_b32_e32 v32, v0
	v_mov_b32_e32 v33, v0
	v_mov_b32_e32 v38, v0
	v_mov_b32_e32 v39, v0
	v_mov_b32_e32 v40, v0
	v_mov_b32_e32 v41, v0
	v_mov_b32_e32 v46, v0
	v_mov_b32_e32 v47, v0
	v_mov_b32_e32 v48, v0
	v_mov_b32_e32 v49, v0
	v_mov_b32_e32 v54, v0
	v_mov_b32_e32 v55, v0
	v_mov_b32_e32 v56, v0
	v_mov_b32_e32 v57, v0
	v_mov_b32_e32 v8, v0
	v_mov_b32_e32 v9, v0
	v_mov_b32_e32 v10, v0
	v_mov_b32_e32 v11, v0
	v_mov_b32_e32 v18, v0
	v_mov_b32_e32 v19, v0
	v_mov_b32_e32 v20, v0
	v_mov_b32_e32 v21, v0
	v_mov_b32_e32 v26, v0
	v_mov_b32_e32 v27, v0
	v_mov_b32_e32 v28, v0
	v_mov_b32_e32 v29, v0
	v_mov_b32_e32 v34, v0
	v_mov_b32_e32 v35, v0
	v_mov_b32_e32 v36, v0
	v_mov_b32_e32 v37, v0
	v_mov_b32_e32 v42, v0
	v_mov_b32_e32 v43, v0
	v_mov_b32_e32 v44, v0
	v_mov_b32_e32 v45, v0
	v_mov_b32_e32 v50, v0
	v_mov_b32_e32 v51, v0
	v_mov_b32_e32 v52, v0
	v_mov_b32_e32 v53, v0
	v_mov_b32_e32 v58, v0
	v_mov_b32_e32 v59, v0
	v_mov_b32_e32 v60, v0
	v_mov_b32_e32 v61, v0
	v_mov_b32_e32 v62, v0
	v_mov_b32_e32 v63, v0
	v_mov_b32_e32 v64, v0
	v_mov_b32_e32 v65, v0
	v_mov_b32_e32 v66, v0
	v_mov_b32_e32 v67, v0
	v_mov_b32_e32 v68, v0
	v_mov_b32_e32 v69, v0
	v_mov_b32_e32 v70, v0
	v_mov_b32_e32 v71, v0
	v_mov_b32_e32 v72, v0
	v_mov_b32_e32 v73, v0
	v_mov_b32_e32 v78, v0
	v_mov_b32_e32 v79, v0
	v_mov_b32_e32 v80, v0
	v_mov_b32_e32 v81, v0
	v_mov_b32_e32 v86, v0
	v_mov_b32_e32 v87, v0
	v_mov_b32_e32 v88, v0
	v_mov_b32_e32 v89, v0
	v_mov_b32_e32 v94, v0
	v_mov_b32_e32 v95, v0
	v_mov_b32_e32 v96, v0
	v_mov_b32_e32 v97, v0
	v_mov_b32_e32 v102, v0
	v_mov_b32_e32 v103, v0
	v_mov_b32_e32 v104, v0
	v_mov_b32_e32 v105, v0
	v_mov_b32_e32 v114, v0
	v_mov_b32_e32 v115, v0
	v_mov_b32_e32 v116, v0
	v_mov_b32_e32 v117, v0
	v_mov_b32_e32 v118, v0
	v_mov_b32_e32 v119, v0
	v_mov_b32_e32 v120, v0
	v_mov_b32_e32 v121, v0
	v_mov_b32_e32 v74, v0
	v_mov_b32_e32 v75, v0
	v_mov_b32_e32 v76, v0
	v_mov_b32_e32 v77, v0
	v_mov_b32_e32 v82, v0
	v_mov_b32_e32 v83, v0
	v_mov_b32_e32 v84, v0
	v_mov_b32_e32 v85, v0
	v_mov_b32_e32 v90, v0
	v_mov_b32_e32 v91, v0
	v_mov_b32_e32 v92, v0
	v_mov_b32_e32 v93, v0
	v_mov_b32_e32 v98, v0
	v_mov_b32_e32 v99, v0
	v_mov_b32_e32 v100, v0
	v_mov_b32_e32 v101, v0
	v_mov_b32_e32 v106, v0
	v_mov_b32_e32 v107, v0
	v_mov_b32_e32 v108, v0
	v_mov_b32_e32 v109, v0
	v_mov_b32_e32 v110, v0
	v_mov_b32_e32 v111, v0
	v_mov_b32_e32 v112, v0
	v_mov_b32_e32 v113, v0
	v_mov_b32_e32 v122, v0
	v_mov_b32_e32 v123, v0
	v_mov_b32_e32 v124, v0
	v_mov_b32_e32 v125, v0
	v_mov_b32_e32 v126, v0
	v_mov_b32_e32 v127, v0
	v_mov_b32_e32 v128, v0
	v_mov_b32_e32 v129, v0
	v_readfirstlane_b32 s98, v232
	s_cmp_ge_u32 s98, 0x100
	s_cbranch_scc0 .Lsp_sk3
	s_setprio 1
.Lsp_sk3:
.LBB0_1375:
	s_add_u32 s12, s10, 0x100
	s_addc_u32 s13, s11, 0
	s_add_i32 s50, 0, 0x10000
	v_add_u32_e32 v152, s50, v177
	ds_read_b128 v[140:143], v152
	ds_read_b128 v[144:147], v152 offset:1024
	ds_read_b128 v[148:151], v152 offset:2048
	ds_read_b128 v[152:155], v152 offset:3072
	s_cmp_eq_u32 s49, 12
	s_cselect_b32 s23, s7, s13
	s_cselect_b32 s22, s6, s12
	s_cselect_b32 s17, s9, s48
	s_cselect_b32 s16, s8, s5
	v_lshl_add_u64 v[198:199], s[10:11], 0, v[136:137]
	s_add_i32 m0, s34, 0xc000
	ds_read_b128 v[156:159], v188
	ds_read_b128 v[160:163], v188 offset:1024
	ds_read_b128 v[164:167], v188 offset:2048
	ds_read_b128 v[168:171], v188 offset:3072
	ds_read_b128 v[172:175], v188 offset:4096
	ds_read_b128 v[178:181], v188 offset:5120
	ds_read_b128 v[190:193], v188 offset:6144
	ds_read_b128 v[194:197], v188 offset:7168
	global_load_lds_dwordx4 v[198:199], off
	v_lshl_add_u64 v[198:199], s[10:11], 0, v[138:139]
	s_add_i32 m0, s34, 0xe000
	s_nop 0
	global_load_lds_dwordx4 v[198:199], off
	s_waitcnt lgkmcnt(8)
	s_barrier
	s_waitcnt lgkmcnt(0)
	s_waitcnt lgkmcnt(0)
	v_mfma_f32_16x16x32_bf16 v[126:129], v[140:143], v[156:159], v[126:129]
	v_mfma_f32_16x16x32_bf16 v[122:125], v[148:151], v[156:159], v[122:125]
	v_mfma_f32_16x16x32_bf16 v[110:113], v[140:143], v[164:167], v[110:113]
	v_mfma_f32_16x16x32_bf16 v[106:109], v[148:151], v[164:167], v[106:109]
	v_mfma_f32_16x16x32_bf16 v[98:101], v[140:143], v[172:175], v[98:101]
	v_mfma_f32_16x16x32_bf16 v[90:93], v[148:151], v[172:175], v[90:93]
	v_mfma_f32_16x16x32_bf16 v[82:85], v[140:143], v[190:193], v[82:85]
	v_mfma_f32_16x16x32_bf16 v[74:77], v[148:151], v[190:193], v[74:77]
	v_mfma_f32_16x16x32_bf16 v[126:129], v[144:147], v[160:163], v[126:129]
	v_mfma_f32_16x16x32_bf16 v[122:125], v[152:155], v[160:163], v[122:125]
	v_mfma_f32_16x16x32_bf16 v[110:113], v[144:147], v[168:171], v[110:113]
	v_mfma_f32_16x16x32_bf16 v[106:109], v[152:155], v[168:171], v[106:109]
	v_mfma_f32_16x16x32_bf16 v[98:101], v[144:147], v[178:181], v[98:101]
	v_mfma_f32_16x16x32_bf16 v[90:93], v[152:155], v[178:181], v[90:93]
	v_mfma_f32_16x16x32_bf16 v[82:85], v[144:147], v[194:197], v[82:85]
	v_mfma_f32_16x16x32_bf16 v[74:77], v[152:155], v[194:197], v[74:77]
	s_barrier
	s_add_i32 s51, 0, 0x14000
	s_add_i32 s10, s50, s33
	v_add_u32_e32 v189, s51, v177
	v_lshl_add_u64 v[214:215], s[16:17], 0, v[16:17]
	s_mov_b32 m0, s10
	ds_read_b128 v[198:201], v189
	ds_read_b128 v[202:205], v189 offset:1024
	ds_read_b128 v[206:209], v189 offset:2048
	ds_read_b128 v[210:213], v189 offset:3072
	global_load_lds_dwordx4 v[214:215], off
	v_lshl_add_u64 v[216:217], s[16:17], 0, v[134:135]
	s_add_i32 m0, s10, 0x2000
	s_nop 0
	global_load_lds_dwordx4 v[216:217], off
	s_barrier
	s_waitcnt lgkmcnt(0)
	s_waitcnt lgkmcnt(0)
	v_mfma_f32_16x16x32_bf16 v[118:121], v[198:201], v[156:159], v[118:121]
	v_mfma_f32_16x16x32_bf16 v[114:117], v[206:209], v[156:159], v[114:117]
	v_mfma_f32_16x16x32_bf16 v[102:105], v[198:201], v[164:167], v[102:105]
	v_mfma_f32_16x16x32_bf16 v[94:97], v[206:209], v[164:167], v[94:97]
	v_mfma_f32_16x16x32_bf16 v[86:89], v[198:201], v[172:175], v[86:89]
	v_mfma_f32_16x16x32_bf16 v[78:81], v[206:209], v[172:175], v[78:81]
	v_mfma_f32_16x16x32_bf16 v[70:73], v[198:201], v[190:193], v[70:73]
	v_mfma_f32_16x16x32_bf16 v[66:69], v[206:209], v[190:193], v[66:69]
	v_mfma_f32_16x16x32_bf16 v[118:121], v[202:205], v[160:163], v[118:121]
	v_mfma_f32_16x16x32_bf16 v[114:117], v[210:213], v[160:163], v[114:117]
	v_mfma_f32_16x16x32_bf16 v[102:105], v[202:205], v[168:171], v[102:105]
	v_mfma_f32_16x16x32_bf16 v[94:97], v[210:213], v[168:171], v[94:97]
	v_mfma_f32_16x16x32_bf16 v[86:89], v[202:205], v[178:181], v[86:89]
	v_mfma_f32_16x16x32_bf16 v[78:81], v[210:213], v[178:181], v[78:81]
	v_mfma_f32_16x16x32_bf16 v[70:73], v[202:205], v[194:197], v[70:73]
	v_mfma_f32_16x16x32_bf16 v[66:69], v[210:213], v[194:197], v[66:69]
	s_mov_b32 m0, s34
	v_lshl_add_u64 v[218:219], s[22:23], 0, v[130:131]
	s_barrier
	ds_read_b128 v[156:159], v188 offset:16384
	ds_read_b128 v[160:163], v188 offset:17408
	ds_read_b128 v[164:167], v188 offset:18432
	ds_read_b128 v[168:171], v188 offset:19456
	ds_read_b128 v[172:175], v188 offset:20480
	ds_read_b128 v[178:181], v188 offset:21504
	ds_read_b128 v[190:193], v188 offset:22528
	ds_read_b128 v[194:197], v188 offset:23552
	global_load_lds_dwordx4 v[218:219], off
	v_lshl_add_u64 v[220:221], s[22:23], 0, v[132:133]
	s_mov_b32 m0, s35
	s_nop 0
	global_load_lds_dwordx4 v[220:221], off
	s_barrier
	s_waitcnt lgkmcnt(0)
	s_waitcnt lgkmcnt(0)
	v_mfma_f32_16x16x32_bf16 v[62:65], v[140:143], v[156:159], v[62:65]
	v_mfma_f32_16x16x32_bf16 v[58:61], v[148:151], v[156:159], v[58:61]
	v_mfma_f32_16x16x32_bf16 v[50:53], v[140:143], v[164:167], v[50:53]
	v_mfma_f32_16x16x32_bf16 v[42:45], v[148:151], v[164:167], v[42:45]
	v_mfma_f32_16x16x32_bf16 v[34:37], v[140:143], v[172:175], v[34:37]
	v_mfma_f32_16x16x32_bf16 v[26:29], v[148:151], v[172:175], v[26:29]
	v_mfma_f32_16x16x32_bf16 v[18:21], v[140:143], v[190:193], v[18:21]
	v_mfma_f32_16x16x32_bf16 v[8:11], v[148:151], v[190:193], v[8:11]
	v_mfma_f32_16x16x32_bf16 v[62:65], v[144:147], v[160:163], v[62:65]
	v_mfma_f32_16x16x32_bf16 v[58:61], v[152:155], v[160:163], v[58:61]
	v_mfma_f32_16x16x32_bf16 v[50:53], v[144:147], v[168:171], v[50:53]
	v_mfma_f32_16x16x32_bf16 v[42:45], v[152:155], v[168:171], v[42:45]
	v_mfma_f32_16x16x32_bf16 v[34:37], v[144:147], v[178:181], v[34:37]
	v_mfma_f32_16x16x32_bf16 v[26:29], v[152:155], v[178:181], v[26:29]
	v_mfma_f32_16x16x32_bf16 v[18:21], v[144:147], v[194:197], v[18:21]
	v_mfma_f32_16x16x32_bf16 v[8:11], v[152:155], v[194:197], v[8:11]
	s_barrier
	s_add_u32 s10, s16, 0x40000
	s_addc_u32 s11, s17, 0
	s_add_i32 s50, s51, s33
	v_lshl_add_u64 v[140:141], s[10:11], 0, v[16:17]
	s_mov_b32 m0, s50
	s_nop 0
	global_load_lds_dwordx4 v[140:141], off
	v_lshl_add_u64 v[140:141], s[10:11], 0, v[134:135]
	s_add_i32 m0, s50, 0x2000
	s_nop 0
	global_load_lds_dwordx4 v[140:141], off
	s_waitcnt vmcnt(6)
	s_barrier
	v_mfma_f32_16x16x32_bf16 v[54:57], v[198:201], v[156:159], v[54:57]
	v_mfma_f32_16x16x32_bf16 v[46:49], v[206:209], v[156:159], v[46:49]
	v_mfma_f32_16x16x32_bf16 v[38:41], v[198:201], v[164:167], v[38:41]
	v_mfma_f32_16x16x32_bf16 v[30:33], v[206:209], v[164:167], v[30:33]
	v_mfma_f32_16x16x32_bf16 v[22:25], v[198:201], v[172:175], v[22:25]
	v_mfma_f32_16x16x32_bf16 v[12:15], v[206:209], v[172:175], v[12:15]
	v_mfma_f32_16x16x32_bf16 v[4:7], v[198:201], v[190:193], v[4:7]
	v_mfma_f32_16x16x32_bf16 v[0:3], v[206:209], v[190:193], v[0:3]
	v_mfma_f32_16x16x32_bf16 v[54:57], v[202:205], v[160:163], v[54:57]
	v_mfma_f32_16x16x32_bf16 v[46:49], v[210:213], v[160:163], v[46:49]
	v_mfma_f32_16x16x32_bf16 v[38:41], v[202:205], v[168:171], v[38:41]
	v_mfma_f32_16x16x32_bf16 v[30:33], v[210:213], v[168:171], v[30:33]
	v_mfma_f32_16x16x32_bf16 v[22:25], v[202:205], v[178:181], v[22:25]
	v_mfma_f32_16x16x32_bf16 v[12:15], v[210:213], v[178:181], v[12:15]
	v_mfma_f32_16x16x32_bf16 v[4:7], v[202:205], v[194:197], v[4:7]
	v_mfma_f32_16x16x32_bf16 v[0:3], v[210:213], v[194:197], v[0:3]
	s_add_i32 s50, 0, 0x18000
	v_add_u32_e32 v152, s50, v177
	s_barrier
	ds_read_b128 v[140:143], v152
	ds_read_b128 v[144:147], v152 offset:1024
	ds_read_b128 v[148:151], v152 offset:2048
	ds_read_b128 v[152:155], v152 offset:3072
	s_add_u32 s10, s22, 0x1c0000
	s_addc_u32 s11, s23, 0
	s_mov_b32 m0, s40
	v_lshl_add_u64 v[198:199], s[10:11], 0, v[130:131]
	ds_read_b128 v[156:159], v188 offset:32768
	ds_read_b128 v[160:163], v188 offset:33792
	ds_read_b128 v[164:167], v188 offset:34816
	ds_read_b128 v[168:171], v188 offset:35840
	ds_read_b128 v[172:175], v188 offset:36864
	ds_read_b128 v[178:181], v188 offset:37888
	ds_read_b128 v[190:193], v188 offset:38912
	ds_read_b128 v[194:197], v188 offset:39936
	global_load_lds_dwordx4 v[198:199], off
	v_lshl_add_u64 v[198:199], s[10:11], 0, v[132:133]
	s_mov_b32 m0, s41
	s_nop 0
	global_load_lds_dwordx4 v[198:199], off
	s_waitcnt lgkmcnt(8)
	s_barrier
	s_waitcnt lgkmcnt(0)
	s_waitcnt lgkmcnt(0)
	v_mfma_f32_16x16x32_bf16 v[126:129], v[140:143], v[156:159], v[126:129]
	v_mfma_f32_16x16x32_bf16 v[122:125], v[148:151], v[156:159], v[122:125]
	v_mfma_f32_16x16x32_bf16 v[110:113], v[140:143], v[164:167], v[110:113]
	v_mfma_f32_16x16x32_bf16 v[106:109], v[148:151], v[164:167], v[106:109]
	v_mfma_f32_16x16x32_bf16 v[98:101], v[140:143], v[172:175], v[98:101]
	v_mfma_f32_16x16x32_bf16 v[90:93], v[148:151], v[172:175], v[90:93]
	v_mfma_f32_16x16x32_bf16 v[82:85], v[140:143], v[190:193], v[82:85]
	v_mfma_f32_16x16x32_bf16 v[74:77], v[148:151], v[190:193], v[74:77]
	v_mfma_f32_16x16x32_bf16 v[126:129], v[144:147], v[160:163], v[126:129]
	v_mfma_f32_16x16x32_bf16 v[122:125], v[152:155], v[160:163], v[122:125]
	v_mfma_f32_16x16x32_bf16 v[110:113], v[144:147], v[168:171], v[110:113]
	v_mfma_f32_16x16x32_bf16 v[106:109], v[152:155], v[168:171], v[106:109]
	v_mfma_f32_16x16x32_bf16 v[98:101], v[144:147], v[178:181], v[98:101]
	v_mfma_f32_16x16x32_bf16 v[90:93], v[152:155], v[178:181], v[90:93]
	v_mfma_f32_16x16x32_bf16 v[82:85], v[144:147], v[194:197], v[82:85]
	v_mfma_f32_16x16x32_bf16 v[74:77], v[152:155], v[194:197], v[74:77]
	s_barrier
	s_add_i32 s22, 0, 0x1c000
	s_add_i32 s10, s50, s33
	v_add_u32_e32 v189, s22, v177
	v_lshl_add_u64 v[214:215], v[214:215], 0, s[14:15]
	s_mov_b32 m0, s10
	ds_read_b128 v[198:201], v189
	ds_read_b128 v[202:205], v189 offset:1024
	ds_read_b128 v[206:209], v189 offset:2048
	ds_read_b128 v[210:213], v189 offset:3072
	global_load_lds_dwordx4 v[214:215], off
	v_lshl_add_u64 v[214:215], v[216:217], 0, s[14:15]
	s_add_i32 m0, s10, 0x2000
	s_nop 0
	global_load_lds_dwordx4 v[214:215], off
	s_barrier
	s_waitcnt lgkmcnt(0)
	s_waitcnt lgkmcnt(0)
	v_mfma_f32_16x16x32_bf16 v[118:121], v[198:201], v[156:159], v[118:121]
	v_mfma_f32_16x16x32_bf16 v[114:117], v[206:209], v[156:159], v[114:117]
	v_mfma_f32_16x16x32_bf16 v[102:105], v[198:201], v[164:167], v[102:105]
	v_mfma_f32_16x16x32_bf16 v[94:97], v[206:209], v[164:167], v[94:97]
	v_mfma_f32_16x16x32_bf16 v[86:89], v[198:201], v[172:175], v[86:89]
	v_mfma_f32_16x16x32_bf16 v[78:81], v[206:209], v[172:175], v[78:81]
	v_mfma_f32_16x16x32_bf16 v[70:73], v[198:201], v[190:193], v[70:73]
	v_mfma_f32_16x16x32_bf16 v[66:69], v[206:209], v[190:193], v[66:69]
	v_mfma_f32_16x16x32_bf16 v[118:121], v[202:205], v[160:163], v[118:121]
	v_mfma_f32_16x16x32_bf16 v[114:117], v[210:213], v[160:163], v[114:117]
	v_mfma_f32_16x16x32_bf16 v[102:105], v[202:205], v[168:171], v[102:105]
	v_mfma_f32_16x16x32_bf16 v[94:97], v[210:213], v[168:171], v[94:97]
	v_mfma_f32_16x16x32_bf16 v[86:89], v[202:205], v[178:181], v[86:89]
	v_mfma_f32_16x16x32_bf16 v[78:81], v[210:213], v[178:181], v[78:81]
	v_mfma_f32_16x16x32_bf16 v[70:73], v[202:205], v[194:197], v[70:73]
	v_mfma_f32_16x16x32_bf16 v[66:69], v[210:213], v[194:197], v[66:69]
	s_mov_b32 m0, s42
	v_lshl_add_u64 v[214:215], v[218:219], 0, s[14:15]
	s_barrier
	ds_read_b128 v[156:159], v188 offset:49152
	ds_read_b128 v[160:163], v188 offset:50176
	ds_read_b128 v[164:167], v188 offset:51200
	ds_read_b128 v[168:171], v188 offset:52224
	ds_read_b128 v[172:175], v188 offset:53248
	ds_read_b128 v[178:181], v188 offset:54272
	ds_read_b128 v[190:193], v188 offset:55296
	ds_read_b128 v[194:197], v188 offset:56320
	global_load_lds_dwordx4 v[214:215], off
	v_lshl_add_u64 v[214:215], v[220:221], 0, s[14:15]
	s_mov_b32 m0, s43
	s_nop 0
	global_load_lds_dwordx4 v[214:215], off
	s_barrier
	s_waitcnt lgkmcnt(0)
	s_waitcnt lgkmcnt(0)
	v_mfma_f32_16x16x32_bf16 v[62:65], v[140:143], v[156:159], v[62:65]
	v_mfma_f32_16x16x32_bf16 v[58:61], v[148:151], v[156:159], v[58:61]
	v_mfma_f32_16x16x32_bf16 v[50:53], v[140:143], v[164:167], v[50:53]
	v_mfma_f32_16x16x32_bf16 v[42:45], v[148:151], v[164:167], v[42:45]
	v_mfma_f32_16x16x32_bf16 v[34:37], v[140:143], v[172:175], v[34:37]
	v_mfma_f32_16x16x32_bf16 v[26:29], v[148:151], v[172:175], v[26:29]
	v_mfma_f32_16x16x32_bf16 v[18:21], v[140:143], v[190:193], v[18:21]
	v_mfma_f32_16x16x32_bf16 v[8:11], v[148:151], v[190:193], v[8:11]
	v_mfma_f32_16x16x32_bf16 v[62:65], v[144:147], v[160:163], v[62:65]
	v_mfma_f32_16x16x32_bf16 v[58:61], v[152:155], v[160:163], v[58:61]
	v_mfma_f32_16x16x32_bf16 v[50:53], v[144:147], v[168:171], v[50:53]
	v_mfma_f32_16x16x32_bf16 v[42:45], v[152:155], v[168:171], v[42:45]
	v_mfma_f32_16x16x32_bf16 v[34:37], v[144:147], v[178:181], v[34:37]
	v_mfma_f32_16x16x32_bf16 v[26:29], v[152:155], v[178:181], v[26:29]
	v_mfma_f32_16x16x32_bf16 v[18:21], v[144:147], v[194:197], v[18:21]
	v_mfma_f32_16x16x32_bf16 v[8:11], v[152:155], v[194:197], v[8:11]
	s_barrier
	s_add_u32 s10, s16, 0x40080
	s_addc_u32 s11, s17, 0
	s_add_i32 s16, s22, s33
	v_lshl_add_u64 v[140:141], s[10:11], 0, v[16:17]
	s_mov_b32 m0, s16
	s_nop 0
	global_load_lds_dwordx4 v[140:141], off
	v_lshl_add_u64 v[140:141], s[10:11], 0, v[134:135]
	s_add_i32 m0, s16, 0x2000
	s_nop 0
	global_load_lds_dwordx4 v[140:141], off
	s_waitcnt vmcnt(6)
	s_barrier
	v_mfma_f32_16x16x32_bf16 v[54:57], v[198:201], v[156:159], v[54:57]
	v_mfma_f32_16x16x32_bf16 v[46:49], v[206:209], v[156:159], v[46:49]
	v_mfma_f32_16x16x32_bf16 v[38:41], v[198:201], v[164:167], v[38:41]
	v_mfma_f32_16x16x32_bf16 v[30:33], v[206:209], v[164:167], v[30:33]
	v_mfma_f32_16x16x32_bf16 v[22:25], v[198:201], v[172:175], v[22:25]
	v_mfma_f32_16x16x32_bf16 v[12:15], v[206:209], v[172:175], v[12:15]
	v_mfma_f32_16x16x32_bf16 v[4:7], v[198:201], v[190:193], v[4:7]
	v_mfma_f32_16x16x32_bf16 v[0:3], v[206:209], v[190:193], v[0:3]
	v_mfma_f32_16x16x32_bf16 v[54:57], v[202:205], v[160:163], v[54:57]
	v_mfma_f32_16x16x32_bf16 v[46:49], v[210:213], v[160:163], v[46:49]
	v_mfma_f32_16x16x32_bf16 v[38:41], v[202:205], v[168:171], v[38:41]
	v_mfma_f32_16x16x32_bf16 v[30:33], v[210:213], v[168:171], v[30:33]
	v_mfma_f32_16x16x32_bf16 v[22:25], v[202:205], v[178:181], v[22:25]
	v_mfma_f32_16x16x32_bf16 v[12:15], v[210:213], v[178:181], v[12:15]
	v_mfma_f32_16x16x32_bf16 v[4:7], v[202:205], v[194:197], v[4:7]
	v_mfma_f32_16x16x32_bf16 v[0:3], v[210:213], v[194:197], v[0:3]
	s_add_i32 s49, s49, 2
	s_add_u32 s5, s5, 0x100
	s_addc_u32 s48, s48, 0
	s_cmp_gt_u32 s49, 13
	s_mov_b64 s[10:11], s[12:13]
	s_barrier
	s_cbranch_scc0 .LBB0_1375
	s_setprio 0
	v_lshl_or_b32 v140, s47, 8, v183
	v_lshl_add_u32 v142, s46, 8, v176
	v_ashrrev_i32_e32 v141, 31, v140
	v_lshlrev_b64 v[140:141], 1, v[140:141]
	v_ashrrev_i32_e32 v143, 31, v142
	v_lshl_add_u64 v[144:145], s[54:55], 0, v[140:141]
	v_lshlrev_b64 v[146:147], 11, v[142:143]
	v_lshl_add_u64 v[146:147], v[144:145], 0, v[146:147]
	global_load_dwordx2 v[178:179], v[146:147], off
	global_load_dwordx2 v[180:181], v[146:147], off offset:32
	global_load_dwordx2 v[190:191], v[146:147], off offset:256
	global_load_dwordx2 v[192:193], v[146:147], off offset:288
	v_or_b32_e32 v172, 16, v142
	v_ashrrev_i32_e32 v173, 31, v172
	v_lshlrev_b64 v[146:147], 11, v[172:173]
	v_lshl_add_u64 v[146:147], v[144:145], 0, v[146:147]
	global_load_dwordx2 v[174:175], v[146:147], off
	global_load_dwordx2 v[170:171], v[146:147], off offset:32
	global_load_dwordx2 v[168:169], v[146:147], off offset:256
	global_load_dwordx2 v[166:167], v[146:147], off offset:288
	v_or_b32_e32 v162, 32, v142
	v_ashrrev_i32_e32 v163, 31, v162
	v_lshlrev_b64 v[146:147], 11, v[162:163]
	v_lshl_add_u64 v[146:147], v[144:145], 0, v[146:147]
	global_load_dwordx2 v[164:165], v[146:147], off
	global_load_dwordx2 v[160:161], v[146:147], off offset:32
	global_load_dwordx2 v[154:155], v[146:147], off offset:256
	global_load_dwordx2 v[150:151], v[146:147], off offset:288
	v_or_b32_e32 v156, 48, v142
	v_ashrrev_i32_e32 v157, 31, v156
	v_lshlrev_b64 v[146:147], 11, v[156:157]
	v_lshl_add_u64 v[146:147], v[144:145], 0, v[146:147]
	global_load_dwordx2 v[158:159], v[146:147], off
	global_load_dwordx2 v[152:153], v[146:147], off offset:32
	global_load_dwordx2 v[148:149], v[146:147], off offset:256
	s_nop 0
	global_load_dwordx2 v[146:147], v[146:147], off offset:288
	v_readlane_b32 s10, v254, 58
	v_lshlrev_b64 v[194:195], 12, v[142:143]
	v_readlane_b32 s11, v254, 59
	s_and_b64 vcc, exec, s[38:39]
	s_mov_b32 s46, s45
	s_mov_b32 s47, s4
	s_mov_b64 s[12:13], s[8:9]
	v_readlane_b32 s50, v255, 1
	s_waitcnt vmcnt(0)
	v_lshlrev_b32_e32 v196, 16, v178
	v_and_b32_e32 v197, 0xffff0000, v178
	v_lshlrev_b32_e32 v178, 16, v179
	v_and_b32_e32 v179, 0xffff0000, v179
	v_pk_add_f32 v[128:129], v[128:129], v[178:179]
	v_pk_add_f32 v[126:127], v[126:127], v[196:197]
	v_lshlrev_b32_e32 v178, 16, v181
	v_cvt_pk_bf16_f32 v126, v126, v127
	v_cvt_pk_bf16_f32 v127, v128, v129
	v_lshl_add_u64 v[128:129], s[10:11], 0, v[194:195]
	v_lshl_add_u64 v[128:129], v[128:129], 0, v[140:141]
	global_store_dwordx2 v[128:129], v[126:127], off
	v_lshlrev_b32_e32 v126, 16, v180
	v_and_b32_e32 v127, 0xffff0000, v180
	v_and_b32_e32 v179, 0xffff0000, v181
	v_pk_add_f32 v[124:125], v[124:125], v[178:179]
	v_pk_add_f32 v[122:123], v[122:123], v[126:127]
	s_nop 0
	v_cvt_pk_bf16_f32 v122, v122, v123
	v_cvt_pk_bf16_f32 v123, v124, v125
	global_store_dwordx2 v[128:129], v[122:123], off offset:32
	v_lshlrev_b32_e32 v122, 16, v190
	v_and_b32_e32 v123, 0xffff0000, v190
	v_lshlrev_b32_e32 v124, 16, v191
	v_and_b32_e32 v125, 0xffff0000, v191
	v_pk_add_f32 v[120:121], v[120:121], v[124:125]
	v_pk_add_f32 v[118:119], v[118:119], v[122:123]
	s_nop 0
	v_cvt_pk_bf16_f32 v118, v118, v119
	v_cvt_pk_bf16_f32 v119, v120, v121
	global_store_dwordx2 v[128:129], v[118:119], off offset:256
	v_lshlrev_b32_e32 v118, 16, v192
	v_and_b32_e32 v119, 0xffff0000, v192
	v_lshlrev_b32_e32 v120, 16, v193
	v_and_b32_e32 v121, 0xffff0000, v193
	v_pk_add_f32 v[116:117], v[116:117], v[120:121]
	v_pk_add_f32 v[114:115], v[114:115], v[118:119]
	v_lshlrev_b32_e32 v118, 16, v175
	v_cvt_pk_bf16_f32 v114, v114, v115
	v_cvt_pk_bf16_f32 v115, v116, v117
	v_lshlrev_b32_e32 v116, 16, v174
	v_and_b32_e32 v117, 0xffff0000, v174
	v_and_b32_e32 v119, 0xffff0000, v175
	global_store_dwordx2 v[128:129], v[114:115], off offset:288
	v_lshlrev_b64 v[114:115], 12, v[172:173]
	v_pk_add_f32 v[112:113], v[112:113], v[118:119]
	v_pk_add_f32 v[110:111], v[110:111], v[116:117]
	s_nop 0
	v_cvt_pk_bf16_f32 v110, v110, v111
	v_cvt_pk_bf16_f32 v111, v112, v113
	v_lshl_add_u64 v[112:113], s[10:11], 0, v[114:115]
	v_lshl_add_u64 v[112:113], v[112:113], 0, v[140:141]
	global_store_dwordx2 v[112:113], v[110:111], off
	v_lshlrev_b32_e32 v110, 16, v170
	v_and_b32_e32 v111, 0xffff0000, v170
	v_lshlrev_b32_e32 v114, 16, v171
	v_and_b32_e32 v115, 0xffff0000, v171
	v_pk_add_f32 v[108:109], v[108:109], v[114:115]
	v_pk_add_f32 v[106:107], v[106:107], v[110:111]
	s_nop 0
	v_cvt_pk_bf16_f32 v106, v106, v107
	v_cvt_pk_bf16_f32 v107, v108, v109
	global_store_dwordx2 v[112:113], v[106:107], off offset:32
	v_lshlrev_b32_e32 v106, 16, v168
	v_and_b32_e32 v107, 0xffff0000, v168
	v_lshlrev_b32_e32 v108, 16, v169
	v_and_b32_e32 v109, 0xffff0000, v169
	v_pk_add_f32 v[104:105], v[104:105], v[108:109]
	v_pk_add_f32 v[102:103], v[102:103], v[106:107]
	s_nop 0
	v_cvt_pk_bf16_f32 v102, v102, v103
	v_cvt_pk_bf16_f32 v103, v104, v105
	global_store_dwordx2 v[112:113], v[102:103], off offset:256
	v_lshlrev_b32_e32 v102, 16, v166
	v_and_b32_e32 v103, 0xffff0000, v166
	v_lshlrev_b32_e32 v104, 16, v167
	v_and_b32_e32 v105, 0xffff0000, v167
	v_pk_add_f32 v[96:97], v[96:97], v[104:105]
	v_pk_add_f32 v[94:95], v[94:95], v[102:103]
	v_lshlrev_b32_e32 v102, 16, v165
	v_cvt_pk_bf16_f32 v94, v94, v95
	v_cvt_pk_bf16_f32 v95, v96, v97
	global_store_dwordx2 v[112:113], v[94:95], off offset:288
	v_lshlrev_b64 v[94:95], 12, v[162:163]
	v_lshlrev_b32_e32 v96, 16, v164
	v_and_b32_e32 v97, 0xffff0000, v164
	v_and_b32_e32 v103, 0xffff0000, v165
	v_pk_add_f32 v[100:101], v[100:101], v[102:103]
	v_pk_add_f32 v[96:97], v[98:99], v[96:97]
	v_lshl_add_u64 v[94:95], s[10:11], 0, v[94:95]
	v_cvt_pk_bf16_f32 v96, v96, v97
	v_cvt_pk_bf16_f32 v97, v100, v101
	v_lshl_add_u64 v[94:95], v[94:95], 0, v[140:141]
	global_store_dwordx2 v[94:95], v[96:97], off
	v_lshlrev_b32_e32 v96, 16, v160
	v_and_b32_e32 v97, 0xffff0000, v160
	v_lshlrev_b32_e32 v98, 16, v161
	v_and_b32_e32 v99, 0xffff0000, v161
	v_pk_add_f32 v[92:93], v[92:93], v[98:99]
	v_pk_add_f32 v[90:91], v[90:91], v[96:97]
	v_add_u32_e32 v100, 0xb0, v142
	v_cvt_pk_bf16_f32 v90, v90, v91
	v_cvt_pk_bf16_f32 v91, v92, v93
	global_store_dwordx2 v[94:95], v[90:91], off offset:32
	v_lshlrev_b32_e32 v90, 16, v154
	v_and_b32_e32 v91, 0xffff0000, v154
	v_lshlrev_b32_e32 v92, 16, v155
	v_and_b32_e32 v93, 0xffff0000, v155
	v_pk_add_f32 v[88:89], v[88:89], v[92:93]
	v_pk_add_f32 v[86:87], v[86:87], v[90:91]
	v_add_u32_e32 v90, 0xa0, v142
	v_cvt_pk_bf16_f32 v86, v86, v87
	v_cvt_pk_bf16_f32 v87, v88, v89
	global_store_dwordx2 v[94:95], v[86:87], off offset:256
	v_lshlrev_b32_e32 v86, 16, v150
	v_and_b32_e32 v87, 0xffff0000, v150
	v_lshlrev_b32_e32 v88, 16, v151
	v_and_b32_e32 v89, 0xffff0000, v151
	v_pk_add_f32 v[80:81], v[80:81], v[88:89]
	v_pk_add_f32 v[78:79], v[78:79], v[86:87]
	v_lshlrev_b32_e32 v86, 16, v159
	v_cvt_pk_bf16_f32 v78, v78, v79
	v_cvt_pk_bf16_f32 v79, v80, v81
	global_store_dwordx2 v[94:95], v[78:79], off offset:288
	v_lshlrev_b64 v[78:79], 12, v[156:157]
	v_lshlrev_b32_e32 v80, 16, v158
	v_and_b32_e32 v81, 0xffff0000, v158
	v_and_b32_e32 v87, 0xffff0000, v159
	v_pk_add_f32 v[84:85], v[84:85], v[86:87]
	v_pk_add_f32 v[80:81], v[82:83], v[80:81]
	v_lshl_add_u64 v[78:79], s[10:11], 0, v[78:79]
	v_cvt_pk_bf16_f32 v80, v80, v81
	v_cvt_pk_bf16_f32 v81, v84, v85
	v_lshl_add_u64 v[78:79], v[78:79], 0, v[140:141]
	global_store_dwordx2 v[78:79], v[80:81], off
	v_lshlrev_b32_e32 v80, 16, v152
	v_and_b32_e32 v81, 0xffff0000, v152
	v_lshlrev_b32_e32 v82, 16, v153
	v_and_b32_e32 v83, 0xffff0000, v153
	v_pk_add_f32 v[76:77], v[76:77], v[82:83]
	v_pk_add_f32 v[74:75], v[74:75], v[80:81]
	v_add_u32_e32 v80, 0x90, v142
	v_cvt_pk_bf16_f32 v74, v74, v75
	v_cvt_pk_bf16_f32 v75, v76, v77
	global_store_dwordx2 v[78:79], v[74:75], off offset:32
	v_lshlrev_b32_e32 v74, 16, v148
	v_and_b32_e32 v75, 0xffff0000, v148
	v_lshlrev_b32_e32 v76, 16, v149
	v_and_b32_e32 v77, 0xffff0000, v149
	v_pk_add_f32 v[72:73], v[72:73], v[76:77]
	v_pk_add_f32 v[70:71], v[70:71], v[74:75]
	v_ashrrev_i32_e32 v81, 31, v80
	v_cvt_pk_bf16_f32 v70, v70, v71
	v_cvt_pk_bf16_f32 v71, v72, v73
	global_store_dwordx2 v[78:79], v[70:71], off offset:256
	v_lshlrev_b32_e32 v70, 16, v146
	v_and_b32_e32 v71, 0xffff0000, v146
	v_lshlrev_b32_e32 v72, 16, v147
	v_and_b32_e32 v73, 0xffff0000, v147
	v_pk_add_f32 v[68:69], v[68:69], v[72:73]
	v_pk_add_f32 v[66:67], v[66:67], v[70:71]
	v_add_u32_e32 v70, 0x80, v142
	v_cvt_pk_bf16_f32 v66, v66, v67
	v_cvt_pk_bf16_f32 v67, v68, v69
	v_ashrrev_i32_e32 v71, 31, v70
	global_store_dwordx2 v[78:79], v[66:67], off offset:288
	v_lshlrev_b64 v[66:67], 11, v[70:71]
	v_lshl_add_u64 v[66:67], v[144:145], 0, v[66:67]
	global_load_dwordx2 v[72:73], v[66:67], off
	global_load_dwordx2 v[74:75], v[66:67], off offset:32
	global_load_dwordx2 v[76:77], v[66:67], off offset:256
	global_load_dwordx2 v[78:79], v[66:67], off offset:288
	v_lshlrev_b64 v[66:67], 11, v[80:81]
	v_lshl_add_u64 v[66:67], v[144:145], 0, v[66:67]
	global_load_dwordx2 v[82:83], v[66:67], off
	global_load_dwordx2 v[84:85], v[66:67], off offset:32
	global_load_dwordx2 v[86:87], v[66:67], off offset:256
	global_load_dwordx2 v[88:89], v[66:67], off offset:288
	v_ashrrev_i32_e32 v91, 31, v90
	v_lshlrev_b64 v[66:67], 11, v[90:91]
	v_lshl_add_u64 v[66:67], v[144:145], 0, v[66:67]
	global_load_dwordx2 v[92:93], v[66:67], off
	global_load_dwordx2 v[94:95], v[66:67], off offset:32
	global_load_dwordx2 v[96:97], v[66:67], off offset:256
	global_load_dwordx2 v[98:99], v[66:67], off offset:288
	v_ashrrev_i32_e32 v101, 31, v100
	v_lshlrev_b64 v[66:67], 11, v[100:101]
	v_lshl_add_u64 v[66:67], v[144:145], 0, v[66:67]
	global_load_dwordx2 v[102:103], v[66:67], off
	global_load_dwordx2 v[104:105], v[66:67], off offset:32
	global_load_dwordx2 v[68:69], v[66:67], off offset:256
	s_nop 0
	global_load_dwordx2 v[66:67], v[66:67], off offset:288
	v_lshlrev_b64 v[70:71], 12, v[70:71]
	s_waitcnt vmcnt(0)
	v_lshlrev_b32_e32 v106, 16, v72
	v_and_b32_e32 v107, 0xffff0000, v72
	v_lshlrev_b32_e32 v72, 16, v73
	v_and_b32_e32 v73, 0xffff0000, v73
	v_pk_add_f32 v[64:65], v[64:65], v[72:73]
	v_pk_add_f32 v[62:63], v[62:63], v[106:107]
	s_nop 0
	v_cvt_pk_bf16_f32 v62, v62, v63
	v_cvt_pk_bf16_f32 v63, v64, v65
	v_lshl_add_u64 v[64:65], s[10:11], 0, v[70:71]
	v_lshl_add_u64 v[64:65], v[64:65], 0, v[140:141]
	global_store_dwordx2 v[64:65], v[62:63], off
	v_lshlrev_b32_e32 v62, 16, v74
	v_and_b32_e32 v63, 0xffff0000, v74
	v_lshlrev_b32_e32 v70, 16, v75
	v_and_b32_e32 v71, 0xffff0000, v75
	v_pk_add_f32 v[60:61], v[60:61], v[70:71]
	v_pk_add_f32 v[58:59], v[58:59], v[62:63]
	s_nop 0
	v_cvt_pk_bf16_f32 v58, v58, v59
	v_cvt_pk_bf16_f32 v59, v60, v61
	global_store_dwordx2 v[64:65], v[58:59], off offset:32
	v_lshlrev_b32_e32 v58, 16, v76
	v_and_b32_e32 v59, 0xffff0000, v76
	v_lshlrev_b32_e32 v60, 16, v77
	v_and_b32_e32 v61, 0xffff0000, v77
	v_pk_add_f32 v[56:57], v[56:57], v[60:61]
	v_pk_add_f32 v[54:55], v[54:55], v[58:59]
	s_nop 0
	v_cvt_pk_bf16_f32 v54, v54, v55
	v_cvt_pk_bf16_f32 v55, v56, v57
	global_store_dwordx2 v[64:65], v[54:55], off offset:256
	v_lshlrev_b32_e32 v54, 16, v78
	v_and_b32_e32 v55, 0xffff0000, v78
	v_lshlrev_b32_e32 v56, 16, v79
	v_and_b32_e32 v57, 0xffff0000, v79
	v_pk_add_f32 v[48:49], v[48:49], v[56:57]
	v_pk_add_f32 v[46:47], v[46:47], v[54:55]
	v_lshlrev_b32_e32 v54, 16, v83
	v_cvt_pk_bf16_f32 v46, v46, v47
	v_cvt_pk_bf16_f32 v47, v48, v49
	global_store_dwordx2 v[64:65], v[46:47], off offset:288
	v_lshlrev_b64 v[46:47], 12, v[80:81]
	v_lshlrev_b32_e32 v48, 16, v82
	v_and_b32_e32 v49, 0xffff0000, v82
	v_and_b32_e32 v55, 0xffff0000, v83
	v_pk_add_f32 v[52:53], v[52:53], v[54:55]
	v_pk_add_f32 v[48:49], v[50:51], v[48:49]
	v_lshl_add_u64 v[46:47], s[10:11], 0, v[46:47]
	v_cvt_pk_bf16_f32 v48, v48, v49
	v_cvt_pk_bf16_f32 v49, v52, v53
	v_lshl_add_u64 v[46:47], v[46:47], 0, v[140:141]
	global_store_dwordx2 v[46:47], v[48:49], off
	v_lshlrev_b32_e32 v48, 16, v84
	v_and_b32_e32 v49, 0xffff0000, v84
	v_lshlrev_b32_e32 v50, 16, v85
	v_and_b32_e32 v51, 0xffff0000, v85
	v_pk_add_f32 v[44:45], v[44:45], v[50:51]
	v_pk_add_f32 v[42:43], v[42:43], v[48:49]
	s_nop 0
	v_cvt_pk_bf16_f32 v42, v42, v43
	v_cvt_pk_bf16_f32 v43, v44, v45
	global_store_dwordx2 v[46:47], v[42:43], off offset:32
	v_lshlrev_b32_e32 v42, 16, v86
	v_and_b32_e32 v43, 0xffff0000, v86
	v_lshlrev_b32_e32 v44, 16, v87
	v_and_b32_e32 v45, 0xffff0000, v87
	v_pk_add_f32 v[40:41], v[40:41], v[44:45]
	v_pk_add_f32 v[38:39], v[38:39], v[42:43]
	s_nop 0
	v_cvt_pk_bf16_f32 v38, v38, v39
	v_cvt_pk_bf16_f32 v39, v40, v41
	global_store_dwordx2 v[46:47], v[38:39], off offset:256
	v_lshlrev_b32_e32 v38, 16, v88
	v_and_b32_e32 v39, 0xffff0000, v88
	v_lshlrev_b32_e32 v40, 16, v89
	v_and_b32_e32 v41, 0xffff0000, v89
	v_pk_add_f32 v[32:33], v[32:33], v[40:41]
	v_pk_add_f32 v[30:31], v[30:31], v[38:39]
	v_lshlrev_b32_e32 v38, 16, v93
	v_cvt_pk_bf16_f32 v30, v30, v31
	v_cvt_pk_bf16_f32 v31, v32, v33
	global_store_dwordx2 v[46:47], v[30:31], off offset:288
	v_lshlrev_b64 v[30:31], 12, v[90:91]
	v_lshlrev_b32_e32 v32, 16, v92
	v_and_b32_e32 v33, 0xffff0000, v92
	v_and_b32_e32 v39, 0xffff0000, v93
	v_pk_add_f32 v[36:37], v[36:37], v[38:39]
	v_pk_add_f32 v[32:33], v[34:35], v[32:33]
	v_lshl_add_u64 v[30:31], s[10:11], 0, v[30:31]
	v_cvt_pk_bf16_f32 v32, v32, v33
	v_cvt_pk_bf16_f32 v33, v36, v37
	v_lshl_add_u64 v[30:31], v[30:31], 0, v[140:141]
	global_store_dwordx2 v[30:31], v[32:33], off
	v_lshlrev_b32_e32 v32, 16, v94
	v_and_b32_e32 v33, 0xffff0000, v94
	v_lshlrev_b32_e32 v34, 16, v95
	v_and_b32_e32 v35, 0xffff0000, v95
	v_pk_add_f32 v[28:29], v[28:29], v[34:35]
	v_pk_add_f32 v[26:27], v[26:27], v[32:33]
	s_nop 0
	v_cvt_pk_bf16_f32 v26, v26, v27
	v_cvt_pk_bf16_f32 v27, v28, v29
	global_store_dwordx2 v[30:31], v[26:27], off offset:32
	v_lshlrev_b32_e32 v26, 16, v96
	v_and_b32_e32 v27, 0xffff0000, v96
	v_lshlrev_b32_e32 v28, 16, v97
	v_and_b32_e32 v29, 0xffff0000, v97
	v_pk_add_f32 v[24:25], v[24:25], v[28:29]
	v_pk_add_f32 v[22:23], v[22:23], v[26:27]
	s_nop 0
	v_cvt_pk_bf16_f32 v22, v22, v23
	v_cvt_pk_bf16_f32 v23, v24, v25
	global_store_dwordx2 v[30:31], v[22:23], off offset:256
	v_lshlrev_b32_e32 v22, 16, v98
	v_and_b32_e32 v23, 0xffff0000, v98
	v_lshlrev_b32_e32 v24, 16, v99
	v_and_b32_e32 v25, 0xffff0000, v99
	v_pk_add_f32 v[14:15], v[14:15], v[24:25]
	v_pk_add_f32 v[12:13], v[12:13], v[22:23]
	v_lshlrev_b32_e32 v22, 16, v103
	v_cvt_pk_bf16_f32 v12, v12, v13
	v_cvt_pk_bf16_f32 v13, v14, v15
	global_store_dwordx2 v[30:31], v[12:13], off offset:288
	v_lshlrev_b64 v[12:13], 12, v[100:101]
	v_lshlrev_b32_e32 v14, 16, v102
	v_and_b32_e32 v15, 0xffff0000, v102
	v_and_b32_e32 v23, 0xffff0000, v103
	v_pk_add_f32 v[20:21], v[20:21], v[22:23]
	v_pk_add_f32 v[14:15], v[18:19], v[14:15]
	v_lshl_add_u64 v[12:13], s[10:11], 0, v[12:13]
	v_cvt_pk_bf16_f32 v14, v14, v15
	v_cvt_pk_bf16_f32 v15, v20, v21
	v_lshl_add_u64 v[12:13], v[12:13], 0, v[140:141]
	global_store_dwordx2 v[12:13], v[14:15], off
	v_lshlrev_b32_e32 v14, 16, v104
	v_and_b32_e32 v15, 0xffff0000, v104
	v_lshlrev_b32_e32 v18, 16, v105
	v_and_b32_e32 v19, 0xffff0000, v105
	v_pk_add_f32 v[10:11], v[10:11], v[18:19]
	v_pk_add_f32 v[8:9], v[8:9], v[14:15]
	s_mov_b64 s[10:11], s[6:7]
	v_cvt_pk_bf16_f32 v8, v8, v9
	v_cvt_pk_bf16_f32 v9, v10, v11
	global_store_dwordx2 v[12:13], v[8:9], off offset:32
	v_lshlrev_b32_e32 v8, 16, v68
	v_and_b32_e32 v9, 0xffff0000, v68
	v_lshlrev_b32_e32 v10, 16, v69
	v_and_b32_e32 v11, 0xffff0000, v69
	v_pk_add_f32 v[6:7], v[6:7], v[10:11]
	v_pk_add_f32 v[4:5], v[4:5], v[8:9]
	s_nop 0
	v_cvt_pk_bf16_f32 v4, v4, v5
	v_cvt_pk_bf16_f32 v5, v6, v7
	global_store_dwordx2 v[12:13], v[4:5], off offset:256
	v_lshlrev_b32_e32 v4, 16, v66
	v_and_b32_e32 v5, 0xffff0000, v66
	v_lshlrev_b32_e32 v6, 16, v67
	v_and_b32_e32 v7, 0xffff0000, v67
	v_pk_add_f32 v[2:3], v[2:3], v[6:7]
	v_pk_add_f32 v[0:1], v[0:1], v[4:5]
	s_nop 0
	v_cvt_pk_bf16_f32 v0, v0, v1
	v_cvt_pk_bf16_f32 v1, v2, v3
	global_store_dwordx2 v[12:13], v[0:1], off offset:288
	s_cbranch_vccz .LBB0_1368
	s_waitcnt vmcnt(0)
	s_cmpk_gt_u32 s21, 0xff
	s_cbranch_scc1 .LBB0_1379
	s_barrier

.LBB0_1399:
	s_add_u32 s5, s16, 0x100
	v_mov_b32_e32 v0, 0
	s_addc_u32 s49, s17, 0
	s_mov_b32 s50, -2
	s_waitcnt lgkmcnt(0)
	v_mov_b32_e32 v1, v0
	v_mov_b32_e32 v2, v0
	v_mov_b32_e32 v3, v0
	v_mov_b32_e32 v4, v0
	v_mov_b32_e32 v5, v0
	v_mov_b32_e32 v6, v0
	v_mov_b32_e32 v7, v0
	v_mov_b32_e32 v18, v0
	v_mov_b32_e32 v19, v0
	v_mov_b32_e32 v20, v0
	v_mov_b32_e32 v21, v0
	v_mov_b32_e32 v22, v0
	v_mov_b32_e32 v23, v0
	v_mov_b32_e32 v24, v0
	v_mov_b32_e32 v25, v0
	v_mov_b32_e32 v34, v0
	v_mov_b32_e32 v35, v0
	v_mov_b32_e32 v36, v0
	v_mov_b32_e32 v37, v0
	v_mov_b32_e32 v38, v0
	v_mov_b32_e32 v39, v0
	v_mov_b32_e32 v40, v0
	v_mov_b32_e32 v41, v0
	v_mov_b32_e32 v50, v0
	v_mov_b32_e32 v51, v0
	v_mov_b32_e32 v52, v0
	v_mov_b32_e32 v53, v0
	v_mov_b32_e32 v54, v0
	v_mov_b32_e32 v55, v0
	v_mov_b32_e32 v56, v0
	v_mov_b32_e32 v57, v0
	v_mov_b32_e32 v8, v0
	v_mov_b32_e32 v9, v0
	v_mov_b32_e32 v10, v0
	v_mov_b32_e32 v11, v0
	v_mov_b32_e32 v12, v0
	v_mov_b32_e32 v13, v0
	v_mov_b32_e32 v14, v0
	v_mov_b32_e32 v15, v0
	v_mov_b32_e32 v26, v0
	v_mov_b32_e32 v27, v0
	v_mov_b32_e32 v28, v0
	v_mov_b32_e32 v29, v0
	v_mov_b32_e32 v30, v0
	v_mov_b32_e32 v31, v0
	v_mov_b32_e32 v32, v0
	v_mov_b32_e32 v33, v0
	v_mov_b32_e32 v42, v0
	v_mov_b32_e32 v43, v0
	v_mov_b32_e32 v44, v0
	v_mov_b32_e32 v45, v0
	v_mov_b32_e32 v46, v0
	v_mov_b32_e32 v47, v0
	v_mov_b32_e32 v48, v0
	v_mov_b32_e32 v49, v0
	v_mov_b32_e32 v58, v0
	v_mov_b32_e32 v59, v0
	v_mov_b32_e32 v60, v0
	v_mov_b32_e32 v61, v0
	v_mov_b32_e32 v62, v0
	v_mov_b32_e32 v63, v0
	v_mov_b32_e32 v64, v0
	v_mov_b32_e32 v65, v0
	v_mov_b32_e32 v66, v0
	v_mov_b32_e32 v67, v0
	v_mov_b32_e32 v68, v0
	v_mov_b32_e32 v69, v0
	v_mov_b32_e32 v70, v0
	v_mov_b32_e32 v71, v0
	v_mov_b32_e32 v72, v0
	v_mov_b32_e32 v73, v0
	v_mov_b32_e32 v82, v0
	v_mov_b32_e32 v83, v0
	v_mov_b32_e32 v84, v0
	v_mov_b32_e32 v85, v0
	v_mov_b32_e32 v86, v0
	v_mov_b32_e32 v87, v0
	v_mov_b32_e32 v88, v0
	v_mov_b32_e32 v89, v0
	v_mov_b32_e32 v98, v0
	v_mov_b32_e32 v99, v0
	v_mov_b32_e32 v100, v0
	v_mov_b32_e32 v101, v0
	v_mov_b32_e32 v102, v0
	v_mov_b32_e32 v103, v0
	v_mov_b32_e32 v104, v0
	v_mov_b32_e32 v105, v0
	v_mov_b32_e32 v114, v0
	v_mov_b32_e32 v115, v0
	v_mov_b32_e32 v116, v0
	v_mov_b32_e32 v117, v0
	v_mov_b32_e32 v118, v0
	v_mov_b32_e32 v119, v0
	v_mov_b32_e32 v120, v0
	v_mov_b32_e32 v121, v0
	v_mov_b32_e32 v74, v0
	v_mov_b32_e32 v75, v0
	v_mov_b32_e32 v76, v0
	v_mov_b32_e32 v77, v0
	v_mov_b32_e32 v78, v0
	v_mov_b32_e32 v79, v0
	v_mov_b32_e32 v80, v0
	v_mov_b32_e32 v81, v0
	v_mov_b32_e32 v90, v0
	v_mov_b32_e32 v91, v0
	v_mov_b32_e32 v92, v0
	v_mov_b32_e32 v93, v0
	v_mov_b32_e32 v94, v0
	v_mov_b32_e32 v95, v0
	v_mov_b32_e32 v96, v0
	v_mov_b32_e32 v97, v0
	v_mov_b32_e32 v106, v0
	v_mov_b32_e32 v107, v0
	v_mov_b32_e32 v108, v0
	v_mov_b32_e32 v109, v0
	v_mov_b32_e32 v110, v0
	v_mov_b32_e32 v111, v0
	v_mov_b32_e32 v112, v0
	v_mov_b32_e32 v113, v0
	v_mov_b32_e32 v122, v0
	v_mov_b32_e32 v123, v0
	v_mov_b32_e32 v124, v0
	v_mov_b32_e32 v125, v0
	v_mov_b32_e32 v126, v0
	v_mov_b32_e32 v127, v0
	v_mov_b32_e32 v128, v0
	v_mov_b32_e32 v129, v0
	v_readfirstlane_b32 s98, v232
	s_cmp_ge_u32 s98, 0x100
	s_cbranch_scc0 .Lsp_sk4
	s_setprio 1
.Lsp_sk4:
.LBB0_1400:
	s_add_u32 s16, s12, 0x100
	s_addc_u32 s17, s13, 0
	s_add_i32 s51, 0, 0x10000
	v_add_u32_e32 v142, s51, v210
	ds_read_b128 v[130:133], v142
	ds_read_b128 v[134:137], v142 offset:1024
	ds_read_b128 v[138:141], v142 offset:2048
	ds_read_b128 v[142:145], v142 offset:3072
	s_cmp_eq_u32 s50, 12
	s_cselect_b32 s35, s7, s17
	s_cselect_b32 s34, s6, s16
	s_cselect_b32 s23, s9, s49
	s_cselect_b32 s22, s8, s5
	v_lshl_add_u64 v[178:179], s[12:13], 0, v[194:195]
	s_add_i32 m0, s33, 0xc000
	ds_read_b128 v[146:149], v212
	ds_read_b128 v[150:153], v212 offset:1024
	ds_read_b128 v[154:157], v212 offset:2048
	ds_read_b128 v[158:161], v212 offset:3072
	ds_read_b128 v[162:165], v212 offset:4096
	ds_read_b128 v[166:169], v212 offset:5120
	ds_read_b128 v[170:173], v212 offset:6144
	ds_read_b128 v[174:177], v212 offset:7168
	global_load_lds_dwordx4 v[178:179], off
	v_lshl_add_u64 v[178:179], s[12:13], 0, v[196:197]
	s_add_i32 m0, s33, 0xe000
	s_nop 0
	global_load_lds_dwordx4 v[178:179], off
	s_waitcnt lgkmcnt(8)
	s_barrier
	s_waitcnt lgkmcnt(0)
	s_waitcnt lgkmcnt(0)
	v_mfma_f32_16x16x32_bf16 v[126:129], v[130:133], v[146:149], v[126:129]
	v_mfma_f32_16x16x32_bf16 v[122:125], v[138:141], v[146:149], v[122:125]
	v_mfma_f32_16x16x32_bf16 v[110:113], v[130:133], v[154:157], v[110:113]
	v_mfma_f32_16x16x32_bf16 v[106:109], v[138:141], v[154:157], v[106:109]
	v_mfma_f32_16x16x32_bf16 v[94:97], v[130:133], v[162:165], v[94:97]
	v_mfma_f32_16x16x32_bf16 v[90:93], v[138:141], v[162:165], v[90:93]
	v_mfma_f32_16x16x32_bf16 v[78:81], v[130:133], v[170:173], v[78:81]
	v_mfma_f32_16x16x32_bf16 v[74:77], v[138:141], v[170:173], v[74:77]
	v_mfma_f32_16x16x32_bf16 v[126:129], v[134:137], v[150:153], v[126:129]
	v_mfma_f32_16x16x32_bf16 v[122:125], v[142:145], v[150:153], v[122:125]
	v_mfma_f32_16x16x32_bf16 v[110:113], v[134:137], v[158:161], v[110:113]
	v_mfma_f32_16x16x32_bf16 v[106:109], v[142:145], v[158:161], v[106:109]
	v_mfma_f32_16x16x32_bf16 v[94:97], v[134:137], v[166:169], v[94:97]
	v_mfma_f32_16x16x32_bf16 v[90:93], v[142:145], v[166:169], v[90:93]
	v_mfma_f32_16x16x32_bf16 v[78:81], v[134:137], v[174:177], v[78:81]
	v_mfma_f32_16x16x32_bf16 v[74:77], v[142:145], v[174:177], v[74:77]
	s_barrier
	s_add_i32 s52, 0, 0x14000
	s_add_i32 s12, s51, s25
	v_add_u32_e32 v206, s52, v210
	v_lshl_add_u64 v[214:215], s[22:23], 0, v[16:17]
	s_mov_b32 m0, s12
	ds_read_b128 v[178:181], v206
	ds_read_b128 v[198:201], v206 offset:1024
	ds_read_b128 v[202:205], v206 offset:2048
	ds_read_b128 v[206:209], v206 offset:3072
	global_load_lds_dwordx4 v[214:215], off
	v_lshl_add_u64 v[216:217], s[22:23], 0, v[192:193]
	s_add_i32 m0, s12, 0x2000
	s_nop 0
	global_load_lds_dwordx4 v[216:217], off
	s_barrier
	s_waitcnt lgkmcnt(0)
	s_waitcnt lgkmcnt(0)
	v_mfma_f32_16x16x32_bf16 v[118:121], v[178:181], v[146:149], v[118:121]
	v_mfma_f32_16x16x32_bf16 v[114:117], v[202:205], v[146:149], v[114:117]
	v_mfma_f32_16x16x32_bf16 v[102:105], v[178:181], v[154:157], v[102:105]
	v_mfma_f32_16x16x32_bf16 v[98:101], v[202:205], v[154:157], v[98:101]
	v_mfma_f32_16x16x32_bf16 v[86:89], v[178:181], v[162:165], v[86:89]
	v_mfma_f32_16x16x32_bf16 v[82:85], v[202:205], v[162:165], v[82:85]
	v_mfma_f32_16x16x32_bf16 v[70:73], v[178:181], v[170:173], v[70:73]
	v_mfma_f32_16x16x32_bf16 v[66:69], v[202:205], v[170:173], v[66:69]
	v_mfma_f32_16x16x32_bf16 v[118:121], v[198:201], v[150:153], v[118:121]
	v_mfma_f32_16x16x32_bf16 v[114:117], v[206:209], v[150:153], v[114:117]
	v_mfma_f32_16x16x32_bf16 v[102:105], v[198:201], v[158:161], v[102:105]
	v_mfma_f32_16x16x32_bf16 v[98:101], v[206:209], v[158:161], v[98:101]
	v_mfma_f32_16x16x32_bf16 v[86:89], v[198:201], v[166:169], v[86:89]
	v_mfma_f32_16x16x32_bf16 v[82:85], v[206:209], v[166:169], v[82:85]
	v_mfma_f32_16x16x32_bf16 v[70:73], v[198:201], v[174:177], v[70:73]
	v_mfma_f32_16x16x32_bf16 v[66:69], v[206:209], v[174:177], v[66:69]
	s_mov_b32 m0, s33
	v_lshl_add_u64 v[218:219], s[34:35], 0, v[188:189]
	s_barrier
	ds_read_b128 v[146:149], v212 offset:16384
	ds_read_b128 v[150:153], v212 offset:17408
	ds_read_b128 v[154:157], v212 offset:18432
	ds_read_b128 v[158:161], v212 offset:19456
	ds_read_b128 v[162:165], v212 offset:20480
	ds_read_b128 v[166:169], v212 offset:21504
	ds_read_b128 v[170:173], v212 offset:22528
	ds_read_b128 v[174:177], v212 offset:23552
	global_load_lds_dwordx4 v[218:219], off
	v_lshl_add_u64 v[220:221], s[34:35], 0, v[190:191]
	s_mov_b32 m0, s40
	s_nop 0
	global_load_lds_dwordx4 v[220:221], off
	s_barrier
	s_waitcnt lgkmcnt(0)
	s_waitcnt lgkmcnt(0)
	v_mfma_f32_16x16x32_bf16 v[62:65], v[130:133], v[146:149], v[62:65]
	v_mfma_f32_16x16x32_bf16 v[58:61], v[138:141], v[146:149], v[58:61]
	v_mfma_f32_16x16x32_bf16 v[46:49], v[130:133], v[154:157], v[46:49]
	v_mfma_f32_16x16x32_bf16 v[42:45], v[138:141], v[154:157], v[42:45]
	v_mfma_f32_16x16x32_bf16 v[30:33], v[130:133], v[162:165], v[30:33]
	v_mfma_f32_16x16x32_bf16 v[26:29], v[138:141], v[162:165], v[26:29]
	v_mfma_f32_16x16x32_bf16 v[12:15], v[130:133], v[170:173], v[12:15]
	v_mfma_f32_16x16x32_bf16 v[8:11], v[138:141], v[170:173], v[8:11]
	v_mfma_f32_16x16x32_bf16 v[62:65], v[134:137], v[150:153], v[62:65]
	v_mfma_f32_16x16x32_bf16 v[58:61], v[142:145], v[150:153], v[58:61]
	v_mfma_f32_16x16x32_bf16 v[46:49], v[134:137], v[158:161], v[46:49]
	v_mfma_f32_16x16x32_bf16 v[42:45], v[142:145], v[158:161], v[42:45]
	v_mfma_f32_16x16x32_bf16 v[30:33], v[134:137], v[166:169], v[30:33]
	v_mfma_f32_16x16x32_bf16 v[26:29], v[142:145], v[166:169], v[26:29]
	v_mfma_f32_16x16x32_bf16 v[12:15], v[134:137], v[174:177], v[12:15]
	v_mfma_f32_16x16x32_bf16 v[8:11], v[142:145], v[174:177], v[8:11]
	s_barrier
	s_add_u32 s12, s22, 0x40000
	s_addc_u32 s13, s23, 0
	s_add_i32 s51, s52, s25
	v_lshl_add_u64 v[130:131], s[12:13], 0, v[16:17]
	s_mov_b32 m0, s51
	s_nop 0
	global_load_lds_dwordx4 v[130:131], off
	v_lshl_add_u64 v[130:131], s[12:13], 0, v[192:193]
	s_add_i32 m0, s51, 0x2000
	s_nop 0
	global_load_lds_dwordx4 v[130:131], off
	s_waitcnt vmcnt(6)
	s_barrier
	v_mfma_f32_16x16x32_bf16 v[54:57], v[178:181], v[146:149], v[54:57]
	v_mfma_f32_16x16x32_bf16 v[50:53], v[202:205], v[146:149], v[50:53]
	v_mfma_f32_16x16x32_bf16 v[38:41], v[178:181], v[154:157], v[38:41]
	v_mfma_f32_16x16x32_bf16 v[34:37], v[202:205], v[154:157], v[34:37]
	v_mfma_f32_16x16x32_bf16 v[22:25], v[178:181], v[162:165], v[22:25]
	v_mfma_f32_16x16x32_bf16 v[18:21], v[202:205], v[162:165], v[18:21]
	v_mfma_f32_16x16x32_bf16 v[4:7], v[178:181], v[170:173], v[4:7]
	v_mfma_f32_16x16x32_bf16 v[0:3], v[202:205], v[170:173], v[0:3]
	v_mfma_f32_16x16x32_bf16 v[54:57], v[198:201], v[150:153], v[54:57]
	v_mfma_f32_16x16x32_bf16 v[50:53], v[206:209], v[150:153], v[50:53]
	v_mfma_f32_16x16x32_bf16 v[38:41], v[198:201], v[158:161], v[38:41]
	v_mfma_f32_16x16x32_bf16 v[34:37], v[206:209], v[158:161], v[34:37]
	v_mfma_f32_16x16x32_bf16 v[22:25], v[198:201], v[166:169], v[22:25]
	v_mfma_f32_16x16x32_bf16 v[18:21], v[206:209], v[166:169], v[18:21]
	v_mfma_f32_16x16x32_bf16 v[4:7], v[198:201], v[174:177], v[4:7]
	v_mfma_f32_16x16x32_bf16 v[0:3], v[206:209], v[174:177], v[0:3]
	s_add_i32 s51, 0, 0x18000
	v_add_u32_e32 v142, s51, v210
	s_barrier
	ds_read_b128 v[130:133], v142
	ds_read_b128 v[134:137], v142 offset:1024
	ds_read_b128 v[138:141], v142 offset:2048
	ds_read_b128 v[142:145], v142 offset:3072
	s_add_u32 s12, s34, 0x1c0000
	s_addc_u32 s13, s35, 0
	s_mov_b32 m0, s41
	v_lshl_add_u64 v[178:179], s[12:13], 0, v[188:189]
	ds_read_b128 v[146:149], v212 offset:32768
	ds_read_b128 v[150:153], v212 offset:33792
	ds_read_b128 v[154:157], v212 offset:34816
	ds_read_b128 v[158:161], v212 offset:35840
	ds_read_b128 v[162:165], v212 offset:36864
	ds_read_b128 v[166:169], v212 offset:37888
	ds_read_b128 v[170:173], v212 offset:38912
	ds_read_b128 v[174:177], v212 offset:39936
	global_load_lds_dwordx4 v[178:179], off
	v_lshl_add_u64 v[178:179], s[12:13], 0, v[190:191]
	s_mov_b32 m0, s42
	s_nop 0
	global_load_lds_dwordx4 v[178:179], off
	s_waitcnt lgkmcnt(8)
	s_barrier
	s_waitcnt lgkmcnt(0)
	s_waitcnt lgkmcnt(0)
	v_mfma_f32_16x16x32_bf16 v[126:129], v[130:133], v[146:149], v[126:129]
	v_mfma_f32_16x16x32_bf16 v[122:125], v[138:141], v[146:149], v[122:125]
	v_mfma_f32_16x16x32_bf16 v[110:113], v[130:133], v[154:157], v[110:113]
	v_mfma_f32_16x16x32_bf16 v[106:109], v[138:141], v[154:157], v[106:109]
	v_mfma_f32_16x16x32_bf16 v[94:97], v[130:133], v[162:165], v[94:97]
	v_mfma_f32_16x16x32_bf16 v[90:93], v[138:141], v[162:165], v[90:93]
	v_mfma_f32_16x16x32_bf16 v[78:81], v[130:133], v[170:173], v[78:81]
	v_mfma_f32_16x16x32_bf16 v[74:77], v[138:141], v[170:173], v[74:77]
	v_mfma_f32_16x16x32_bf16 v[126:129], v[134:137], v[150:153], v[126:129]
	v_mfma_f32_16x16x32_bf16 v[122:125], v[142:145], v[150:153], v[122:125]
	v_mfma_f32_16x16x32_bf16 v[110:113], v[134:137], v[158:161], v[110:113]
	v_mfma_f32_16x16x32_bf16 v[106:109], v[142:145], v[158:161], v[106:109]
	v_mfma_f32_16x16x32_bf16 v[94:97], v[134:137], v[166:169], v[94:97]
	v_mfma_f32_16x16x32_bf16 v[90:93], v[142:145], v[166:169], v[90:93]
	v_mfma_f32_16x16x32_bf16 v[78:81], v[134:137], v[174:177], v[78:81]
	v_mfma_f32_16x16x32_bf16 v[74:77], v[142:145], v[174:177], v[74:77]
	s_barrier
	s_add_i32 s34, 0, 0x1c000
	s_add_i32 s12, s51, s25
	v_add_u32_e32 v206, s34, v210
	v_lshl_add_u64 v[214:215], v[214:215], 0, s[14:15]
	s_mov_b32 m0, s12
	ds_read_b128 v[178:181], v206
	ds_read_b128 v[198:201], v206 offset:1024
	ds_read_b128 v[202:205], v206 offset:2048
	ds_read_b128 v[206:209], v206 offset:3072
	global_load_lds_dwordx4 v[214:215], off
	v_lshl_add_u64 v[214:215], v[216:217], 0, s[14:15]
	s_add_i32 m0, s12, 0x2000
	s_nop 0
	global_load_lds_dwordx4 v[214:215], off
	s_barrier
	s_waitcnt lgkmcnt(0)
	s_waitcnt lgkmcnt(0)
	v_mfma_f32_16x16x32_bf16 v[118:121], v[178:181], v[146:149], v[118:121]
	v_mfma_f32_16x16x32_bf16 v[114:117], v[202:205], v[146:149], v[114:117]
	v_mfma_f32_16x16x32_bf16 v[102:105], v[178:181], v[154:157], v[102:105]
	v_mfma_f32_16x16x32_bf16 v[98:101], v[202:205], v[154:157], v[98:101]
	v_mfma_f32_16x16x32_bf16 v[86:89], v[178:181], v[162:165], v[86:89]
	v_mfma_f32_16x16x32_bf16 v[82:85], v[202:205], v[162:165], v[82:85]
	v_mfma_f32_16x16x32_bf16 v[70:73], v[178:181], v[170:173], v[70:73]
	v_mfma_f32_16x16x32_bf16 v[66:69], v[202:205], v[170:173], v[66:69]
	v_mfma_f32_16x16x32_bf16 v[118:121], v[198:201], v[150:153], v[118:121]
	v_mfma_f32_16x16x32_bf16 v[114:117], v[206:209], v[150:153], v[114:117]
	v_mfma_f32_16x16x32_bf16 v[102:105], v[198:201], v[158:161], v[102:105]
	v_mfma_f32_16x16x32_bf16 v[98:101], v[206:209], v[158:161], v[98:101]
	v_mfma_f32_16x16x32_bf16 v[86:89], v[198:201], v[166:169], v[86:89]
	v_mfma_f32_16x16x32_bf16 v[82:85], v[206:209], v[166:169], v[82:85]
	v_mfma_f32_16x16x32_bf16 v[70:73], v[198:201], v[174:177], v[70:73]
	v_mfma_f32_16x16x32_bf16 v[66:69], v[206:209], v[174:177], v[66:69]
	s_mov_b32 m0, s44
	v_lshl_add_u64 v[214:215], v[218:219], 0, s[14:15]
	s_barrier
	ds_read_b128 v[146:149], v212 offset:49152
	ds_read_b128 v[150:153], v212 offset:50176
	ds_read_b128 v[154:157], v212 offset:51200
	ds_read_b128 v[158:161], v212 offset:52224
	ds_read_b128 v[162:165], v212 offset:53248
	ds_read_b128 v[166:169], v212 offset:54272
	ds_read_b128 v[170:173], v212 offset:55296
	ds_read_b128 v[174:177], v212 offset:56320
	global_load_lds_dwordx4 v[214:215], off
	v_lshl_add_u64 v[214:215], v[220:221], 0, s[14:15]
	s_mov_b32 m0, s45
	s_nop 0
	global_load_lds_dwordx4 v[214:215], off
	s_barrier
	s_waitcnt lgkmcnt(0)
	s_waitcnt lgkmcnt(0)
	v_mfma_f32_16x16x32_bf16 v[62:65], v[130:133], v[146:149], v[62:65]
	v_mfma_f32_16x16x32_bf16 v[58:61], v[138:141], v[146:149], v[58:61]
	v_mfma_f32_16x16x32_bf16 v[46:49], v[130:133], v[154:157], v[46:49]
	v_mfma_f32_16x16x32_bf16 v[42:45], v[138:141], v[154:157], v[42:45]
	v_mfma_f32_16x16x32_bf16 v[30:33], v[130:133], v[162:165], v[30:33]
	v_mfma_f32_16x16x32_bf16 v[26:29], v[138:141], v[162:165], v[26:29]
	v_mfma_f32_16x16x32_bf16 v[12:15], v[130:133], v[170:173], v[12:15]
	v_mfma_f32_16x16x32_bf16 v[8:11], v[138:141], v[170:173], v[8:11]
	v_mfma_f32_16x16x32_bf16 v[62:65], v[134:137], v[150:153], v[62:65]
	v_mfma_f32_16x16x32_bf16 v[58:61], v[142:145], v[150:153], v[58:61]
	v_mfma_f32_16x16x32_bf16 v[46:49], v[134:137], v[158:161], v[46:49]
	v_mfma_f32_16x16x32_bf16 v[42:45], v[142:145], v[158:161], v[42:45]
	v_mfma_f32_16x16x32_bf16 v[30:33], v[134:137], v[166:169], v[30:33]
	v_mfma_f32_16x16x32_bf16 v[26:29], v[142:145], v[166:169], v[26:29]
	v_mfma_f32_16x16x32_bf16 v[12:15], v[134:137], v[174:177], v[12:15]
	v_mfma_f32_16x16x32_bf16 v[8:11], v[142:145], v[174:177], v[8:11]
	s_barrier
	s_add_u32 s12, s22, 0x40080
	s_addc_u32 s13, s23, 0
	s_add_i32 s22, s34, s25
	v_lshl_add_u64 v[130:131], s[12:13], 0, v[16:17]
	s_mov_b32 m0, s22
	s_nop 0
	global_load_lds_dwordx4 v[130:131], off
	v_lshl_add_u64 v[130:131], s[12:13], 0, v[192:193]
	s_add_i32 m0, s22, 0x2000
	s_nop 0
	global_load_lds_dwordx4 v[130:131], off
	s_waitcnt vmcnt(6)
	s_barrier
	v_mfma_f32_16x16x32_bf16 v[54:57], v[178:181], v[146:149], v[54:57]
	v_mfma_f32_16x16x32_bf16 v[50:53], v[202:205], v[146:149], v[50:53]
	v_mfma_f32_16x16x32_bf16 v[38:41], v[178:181], v[154:157], v[38:41]
	v_mfma_f32_16x16x32_bf16 v[34:37], v[202:205], v[154:157], v[34:37]
	v_mfma_f32_16x16x32_bf16 v[22:25], v[178:181], v[162:165], v[22:25]
	v_mfma_f32_16x16x32_bf16 v[18:21], v[202:205], v[162:165], v[18:21]
	v_mfma_f32_16x16x32_bf16 v[4:7], v[178:181], v[170:173], v[4:7]
	v_mfma_f32_16x16x32_bf16 v[0:3], v[202:205], v[170:173], v[0:3]
	v_mfma_f32_16x16x32_bf16 v[54:57], v[198:201], v[150:153], v[54:57]
	v_mfma_f32_16x16x32_bf16 v[50:53], v[206:209], v[150:153], v[50:53]
	v_mfma_f32_16x16x32_bf16 v[38:41], v[198:201], v[158:161], v[38:41]
	v_mfma_f32_16x16x32_bf16 v[34:37], v[206:209], v[158:161], v[34:37]
	v_mfma_f32_16x16x32_bf16 v[22:25], v[198:201], v[166:169], v[22:25]
	v_mfma_f32_16x16x32_bf16 v[18:21], v[206:209], v[166:169], v[18:21]
	v_mfma_f32_16x16x32_bf16 v[4:7], v[198:201], v[174:177], v[4:7]
	v_mfma_f32_16x16x32_bf16 v[0:3], v[206:209], v[174:177], v[0:3]
	s_add_i32 s50, s50, 2
	s_add_u32 s5, s5, 0x100
	s_addc_u32 s49, s49, 0
	s_cmp_gt_u32 s50, 13
	s_mov_b64 s[12:13], s[16:17]
	s_barrier
	s_cbranch_scc0 .LBB0_1400
	s_setprio 0
	v_lshl_add_u32 v200, s11, 8, v183
	v_lshl_or_b32 v198, s10, 8, v211
	v_readlane_b32 s12, v254, 56
	v_ashrrev_i32_e32 v199, 31, v198
	v_readlane_b32 s13, v254, 57
	v_ashrrev_i32_e32 v201, 31, v200
	v_lshlrev_b64 v[130:131], 12, v[200:201]
	v_lshl_add_u64 v[202:203], v[198:199], 2, s[12:13]
	v_lshl_add_u64 v[130:131], v[202:203], 0, v[130:131]
	global_load_dwordx4 v[178:181], v[130:131], off
	global_load_dwordx4 v[216:219], v[130:131], off offset:64
	global_load_dwordx4 v[220:223], v[130:131], off offset:512
	global_load_dwordx4 v[224:227], v[130:131], off offset:576
	v_or_b32_e32 v208, 16, v200
	v_or_b32_e32 v206, 32, v200
	v_or_b32_e32 v204, 48, v200
	v_ashrrev_i32_e32 v209, 31, v208
	v_ashrrev_i32_e32 v207, 31, v206
	v_ashrrev_i32_e32 v205, 31, v204
	v_lshlrev_b64 v[130:131], 12, v[208:209]
	v_lshlrev_b64 v[132:133], 12, v[206:207]
	v_lshlrev_b64 v[134:135], 12, v[204:205]
	v_lshl_add_u64 v[130:131], v[202:203], 0, v[130:131]
	v_lshl_add_u64 v[132:133], v[202:203], 0, v[132:133]
	v_lshl_add_u64 v[214:215], v[202:203], 0, v[134:135]
	global_load_dwordx4 v[174:177], v[130:131], off
	global_load_dwordx4 v[170:173], v[130:131], off offset:64
	global_load_dwordx4 v[166:169], v[130:131], off offset:512
	global_load_dwordx4 v[162:165], v[130:131], off offset:576
	global_load_dwordx4 v[158:161], v[132:133], off
	global_load_dwordx4 v[154:157], v[132:133], off offset:64
	global_load_dwordx4 v[150:153], v[132:133], off offset:512
	global_load_dwordx4 v[146:149], v[132:133], off offset:576
	global_load_dwordx4 v[142:145], v[214:215], off
	global_load_dwordx4 v[138:141], v[214:215], off offset:64
	global_load_dwordx4 v[134:137], v[214:215], off offset:512
	s_nop 0
	global_load_dwordx4 v[130:133], v[214:215], off offset:576
	v_cmp_lt_i32_e32 vcc, v245, v240
	s_ashr_i32 s11, s10, 31
	s_lshl_b64 s[10:11], s[10:11], 18
	v_cndmask_b32_e32 v213, v239, v245, vcc
	v_cmp_lt_i32_e32 vcc, v246, v240
	v_lshlrev_b32_e32 v214, 2, v213
	s_waitcnt vmcnt(0)
	v_pk_add_f32 v[128:129], v[128:129], v[180:181]
	v_pk_add_f32 v[126:127], v[126:127], v[178:179]
	v_pk_add_f32 v[124:125], v[124:125], v[218:219]
	v_pk_add_f32 v[122:123], v[122:123], v[216:217]
	v_pk_add_f32 v[120:121], v[120:121], v[222:223]
	v_pk_add_f32 v[118:119], v[118:119], v[220:221]
	v_pk_add_f32 v[116:117], v[116:117], v[226:227]
	v_pk_add_f32 v[114:115], v[114:115], v[224:225]
	v_cvt_pk_bf16_f32 v126, v126, v127
	v_cvt_pk_bf16_f32 v127, v128, v129
	v_cvt_pk_bf16_f32 v122, v122, v123
	v_cvt_pk_bf16_f32 v123, v124, v125
	v_cvt_pk_bf16_f32 v118, v118, v119
	v_cvt_pk_bf16_f32 v119, v120, v121
	v_cvt_pk_bf16_f32 v120, v114, v115
	v_cvt_pk_bf16_f32 v121, v116, v117
	v_and_b32_e32 v115, 0xffff0000, v126
	v_and_b32_e32 v117, 0xffff0000, v127
	v_and_b32_e32 v125, 0xffff0000, v122
	v_and_b32_e32 v129, 0xffff0000, v123
	v_lshlrev_b32_e32 v114, 16, v126
	v_lshlrev_b32_e32 v116, 16, v127
	v_lshlrev_b32_e32 v124, 16, v122
	v_lshlrev_b32_e32 v128, 16, v123
	v_mul_f32_e32 v115, v115, v115
	v_mul_f32_e32 v117, v117, v117
	v_mul_f32_e32 v125, v125, v125
	v_mul_f32_e32 v129, v129, v129
	v_and_b32_e32 v179, 0xffff0000, v118
	v_and_b32_e32 v181, 0xffff0000, v119
	v_fmac_f32_e32 v115, v114, v114
	v_fmac_f32_e32 v117, v116, v116
	v_fmac_f32_e32 v125, v124, v124
	v_fmac_f32_e32 v129, v128, v128
	v_cndmask_b32_e32 v215, v239, v246, vcc
	v_lshlrev_b32_e32 v178, 16, v118
	v_lshlrev_b32_e32 v180, 16, v119
	v_and_b32_e32 v216, 0xffff0000, v120
	v_and_b32_e32 v218, 0xffff0000, v121
	v_mul_f32_e32 v179, v179, v179
	v_mul_f32_e32 v181, v181, v181
	v_add_f32_e32 v114, v115, v117
	v_add_f32_e32 v115, v125, v129
	v_lshlrev_b32_e32 v213, 2, v215
	v_lshlrev_b32_e32 v215, 16, v120
	v_lshlrev_b32_e32 v217, 16, v121
	v_mul_f32_e32 v216, v216, v216
	v_fmac_f32_e32 v179, v178, v178
	v_fmac_f32_e32 v181, v180, v180
	v_add_f32_e32 v114, v114, v115
	v_mul_f32_e32 v115, v218, v218
	v_add_f32_e32 v116, v179, v181
	v_fmac_f32_e32 v216, v215, v215
	v_fmac_f32_e32 v115, v217, v217
	v_add_f32_e32 v114, v114, v116
	v_add_f32_e32 v115, v216, v115
	v_add_f32_e32 v124, v114, v115
	ds_bpermute_b32 v125, v214, v124
	v_lshlrev_b64 v[114:115], 11, v[200:201]
	v_lshl_add_u64 v[114:115], s[54:55], 0, v[114:115]
	v_lshl_add_u64 v[116:117], v[198:199], 1, v[114:115]
	global_store_dwordx2 v[116:117], v[126:127], off
	global_store_dwordx2 v[116:117], v[122:123], off offset:32
	global_store_dwordx2 v[116:117], v[118:119], off offset:256
	global_store_dwordx2 v[116:117], v[120:121], off offset:288
	s_waitcnt lgkmcnt(0)
	v_add_f32_e32 v114, v124, v125
	ds_bpermute_b32 v115, v213, v114
	s_and_saveexec_b64 s[12:13], s[0:1]
	v_readlane_b32 s34, v254, 46
	v_readlane_b32 s35, v254, 47
	s_cbranch_execz .LBB0_1403
	s_add_u32 s16, s34, s10
	s_addc_u32 s17, s35, s11
	v_lshl_add_u64 v[116:117], v[200:201], 4, s[16:17]
	s_lshl_b32 s96, s43, 2
	v_lshl_add_u64 v[116:117], v[116:117], 0, s[96:97]
	s_waitcnt lgkmcnt(0)
	v_add_f32_e32 v114, v114, v115
	global_store_dword v[116:117], v114, off
